# rename-safe N=1 + chained accumulators, activation-major snake traversal over all 16 accumulators of a cluster
# speedup vs baseline: 1.0180x; 1.0008x over previous
; #define PG8_STAGE(bufoff, gbase, voff) do { _Pragma("unroll") for (int _i = 0; _i < 2; ++_i) \
;         asm volatile("s_mov_b32 m0, %2\n\ts_nop 0\n\tglobal_load_lds_dwordx4 %0, %1" :: "v"((voff)[_i]), "s"((const char*)(gbase)), "s"(ldsbase + (unsigned)(bufoff) + ldsw + (unsigned)_i * 8192u) : "memory", "m0"); } while (0)
; #define PG8_LDA(dst, b, h) do { _Pragma("unroll") for (int m = 0; m < 4; ++m) _Pragma("unroll") for (int k = 0; k < 2; ++k) dst[m][k] = *(const PG8_LAS bf16x8*)(lds + PG8_SA(b, h) + aoff + m * 2048 + k * 1024); } while (0)
; #define PG8_LDB(dst, b, h) do { _Pragma("unroll") for (int n = 0; n < 2; ++n) _Pragma("unroll") for (int k = 0; k < 2; ++k) dst[n][k] = *(const PG8_LAS bf16x8*)(lds + PG8_SB(b, h) + boff + n * 2048 + k * 1024); } while (0)
; #define PG8_MMA(ai, bj, At, Bt) do { __builtin_amdgcn_s_setprio(1); _Pragma("unroll") for (int m = 0; m < 4; ++m) _Pragma("unroll") for (int n = 0; n < 2; ++n) _Pragma("unroll") for (int k = 0; k < 2; ++k) \
;         acc[ai][bj][m][n] = __builtin_amdgcn_mfma_f32_16x16x32_bf16(Bt[n][k], At[m][k], acc[ai][bj][m][n], 0, 0, 0); __builtin_amdgcn_s_setprio(0); } while (0)
; #define PG8_WAIT_V(n) asm volatile("s_waitcnt vmcnt(" #n ")" ::: "memory")
; #define PG8_BAR __builtin_amdgcn_s_barrier()
; template <class Epi, class Sched, bool ALIGN_EPI = false, bool SP2 = false>
; __device__ __forceinline__ void gemm_phase(PG8_LAS unsigned char* lds, const Gemm g, const Sched& S, const Epi& E) {
;     ...
;             const bool last = (t == nt - 2);
;             const char* a1 = cA + (size_t)(t + 1) * kstep;
;             const char* a2 = last ? nA : cA + (size_t)(t + 2) * kstep; const char* b2 = last ? nB : cB + (size_t)(t + 2) * kstep;
;             const char* a3 = a2 + kstep; const char* b3 = b2 + kstep;
;             if (last && has_next) S.a_ready(nxt);
;             if constexpr (epi_has_mid<Epi>::value) { if (t == Epi::MID_T) E.mid(acc, cur, wr, wc, fr, fq); }
;             if constexpr (SP2) {
;             PG8_LDB(B0, 0, 0); PG8_LDB(B1, 0, 1); PG8_SCHED; PG8_LDA(At, 0, 0); PG8_STAGE(PG8_SA(1, 1), a1 + hstep, voffA);
;             PG8_WAIT_V(8); PG8_WAIT_L(0); PG8_BAR; PG8_MMA(0, 0, At, B0); PG8_MMA(0, 1, At, B1); PG8_BAR; PG8_SCHED;
;             PG8_LDA(At, 0, 1); PG8_STAGE(PG8_SB(0, 0), b2, voffB); PG8_STAGE(PG8_SB(0, 1), b2 + hstep, voffB); PG8_STAGE(PG8_SA(0, 0), a2, voffA);
.LBB0_138:
	ds_read_b128 v[148:151], v142
	ds_read_b128 v[152:155], v142 offset:1024
	ds_read_b128 v[156:159], v142 offset:2048
	ds_read_b128 v[160:163], v142 offset:3072
	ds_read_b128 v[164:167], v143
	ds_read_b128 v[168:171], v143 offset:1024
	ds_read_b128 v[172:175], v143 offset:2048
	ds_read_b128 v[176:179], v143 offset:3072
	s_add_u32 s62, s66, 0x100
	s_addc_u32 s63, s67, 0
	s_cmp_eq_u32 s96, 60
	s_cselect_b32 s86, s92, s62
	s_cselect_b32 s87, s13, s63
	s_cselect_b32 s84, s93, s94
	s_cselect_b32 s85, s11, s95
	s_add_u32 s76, s86, 0x80
	s_addc_u32 s77, s87, 0
	ds_read_b128 v[180:183], v144
	ds_read_b128 v[184:187], v144 offset:1024
	ds_read_b128 v[188:191], v144 offset:2048
	ds_read_b128 v[192:195], v144 offset:3072
	ds_read_b128 v[196:199], v144 offset:4096
	ds_read_b128 v[200:203], v144 offset:5120
	ds_read_b128 v[204:207], v144 offset:6144
	ds_read_b128 v[208:211], v144 offset:7168
	s_add_u32 s66, s66, 0x100080
	s_addc_u32 s67, s67, 0
	s_mov_b32 m0, s83
	s_nop 0
	global_load_lds_dwordx4 v136, s[66:67]
	s_nop 0
	s_mov_b32 m0, s88
	s_nop 0
	global_load_lds_dwordx4 v138, s[66:67]
	s_waitcnt vmcnt(8)
	s_waitcnt lgkmcnt(0)
	s_barrier
	s_setprio 1
	s_waitcnt lgkmcnt(7)
	v_mfma_f32_16x16x32_bf16 v[126:129], v[148:151], v[180:183], v[126:129]
	v_mfma_f32_16x16x32_bf16 v[126:129], v[152:155], v[184:187], v[126:129]
	s_waitcnt lgkmcnt(5)
	v_mfma_f32_16x16x32_bf16 v[122:125], v[160:163], v[184:187], v[122:125]
	v_mfma_f32_16x16x32_bf16 v[122:125], v[156:159], v[180:183], v[122:125]
	s_waitcnt lgkmcnt(3)
	v_mfma_f32_16x16x32_bf16 v[118:121], v[164:167], v[180:183], v[118:121]
	v_mfma_f32_16x16x32_bf16 v[118:121], v[168:171], v[184:187], v[118:121]
	s_waitcnt lgkmcnt(1)
	v_mfma_f32_16x16x32_bf16 v[114:117], v[176:179], v[184:187], v[114:117]
	v_mfma_f32_16x16x32_bf16 v[114:117], v[172:175], v[180:183], v[114:117]
	v_mfma_f32_16x16x32_bf16 v[98:101], v[172:175], v[188:191], v[98:101]
	v_mfma_f32_16x16x32_bf16 v[98:101], v[176:179], v[192:195], v[98:101]
	v_mfma_f32_16x16x32_bf16 v[102:105], v[168:171], v[192:195], v[102:105]
	v_mfma_f32_16x16x32_bf16 v[102:105], v[164:167], v[188:191], v[102:105]
	v_mfma_f32_16x16x32_bf16 v[106:109], v[156:159], v[188:191], v[106:109]
	v_mfma_f32_16x16x32_bf16 v[106:109], v[160:163], v[192:195], v[106:109]
	s_waitcnt lgkmcnt(0)
	v_mfma_f32_16x16x32_bf16 v[110:113], v[152:155], v[192:195], v[110:113]
	v_mfma_f32_16x16x32_bf16 v[110:113], v[148:151], v[188:191], v[110:113]
	s_setprio 0
	s_setprio 1
	v_mfma_f32_16x16x32_bf16 v[94:97], v[148:151], v[196:199], v[94:97]
	v_mfma_f32_16x16x32_bf16 v[94:97], v[152:155], v[200:203], v[94:97]
	v_mfma_f32_16x16x32_bf16 v[90:93], v[160:163], v[200:203], v[90:93]
	v_mfma_f32_16x16x32_bf16 v[90:93], v[156:159], v[196:199], v[90:93]
	v_mfma_f32_16x16x32_bf16 v[86:89], v[164:167], v[196:199], v[86:89]
	v_mfma_f32_16x16x32_bf16 v[86:89], v[168:171], v[200:203], v[86:89]
	v_mfma_f32_16x16x32_bf16 v[82:85], v[176:179], v[200:203], v[82:85]
	v_mfma_f32_16x16x32_bf16 v[82:85], v[172:175], v[196:199], v[82:85]
	v_mfma_f32_16x16x32_bf16 v[66:69], v[172:175], v[204:207], v[66:69]
	v_mfma_f32_16x16x32_bf16 v[66:69], v[176:179], v[208:211], v[66:69]
	v_mfma_f32_16x16x32_bf16 v[70:73], v[168:171], v[208:211], v[70:73]
	v_mfma_f32_16x16x32_bf16 v[70:73], v[164:167], v[204:207], v[70:73]
	v_mfma_f32_16x16x32_bf16 v[74:77], v[156:159], v[204:207], v[74:77]
	v_mfma_f32_16x16x32_bf16 v[74:77], v[160:163], v[208:211], v[74:77]
	v_mfma_f32_16x16x32_bf16 v[78:81], v[152:155], v[208:211], v[78:81]
	s_setprio 2
	s_barrier
	v_mfma_f32_16x16x32_bf16 v[78:81], v[148:151], v[204:207], v[78:81]
	s_setprio 0
	ds_read_b128 v[180:183], v144 offset:16384
	ds_read_b128 v[184:187], v144 offset:17408
	ds_read_b128 v[188:191], v144 offset:18432
	ds_read_b128 v[192:195], v144 offset:19456
	ds_read_b128 v[196:199], v144 offset:20480
	ds_read_b128 v[200:203], v144 offset:21504
	ds_read_b128 v[252:255], v144 offset:22528
	ds_read_b128 v[208:211], v144 offset:23552
	s_mov_b32 m0, s55
	s_nop 0
	global_load_lds_dwordx4 v137, s[84:85]
	s_add_u32 s66, s84, 0x100000
	s_mov_b32 m0, s56
	s_nop 0
	global_load_lds_dwordx4 v139, s[84:85]
	s_addc_u32 s67, s85, 0
	s_mov_b32 m0, s57
	s_nop 0
	global_load_lds_dwordx4 v137, s[66:67]
	s_nop 0
	s_mov_b32 m0, s58
	s_nop 0
	global_load_lds_dwordx4 v139, s[66:67]
	s_nop 0
	s_mov_b32 m0, s54
	s_nop 0
	global_load_lds_dwordx4 v136, s[86:87]
	s_nop 0
	s_mov_b32 m0, s59
	s_nop 0
	global_load_lds_dwordx4 v138, s[86:87]
	s_waitcnt vmcnt(8)
	s_waitcnt lgkmcnt(0)
	s_barrier
; #define PG8_STAGE(bufoff, gbase, voff) do { _Pragma("unroll") for (int _i = 0; _i < 2; ++_i) \
;         asm volatile("s_mov_b32 m0, %2\n\ts_nop 0\n\tglobal_load_lds_dwordx4 %0, %1" :: "v"((voff)[_i]), "s"((const char*)(gbase)), "s"(ldsbase + (unsigned)(bufoff) + ldsw + (unsigned)_i * 8192u) : "memory", "m0"); } while (0)
; #define PG8_LDA(dst, b, h) do { _Pragma("unroll") for (int m = 0; m < 4; ++m) _Pragma("unroll") for (int k = 0; k < 2; ++k) dst[m][k] = *(const PG8_LAS bf16x8*)(lds + PG8_SA(b, h) + aoff + m * 2048 + k * 1024); } while (0)
; #define PG8_LDB(dst, b, h) do { _Pragma("unroll") for (int n = 0; n < 2; ++n) _Pragma("unroll") for (int k = 0; k < 2; ++k) dst[n][k] = *(const PG8_LAS bf16x8*)(lds + PG8_SB(b, h) + boff + n * 2048 + k * 1024); } while (0)
; #define PG8_MMA(ai, bj, At, Bt) do { __builtin_amdgcn_s_setprio(1); _Pragma("unroll") for (int m = 0; m < 4; ++m) _Pragma("unroll") for (int n = 0; n < 2; ++n) _Pragma("unroll") for (int k = 0; k < 2; ++k) \
;         acc[ai][bj][m][n] = __builtin_amdgcn_mfma_f32_16x16x32_bf16(Bt[n][k], At[m][k], acc[ai][bj][m][n], 0, 0, 0); __builtin_amdgcn_s_setprio(0); } while (0)
; #define PG8_WAIT_V(n) asm volatile("s_waitcnt vmcnt(" #n ")" ::: "memory")
; #define PG8_WAIT_L(n) asm volatile("s_waitcnt lgkmcnt(" #n ")" ::: "memory")
; #define PG8_BAR __builtin_amdgcn_s_barrier()
; #define PG8_SCHED __builtin_amdgcn_sched_barrier(0)
; template <class Epi, class Sched, bool ALIGN_EPI = false, bool SP2 = false>
; __device__ __forceinline__ void gemm_phase(PG8_LAS unsigned char* lds, const Gemm g, const Sched& S, const Epi& E) {
;     ...
;             PG8_WAIT_V(8); PG8_WAIT_L(0); PG8_BAR; PG8_MMA(1, 0, At, B0); PG8_MMA(1, 1, At, B1); PG8_BAR; PG8_SCHED;
;             PG8_LDB(B0, 1, 0); PG8_LDB(B1, 1, 1); PG8_SCHED; PG8_LDA(At, 1, 0); PG8_STAGE(PG8_SA(0, 1), a2 + hstep, voffA);
;             PG8_WAIT_V(8); PG8_WAIT_L(0); PG8_BAR; PG8_MMA(0, 0, At, B0); PG8_MMA(0, 1, At, B1); PG8_BAR; PG8_SCHED;
	s_setprio 1
	s_waitcnt lgkmcnt(7)
	v_mfma_f32_16x16x32_bf16 v[62:65], v[148:151], v[180:183], v[62:65]
	v_mfma_f32_16x16x32_bf16 v[62:65], v[152:155], v[184:187], v[62:65]
	s_waitcnt lgkmcnt(5)
	v_mfma_f32_16x16x32_bf16 v[58:61], v[160:163], v[184:187], v[58:61]
	v_mfma_f32_16x16x32_bf16 v[58:61], v[156:159], v[180:183], v[58:61]
	s_waitcnt lgkmcnt(3)
	v_mfma_f32_16x16x32_bf16 v[54:57], v[164:167], v[180:183], v[54:57]
	v_mfma_f32_16x16x32_bf16 v[54:57], v[168:171], v[184:187], v[54:57]
	s_waitcnt lgkmcnt(1)
	v_mfma_f32_16x16x32_bf16 v[50:53], v[176:179], v[184:187], v[50:53]
	v_mfma_f32_16x16x32_bf16 v[50:53], v[172:175], v[180:183], v[50:53]
	v_mfma_f32_16x16x32_bf16 v[34:37], v[172:175], v[188:191], v[34:37]
	v_mfma_f32_16x16x32_bf16 v[34:37], v[176:179], v[192:195], v[34:37]
	v_mfma_f32_16x16x32_bf16 v[38:41], v[168:171], v[192:195], v[38:41]
	v_mfma_f32_16x16x32_bf16 v[38:41], v[164:167], v[188:191], v[38:41]
	v_mfma_f32_16x16x32_bf16 v[42:45], v[156:159], v[188:191], v[42:45]
	v_mfma_f32_16x16x32_bf16 v[42:45], v[160:163], v[192:195], v[42:45]
	s_waitcnt lgkmcnt(0)
	v_mfma_f32_16x16x32_bf16 v[46:49], v[152:155], v[192:195], v[46:49]
	v_mfma_f32_16x16x32_bf16 v[46:49], v[148:151], v[188:191], v[46:49]
	s_setprio 0
	s_setprio 1
	v_mfma_f32_16x16x32_bf16 v[30:33], v[148:151], v[196:199], v[30:33]
	v_mfma_f32_16x16x32_bf16 v[30:33], v[152:155], v[200:203], v[30:33]
	v_mfma_f32_16x16x32_bf16 v[26:29], v[160:163], v[200:203], v[26:29]
	v_mfma_f32_16x16x32_bf16 v[26:29], v[156:159], v[196:199], v[26:29]
	v_mfma_f32_16x16x32_bf16 v[22:25], v[164:167], v[196:199], v[22:25]
	v_mfma_f32_16x16x32_bf16 v[22:25], v[168:171], v[200:203], v[22:25]
	v_mfma_f32_16x16x32_bf16 v[18:21], v[176:179], v[200:203], v[18:21]
	v_mfma_f32_16x16x32_bf16 v[18:21], v[172:175], v[196:199], v[18:21]
	v_mfma_f32_16x16x32_bf16 v[2:5], v[172:175], v[252:255], v[2:5]
	v_mfma_f32_16x16x32_bf16 v[2:5], v[176:179], v[208:211], v[2:5]
	v_mfma_f32_16x16x32_bf16 v[6:9], v[168:171], v[208:211], v[6:9]
	v_mfma_f32_16x16x32_bf16 v[6:9], v[164:167], v[252:255], v[6:9]
	v_mfma_f32_16x16x32_bf16 v[10:13], v[156:159], v[252:255], v[10:13]
	v_mfma_f32_16x16x32_bf16 v[10:13], v[160:163], v[208:211], v[10:13]
	v_mfma_f32_16x16x32_bf16 v[14:17], v[152:155], v[208:211], v[14:17]
	s_setprio 2
	s_barrier
	v_mfma_f32_16x16x32_bf16 v[14:17], v[148:151], v[252:255], v[14:17]
	s_setprio 0
	ds_read_b128 v[248:251], v145
	ds_read_b128 v[152:155], v145 offset:1024
	ds_read_b128 v[156:159], v145 offset:2048
	ds_read_b128 v[160:163], v145 offset:3072
	ds_read_b128 v[164:167], v146
	ds_read_b128 v[168:171], v146 offset:1024
	ds_read_b128 v[172:175], v146 offset:2048
	ds_read_b128 v[176:179], v146 offset:3072
	ds_read_b128 v[180:183], v144 offset:32768
	ds_read_b128 v[184:187], v144 offset:33792
	ds_read_b128 v[188:191], v144 offset:34816
	ds_read_b128 v[192:195], v144 offset:35840
	ds_read_b128 v[196:199], v144 offset:36864
	ds_read_b128 v[200:203], v144 offset:37888
	ds_read_b128 v[204:207], v144 offset:38912
	ds_read_b128 v[208:211], v144 offset:39936
	s_add_u32 s66, s86, 0x100000
	s_addc_u32 s67, s87, 0
	s_mov_b32 m0, s60
	s_nop 0
	global_load_lds_dwordx4 v136, s[66:67]
	s_nop 0
	s_mov_b32 m0, s61
	s_nop 0
	global_load_lds_dwordx4 v138, s[66:67]
	s_waitcnt vmcnt(8)
	s_waitcnt lgkmcnt(0)
	s_barrier
	s_setprio 1
	s_waitcnt lgkmcnt(7)
	v_mfma_f32_16x16x32_bf16 v[126:129], v[248:251], v[180:183], v[126:129]
	v_mfma_f32_16x16x32_bf16 v[126:129], v[152:155], v[184:187], v[126:129]
	s_waitcnt lgkmcnt(5)
	v_mfma_f32_16x16x32_bf16 v[122:125], v[160:163], v[184:187], v[122:125]
	v_mfma_f32_16x16x32_bf16 v[122:125], v[156:159], v[180:183], v[122:125]
	s_waitcnt lgkmcnt(3)
	v_mfma_f32_16x16x32_bf16 v[118:121], v[164:167], v[180:183], v[118:121]
	v_mfma_f32_16x16x32_bf16 v[118:121], v[168:171], v[184:187], v[118:121]
	s_waitcnt lgkmcnt(1)
	v_mfma_f32_16x16x32_bf16 v[114:117], v[176:179], v[184:187], v[114:117]
	v_mfma_f32_16x16x32_bf16 v[114:117], v[172:175], v[180:183], v[114:117]
	v_mfma_f32_16x16x32_bf16 v[98:101], v[172:175], v[188:191], v[98:101]
	v_mfma_f32_16x16x32_bf16 v[98:101], v[176:179], v[192:195], v[98:101]
	v_mfma_f32_16x16x32_bf16 v[102:105], v[168:171], v[192:195], v[102:105]
	v_mfma_f32_16x16x32_bf16 v[102:105], v[164:167], v[188:191], v[102:105]
	v_mfma_f32_16x16x32_bf16 v[106:109], v[156:159], v[188:191], v[106:109]
	v_mfma_f32_16x16x32_bf16 v[106:109], v[160:163], v[192:195], v[106:109]
	s_waitcnt lgkmcnt(0)
	v_mfma_f32_16x16x32_bf16 v[110:113], v[152:155], v[192:195], v[110:113]
	v_mfma_f32_16x16x32_bf16 v[110:113], v[248:251], v[188:191], v[110:113]
	s_setprio 0
	s_setprio 1
	v_mfma_f32_16x16x32_bf16 v[94:97], v[248:251], v[196:199], v[94:97]
	v_mfma_f32_16x16x32_bf16 v[94:97], v[152:155], v[200:203], v[94:97]
	v_mfma_f32_16x16x32_bf16 v[90:93], v[160:163], v[200:203], v[90:93]
	v_mfma_f32_16x16x32_bf16 v[90:93], v[156:159], v[196:199], v[90:93]
	v_mfma_f32_16x16x32_bf16 v[86:89], v[164:167], v[196:199], v[86:89]
	v_mfma_f32_16x16x32_bf16 v[86:89], v[168:171], v[200:203], v[86:89]
	v_mfma_f32_16x16x32_bf16 v[82:85], v[176:179], v[200:203], v[82:85]
	v_mfma_f32_16x16x32_bf16 v[82:85], v[172:175], v[196:199], v[82:85]
	v_mfma_f32_16x16x32_bf16 v[66:69], v[172:175], v[204:207], v[66:69]
	v_mfma_f32_16x16x32_bf16 v[66:69], v[176:179], v[208:211], v[66:69]
	v_mfma_f32_16x16x32_bf16 v[70:73], v[168:171], v[208:211], v[70:73]
	v_mfma_f32_16x16x32_bf16 v[70:73], v[164:167], v[204:207], v[70:73]
	v_mfma_f32_16x16x32_bf16 v[74:77], v[156:159], v[204:207], v[74:77]
	v_mfma_f32_16x16x32_bf16 v[74:77], v[160:163], v[208:211], v[74:77]
	v_mfma_f32_16x16x32_bf16 v[78:81], v[152:155], v[208:211], v[78:81]
	s_setprio 2
	s_barrier
; __device__ __forceinline__ unsigned cvt_pk_bf16(float lo, float hi) { unsigned r; asm volatile("v_cvt_pk_bf16_f32 %0, %1, %2" : "=v"(r) : "v"(lo), "v"(hi)); return r; }
; __device__ __forceinline__ float silu_f(float x) { return x * sigmoid_f(x); }
; #define PG8_STAGE(bufoff, gbase, voff) do { _Pragma("unroll") for (int _i = 0; _i < 2; ++_i) \
;         asm volatile("s_mov_b32 m0, %2\n\ts_nop 0\n\tglobal_load_lds_dwordx4 %0, %1" :: "v"((voff)[_i]), "s"((const char*)(gbase)), "s"(ldsbase + (unsigned)(bufoff) + ldsw + (unsigned)_i * 8192u) : "memory", "m0"); } while (0)
; #define PG8_LDA(dst, b, h) do { _Pragma("unroll") for (int m = 0; m < 4; ++m) _Pragma("unroll") for (int k = 0; k < 2; ++k) dst[m][k] = *(const PG8_LAS bf16x8*)(lds + PG8_SA(b, h) + aoff + m * 2048 + k * 1024); } while (0)
; #define PG8_MMA(ai, bj, At, Bt) do { __builtin_amdgcn_s_setprio(1); _Pragma("unroll") for (int m = 0; m < 4; ++m) _Pragma("unroll") for (int n = 0; n < 2; ++n) _Pragma("unroll") for (int k = 0; k < 2; ++k) \
;         acc[ai][bj][m][n] = __builtin_amdgcn_mfma_f32_16x16x32_bf16(Bt[n][k], At[m][k], acc[ai][bj][m][n], 0, 0, 0); __builtin_amdgcn_s_setprio(0); } while (0)
;     __device__ __forceinline__ void operator()(const f32x4 (&acc)[2][2][4][2], const Unit& u, int wr, int wc, int fr, int fq) const {
;     ...
;             for (int m = 0; m < 4; ++m) { bf16_t* rowp = O + (size_t)(row0 + ai * HALF + m * 16) * ldc + col0;
;                 const f32x4 g0 = acc[ai][0][m][0], g1 = acc[ai][0][m][1], u0 = acc[ai][1][m][0], u1 = acc[ai][1][m][1];
;                 f32x4 v0, v1;
; #pragma unroll
;                 for (int j = 0; j < 4; ++j) { v0[j] = silu_f(g0[j]) * u0[j]; v1[j] = silu_f(g1[j]) * u1[j]; }
;                 u32x4 w; w.x = cvt_pk_bf16(v0[0], v0[1]); w.y = cvt_pk_bf16(v0[2], v0[3]); w.z = cvt_pk_bf16(v1[0], v1[1]); w.w = cvt_pk_bf16(v1[2], v1[3]);
;                 *(u32x4*)rowp = w; }
; template <class Epi, class Sched, bool ALIGN_EPI = false, bool SP2 = false>
; __device__ __forceinline__ void gemm_phase(PG8_LAS unsigned char* lds, const Gemm g, const Sched& S, const Epi& E) {
;     ...
;             PG8_LDA(At, 1, 1); PG8_STAGE(PG8_SB(1, 0), b3, voffB); PG8_STAGE(PG8_SB(1, 1), b3 + hstep, voffB); PG8_STAGE(PG8_SA(1, 0), a3, voffA);
;             PG8_WAIT_V(8); PG8_WAIT_L(0); PG8_BAR; PG8_MMA(1, 0, At, B0); PG8_MMA(1, 1, At, B1); PG8_BAR; PG8_SCHED;
	v_mfma_f32_16x16x32_bf16 v[78:81], v[248:251], v[204:207], v[78:81]
	s_setprio 0
	ds_read_b128 v[180:183], v144 offset:49152
	ds_read_b128 v[184:187], v144 offset:50176
	ds_read_b128 v[188:191], v144 offset:51200
	ds_read_b128 v[192:195], v144 offset:52224
	ds_read_b128 v[196:199], v144 offset:53248
	ds_read_b128 v[200:203], v144 offset:54272
	ds_read_b128 v[252:255], v144 offset:55296
	ds_read_b128 v[208:211], v144 offset:56320
	s_add_u32 s66, s84, 0x80
	s_addc_u32 s67, s85, 0
	s_mov_b32 m0, s64
	s_nop 0
	global_load_lds_dwordx4 v137, s[66:67]
	s_nop 0
	s_mov_b32 m0, s65
	s_nop 0
	global_load_lds_dwordx4 v139, s[66:67]
	s_add_u32 s66, s84, 0x100080
	s_addc_u32 s67, s85, 0
	s_mov_b32 m0, s70
	s_nop 0
	global_load_lds_dwordx4 v137, s[66:67]
	s_nop 0
	s_mov_b32 m0, s71
	s_nop 0
	global_load_lds_dwordx4 v139, s[66:67]
	s_nop 0
	s_mov_b32 m0, s68
	s_nop 0
	global_load_lds_dwordx4 v136, s[76:77]
	s_nop 0
	s_mov_b32 m0, s69
	s_nop 0
	global_load_lds_dwordx4 v138, s[76:77]
	s_waitcnt vmcnt(8)
	s_waitcnt lgkmcnt(0)
	s_barrier
	s_setprio 1
	s_waitcnt lgkmcnt(7)
	v_mfma_f32_16x16x32_bf16 v[62:65], v[248:251], v[180:183], v[62:65]
	v_mfma_f32_16x16x32_bf16 v[62:65], v[152:155], v[184:187], v[62:65]
	s_waitcnt lgkmcnt(5)
	v_mfma_f32_16x16x32_bf16 v[58:61], v[160:163], v[184:187], v[58:61]
	v_mfma_f32_16x16x32_bf16 v[58:61], v[156:159], v[180:183], v[58:61]
	s_waitcnt lgkmcnt(3)
	v_mfma_f32_16x16x32_bf16 v[54:57], v[164:167], v[180:183], v[54:57]
	v_mfma_f32_16x16x32_bf16 v[54:57], v[168:171], v[184:187], v[54:57]
	s_waitcnt lgkmcnt(1)
	v_mfma_f32_16x16x32_bf16 v[50:53], v[176:179], v[184:187], v[50:53]
	v_mfma_f32_16x16x32_bf16 v[50:53], v[172:175], v[180:183], v[50:53]
	v_mfma_f32_16x16x32_bf16 v[34:37], v[172:175], v[188:191], v[34:37]
	v_mfma_f32_16x16x32_bf16 v[34:37], v[176:179], v[192:195], v[34:37]
	v_mfma_f32_16x16x32_bf16 v[38:41], v[168:171], v[192:195], v[38:41]
	v_mfma_f32_16x16x32_bf16 v[38:41], v[164:167], v[188:191], v[38:41]
	v_mfma_f32_16x16x32_bf16 v[42:45], v[156:159], v[188:191], v[42:45]
	v_mfma_f32_16x16x32_bf16 v[42:45], v[160:163], v[192:195], v[42:45]
	s_waitcnt lgkmcnt(0)
	v_mfma_f32_16x16x32_bf16 v[46:49], v[152:155], v[192:195], v[46:49]
	v_mfma_f32_16x16x32_bf16 v[46:49], v[248:251], v[188:191], v[46:49]
	s_setprio 0
	s_setprio 1
	v_mfma_f32_16x16x32_bf16 v[30:33], v[248:251], v[196:199], v[30:33]
	v_mfma_f32_16x16x32_bf16 v[30:33], v[152:155], v[200:203], v[30:33]
	v_mfma_f32_16x16x32_bf16 v[26:29], v[160:163], v[200:203], v[26:29]
	v_mfma_f32_16x16x32_bf16 v[26:29], v[156:159], v[196:199], v[26:29]
	v_mfma_f32_16x16x32_bf16 v[22:25], v[164:167], v[196:199], v[22:25]
	v_mfma_f32_16x16x32_bf16 v[22:25], v[168:171], v[200:203], v[22:25]
	v_mfma_f32_16x16x32_bf16 v[18:21], v[176:179], v[200:203], v[18:21]
	v_mfma_f32_16x16x32_bf16 v[18:21], v[172:175], v[196:199], v[18:21]
	v_mfma_f32_16x16x32_bf16 v[2:5], v[172:175], v[252:255], v[2:5]
	v_mfma_f32_16x16x32_bf16 v[2:5], v[176:179], v[208:211], v[2:5]
	v_mfma_f32_16x16x32_bf16 v[6:9], v[168:171], v[208:211], v[6:9]
	v_mfma_f32_16x16x32_bf16 v[6:9], v[164:167], v[252:255], v[6:9]
	v_mfma_f32_16x16x32_bf16 v[10:13], v[156:159], v[252:255], v[10:13]
	v_mfma_f32_16x16x32_bf16 v[10:13], v[160:163], v[208:211], v[10:13]
	v_mfma_f32_16x16x32_bf16 v[14:17], v[152:155], v[208:211], v[14:17]
	s_setprio 2
	s_barrier
	v_mfma_f32_16x16x32_bf16 v[14:17], v[248:251], v[252:255], v[14:17]
	s_setprio 0
	s_add_i32 s96, s96, 2
	s_add_u32 s94, s94, 0x100
	s_addc_u32 s95, s95, 0
	s_cmp_gt_u32 s96, 61
	s_mov_b64 s[66:67], s[62:63]
	s_cbranch_scc0 .LBB0_138
	v_mul_f32_e32 v134, 0xbfb8aa3b, v126
	v_exp_f32_e32 v150, v134
	v_mul_f32_e32 v134, 0xbfb8aa3b, v122
	v_exp_f32_e32 v151, v134
	v_lshl_or_b32 v148, s91, 7, v141
	v_add_f32_e32 v150, 1.0, v150
	v_rcp_f32_e32 v152, v150
	v_add_f32_e32 v150, 1.0, v151
	v_rcp_f32_e32 v153, v150
	v_lshl_add_u32 v147, s82, 8, v140
	v_mul_f32_e32 v126, v126, v152
	v_mul_f32_e32 v118, v126, v118
	v_mul_f32_e32 v126, 0xbfb8aa3b, v127
	v_exp_f32_e32 v126, v126
	v_mul_f32_e32 v152, 0xbfb8aa3b, v123
	v_exp_f32_e32 v152, v152
	v_mul_f32_e32 v122, v122, v153
	v_mul_f32_e32 v122, v122, v114
	v_add_f32_e32 v114, 1.0, v126
	v_rcp_f32_e32 v114, v114
	v_add_f32_e32 v126, 1.0, v152
	v_mul_f32_e32 v152, 0xbfb8aa3b, v128
	v_rcp_f32_e32 v126, v126
	v_exp_f32_e32 v152, v152
	v_mul_f32_e32 v114, v127, v114
	v_mul_f32_e32 v119, v114, v119
	v_mul_f32_e32 v114, v123, v126
	v_add_f32_e32 v123, 1.0, v152
	v_rcp_f32_e32 v123, v123
	v_mul_f32_e32 v126, 0xbfb8aa3b, v124
	v_exp_f32_e32 v126, v126
	v_mul_f32_e32 v127, v114, v115
	v_mul_f32_e32 v114, v128, v123
	v_mul_f32_e32 v115, 0xbfb8aa3b, v129
	v_mul_f32_e32 v123, v114, v120
	v_exp_f32_e32 v115, v115
	v_mul_f32_e32 v120, 0xbfb8aa3b, v125
	v_exp_f32_e32 v120, v120
	v_add_f32_e32 v114, 1.0, v126
	v_rcp_f32_e32 v114, v114
	v_add_f32_e32 v115, 1.0, v115
	v_rcp_f32_e32 v115, v115
	v_add_f32_e32 v120, 1.0, v120
	v_rcp_f32_e32 v120, v120
	v_mul_f32_e32 v114, v124, v114
	v_mul_f32_e32 v124, v114, v116
	v_mul_f32_e32 v114, v129, v115
	v_ashrrev_i32_e32 v149, 31, v148
	v_mov_b64_e32 v[134:135], s[72:73]
	v_mul_f32_e32 v126, v114, v121
	v_mul_f32_e32 v114, v125, v120
	v_mad_i64_i32 v[150:151], s[62:63], v147, s90, v[134:135]
	v_mul_f32_e32 v125, v114, v117
	v_lshlrev_b64 v[114:115], 1, v[148:149]
	v_lshl_add_u64 v[120:121], v[150:151], 0, v[114:115]
	v_cvt_pk_bf16_f32 v116, v118, v119
	v_cvt_pk_bf16_f32 v117, v123, v126
	v_cvt_pk_bf16_f32 v118, v122, v127
	v_cvt_pk_bf16_f32 v119, v124, v125
	global_store_dwordx4 v[120:121], v[116:119], off
	s_and_b64 vcc, exec, s[0:1]
	s_mov_b32 s91, s10
	v_mul_f32_e32 v116, 0xbfb8aa3b, v110
	v_exp_f32_e32 v116, v116
; __device__ __forceinline__ unsigned cvt_pk_bf16(float lo, float hi) { unsigned r; asm volatile("v_cvt_pk_bf16_f32 %0, %1, %2" : "=v"(r) : "v"(lo), "v"(hi)); return r; }
; __device__ __forceinline__ float silu_f(float x) { return x * sigmoid_f(x); }
;     __device__ __forceinline__ void operator()(const f32x4 (&acc)[2][2][4][2], const Unit& u, int wr, int wc, int fr, int fq) const {
;     ...
;         for (int ai = 0; ai < 2; ++ai)
; #pragma unroll
;             for (int m = 0; m < 4; ++m) { bf16_t* rowp = O + (size_t)(row0 + ai * HALF + m * 16) * ldc + col0;
;                 const f32x4 g0 = acc[ai][0][m][0], g1 = acc[ai][0][m][1], u0 = acc[ai][1][m][0], u1 = acc[ai][1][m][1];
;                 f32x4 v0, v1;
; #pragma unroll
;                 for (int j = 0; j < 4; ++j) { v0[j] = silu_f(g0[j]) * u0[j]; v1[j] = silu_f(g1[j]) * u1[j]; }
;                 u32x4 w; w.x = cvt_pk_bf16(v0[0], v0[1]); w.y = cvt_pk_bf16(v0[2], v0[3]); w.z = cvt_pk_bf16(v1[0], v1[1]); w.w = cvt_pk_bf16(v1[2], v1[3]);
;                 *(u32x4*)rowp = w; }
	v_mul_f32_e32 v117, 0xbfb8aa3b, v106
	v_exp_f32_e32 v117, v117
	v_or_b32_e32 v118, 16, v147
	v_add_f32_e32 v116, 1.0, v116
	v_rcp_f32_e32 v119, v116
	v_add_f32_e32 v116, 1.0, v117
	v_rcp_f32_e32 v120, v116
	v_mad_i64_i32 v[116:117], s[62:63], v118, s90, v[134:135]
	v_mul_f32_e32 v110, v110, v119
	v_mul_f32_e32 v110, v110, v102
	v_mul_f32_e32 v102, v106, v120
	v_mul_f32_e32 v106, 0xbfb8aa3b, v111
	v_exp_f32_e32 v106, v106
	v_mul_f32_e32 v118, 0xbfb8aa3b, v107
	v_mul_f32_e32 v119, v102, v98
	v_exp_f32_e32 v118, v118
	v_add_f32_e32 v98, 1.0, v106
	v_rcp_f32_e32 v98, v98
	v_mul_f32_e32 v106, 0xbfb8aa3b, v112
	v_exp_f32_e32 v106, v106
	v_add_f32_e32 v102, 1.0, v118
	v_mul_f32_e32 v98, v111, v98
	v_rcp_f32_e32 v102, v102
	v_mul_f32_e32 v98, v98, v103
	v_add_f32_e32 v103, 1.0, v106
	v_rcp_f32_e32 v103, v103
	v_mul_f32_e32 v102, v107, v102
	v_mul_f32_e32 v106, 0xbfb8aa3b, v108
	v_mul_f32_e32 v107, v102, v99
	v_mul_f32_e32 v99, v112, v103
	v_exp_f32_e32 v106, v106
	v_mul_f32_e32 v99, v99, v104
	v_mul_f32_e32 v103, 0xbfb8aa3b, v113
	v_mul_f32_e32 v104, 0xbfb8aa3b, v109
	v_exp_f32_e32 v103, v103
	v_exp_f32_e32 v104, v104
	v_add_f32_e32 v102, 1.0, v106
	v_rcp_f32_e32 v102, v102
	v_add_f32_e32 v103, 1.0, v103
	v_add_f32_e32 v104, 1.0, v104
	v_rcp_f32_e32 v103, v103
	v_rcp_f32_e32 v104, v104
	v_mul_f32_e32 v102, v108, v102
	v_mul_f32_e32 v106, v102, v100
	v_mul_f32_e32 v100, v113, v103
	v_mul_f32_e32 v102, v109, v104
	v_mul_f32_e32 v100, v100, v105
	v_mul_f32_e32 v101, v102, v101
	v_lshl_add_u64 v[102:103], v[116:117], 0, v[114:115]
	v_cvt_pk_bf16_f32 v98, v110, v98
	v_cvt_pk_bf16_f32 v99, v99, v100
	v_cvt_pk_bf16_f32 v100, v119, v107
	v_cvt_pk_bf16_f32 v101, v106, v101
	global_store_dwordx4 v[102:103], v[98:101], off
	s_mov_b32 s82, s12
	s_mov_b64 s[66:67], s[14:15]
	v_mul_f32_e32 v98, 0xbfb8aa3b, v94
	v_exp_f32_e32 v98, v98
	v_mul_f32_e32 v99, 0xbfb8aa3b, v90
	v_exp_f32_e32 v99, v99
	v_or_b32_e32 v100, 32, v147
	v_add_f32_e32 v98, 1.0, v98
	v_rcp_f32_e32 v101, v98
	v_add_f32_e32 v98, 1.0, v99
	v_rcp_f32_e32 v102, v98
	v_mad_i64_i32 v[98:99], s[62:63], v100, s90, v[134:135]
	v_mul_f32_e32 v94, v94, v101
	v_mul_f32_e32 v94, v94, v86
	v_mul_f32_e32 v86, v90, v102
	v_mul_f32_e32 v90, 0xbfb8aa3b, v95
	v_exp_f32_e32 v90, v90
	v_mul_f32_e32 v100, 0xbfb8aa3b, v91
	v_mul_f32_e32 v101, v86, v82
	v_exp_f32_e32 v100, v100
	v_add_f32_e32 v82, 1.0, v90
	v_rcp_f32_e32 v82, v82
	v_mul_f32_e32 v90, 0xbfb8aa3b, v96
	v_exp_f32_e32 v90, v90
	v_add_f32_e32 v86, 1.0, v100
	v_mul_f32_e32 v82, v95, v82
	v_rcp_f32_e32 v86, v86
	v_mul_f32_e32 v82, v82, v87
	v_add_f32_e32 v87, 1.0, v90
	v_rcp_f32_e32 v87, v87
	v_mul_f32_e32 v86, v91, v86
	v_mul_f32_e32 v90, 0xbfb8aa3b, v92
	v_mul_f32_e32 v91, v86, v83
	v_mul_f32_e32 v83, v96, v87
	v_exp_f32_e32 v90, v90
	v_mul_f32_e32 v83, v83, v88
	v_mul_f32_e32 v87, 0xbfb8aa3b, v97
	v_mul_f32_e32 v88, 0xbfb8aa3b, v93
	v_exp_f32_e32 v87, v87
	v_exp_f32_e32 v88, v88
	v_add_f32_e32 v86, 1.0, v90
	v_rcp_f32_e32 v86, v86
	v_add_f32_e32 v87, 1.0, v87
	v_add_f32_e32 v88, 1.0, v88
	v_rcp_f32_e32 v87, v87
	v_rcp_f32_e32 v88, v88
	v_mul_f32_e32 v86, v92, v86
	v_mul_f32_e32 v90, v86, v84
	v_mul_f32_e32 v84, v97, v87
	v_mul_f32_e32 v86, v93, v88
	v_mul_f32_e32 v84, v84, v89
	v_mul_f32_e32 v85, v86, v85
	v_lshl_add_u64 v[86:87], v[98:99], 0, v[114:115]
	v_cvt_pk_bf16_f32 v82, v94, v82
	v_cvt_pk_bf16_f32 v83, v83, v84
	v_cvt_pk_bf16_f32 v84, v101, v91
	v_cvt_pk_bf16_f32 v85, v90, v85
	global_store_dwordx4 v[86:87], v[82:85], off
	s_nop 1
	v_mul_f32_e32 v82, 0xbfb8aa3b, v78
	v_exp_f32_e32 v82, v82
	v_mul_f32_e32 v83, 0xbfb8aa3b, v74
	v_exp_f32_e32 v83, v83
	v_or_b32_e32 v84, 48, v147
	v_add_f32_e32 v82, 1.0, v82
	v_rcp_f32_e32 v85, v82
	v_add_f32_e32 v82, 1.0, v83
	v_rcp_f32_e32 v86, v82
	v_mad_i64_i32 v[82:83], s[62:63], v84, s90, v[134:135]
	v_mul_f32_e32 v78, v78, v85
	v_mul_f32_e32 v78, v78, v70
	v_mul_f32_e32 v70, v74, v86
	v_mul_f32_e32 v74, 0xbfb8aa3b, v79
	v_exp_f32_e32 v74, v74
	v_mul_f32_e32 v84, 0xbfb8aa3b, v75
	v_mul_f32_e32 v85, v70, v66
	v_exp_f32_e32 v84, v84
	v_add_f32_e32 v66, 1.0, v74
	v_rcp_f32_e32 v66, v66
	v_mul_f32_e32 v74, 0xbfb8aa3b, v80
	v_exp_f32_e32 v74, v74
	v_add_f32_e32 v70, 1.0, v84
	v_mul_f32_e32 v66, v79, v66
	v_rcp_f32_e32 v70, v70
	v_mul_f32_e32 v66, v66, v71
	v_add_f32_e32 v71, 1.0, v74
	v_rcp_f32_e32 v71, v71
	v_mul_f32_e32 v70, v75, v70
	v_mul_f32_e32 v74, 0xbfb8aa3b, v76
	v_mul_f32_e32 v75, v70, v67
	v_mul_f32_e32 v67, v80, v71
	v_exp_f32_e32 v74, v74
	v_mul_f32_e32 v67, v67, v72
	v_mul_f32_e32 v71, 0xbfb8aa3b, v81
	v_mul_f32_e32 v72, 0xbfb8aa3b, v77
	v_exp_f32_e32 v71, v71
	v_exp_f32_e32 v72, v72
	v_add_f32_e32 v70, 1.0, v74
	v_rcp_f32_e32 v70, v70
	v_add_f32_e32 v71, 1.0, v71
	v_add_f32_e32 v72, 1.0, v72
	v_rcp_f32_e32 v71, v71
	v_rcp_f32_e32 v72, v72
	v_mul_f32_e32 v70, v76, v70
	v_mul_f32_e32 v74, v70, v68
	v_mul_f32_e32 v68, v81, v71
	v_mul_f32_e32 v70, v77, v72
	v_mul_f32_e32 v68, v68, v73
	v_mul_f32_e32 v69, v70, v69
	v_lshl_add_u64 v[70:71], v[82:83], 0, v[114:115]
	v_cvt_pk_bf16_f32 v66, v78, v66
	v_cvt_pk_bf16_f32 v67, v67, v68
	v_cvt_pk_bf16_f32 v68, v85, v75
	v_cvt_pk_bf16_f32 v69, v74, v69
	global_store_dwordx4 v[70:71], v[66:69], off
	s_nop 1
	v_mul_f32_e32 v66, 0xbfb8aa3b, v62
	v_exp_f32_e32 v66, v66
	v_mul_f32_e32 v67, 0xbfb8aa3b, v58
	v_exp_f32_e32 v67, v67
	v_add_u32_e32 v68, 0x80, v147
	v_add_f32_e32 v66, 1.0, v66
	v_rcp_f32_e32 v69, v66
	v_add_f32_e32 v66, 1.0, v67
	v_rcp_f32_e32 v70, v66
	v_mad_i64_i32 v[66:67], s[62:63], v68, s90, v[134:135]
	v_mul_f32_e32 v62, v62, v69
	v_mul_f32_e32 v62, v62, v54
	v_mul_f32_e32 v54, v58, v70
	v_mul_f32_e32 v58, 0xbfb8aa3b, v63
	v_exp_f32_e32 v58, v58
; __device__ __forceinline__ unsigned cvt_pk_bf16(float lo, float hi) { unsigned r; asm volatile("v_cvt_pk_bf16_f32 %0, %1, %2" : "=v"(r) : "v"(lo), "v"(hi)); return r; }
; __device__ __forceinline__ float silu_f(float x) { return x * sigmoid_f(x); }
; #define PG8_WAIT_V(n) asm volatile("s_waitcnt vmcnt(" #n ")" ::: "memory")
; #define PG8_BAR __builtin_amdgcn_s_barrier()
;     __device__ __forceinline__ void operator()(const f32x4 (&acc)[2][2][4][2], const Unit& u, int wr, int wc, int fr, int fq) const {
;     ...
;         for (int ai = 0; ai < 2; ++ai)
; #pragma unroll
;             for (int m = 0; m < 4; ++m) { bf16_t* rowp = O + (size_t)(row0 + ai * HALF + m * 16) * ldc + col0;
;                 const f32x4 g0 = acc[ai][0][m][0], g1 = acc[ai][0][m][1], u0 = acc[ai][1][m][0], u1 = acc[ai][1][m][1];
;                 f32x4 v0, v1;
; #pragma unroll
;                 for (int j = 0; j < 4; ++j) { v0[j] = silu_f(g0[j]) * u0[j]; v1[j] = silu_f(g1[j]) * u1[j]; }
;                 u32x4 w; w.x = cvt_pk_bf16(v0[0], v0[1]); w.y = cvt_pk_bf16(v0[2], v0[3]); w.z = cvt_pk_bf16(v1[0], v1[1]); w.w = cvt_pk_bf16(v1[2], v1[3]);
;                 *(u32x4*)rowp = w; }
; template <class Epi, class Sched, bool ALIGN_EPI = false, bool SP2 = false>
; __device__ __forceinline__ void gemm_phase(PG8_LAS unsigned char* lds, const Gemm g, const Sched& S, const Epi& E) {
;     ...
;     PG8_WAIT_V(0);
;     if constexpr (!ALIGN_EPI) { if (wr == 0) PG8_BAR; }
;     PG8_BAR;
	v_mul_f32_e32 v68, 0xbfb8aa3b, v59
	v_mul_f32_e32 v69, v54, v50
	v_exp_f32_e32 v68, v68
	v_add_f32_e32 v50, 1.0, v58
	v_rcp_f32_e32 v50, v50
	v_mul_f32_e32 v58, 0xbfb8aa3b, v64
	v_exp_f32_e32 v58, v58
	v_add_f32_e32 v54, 1.0, v68
	v_mul_f32_e32 v50, v63, v50
	v_rcp_f32_e32 v54, v54
	v_mul_f32_e32 v50, v50, v55
	v_add_f32_e32 v55, 1.0, v58
	v_rcp_f32_e32 v55, v55
	v_mul_f32_e32 v54, v59, v54
	v_mul_f32_e32 v58, 0xbfb8aa3b, v60
	v_mul_f32_e32 v59, v54, v51
	v_mul_f32_e32 v51, v64, v55
	v_exp_f32_e32 v58, v58
	v_mul_f32_e32 v51, v51, v56
	v_mul_f32_e32 v55, 0xbfb8aa3b, v65
	v_mul_f32_e32 v56, 0xbfb8aa3b, v61
	v_exp_f32_e32 v55, v55
	v_exp_f32_e32 v56, v56
	v_add_f32_e32 v54, 1.0, v58
	v_rcp_f32_e32 v54, v54
	v_add_f32_e32 v55, 1.0, v55
	v_add_f32_e32 v56, 1.0, v56
	v_rcp_f32_e32 v55, v55
	v_rcp_f32_e32 v56, v56
	v_mul_f32_e32 v54, v60, v54
	v_mul_f32_e32 v58, v54, v52
	v_mul_f32_e32 v52, v65, v55
	v_mul_f32_e32 v54, v61, v56
	v_mul_f32_e32 v52, v52, v57
	v_mul_f32_e32 v53, v54, v53
	v_lshl_add_u64 v[54:55], v[66:67], 0, v[114:115]
	v_cvt_pk_bf16_f32 v50, v62, v50
	v_cvt_pk_bf16_f32 v51, v51, v52
	v_cvt_pk_bf16_f32 v52, v69, v59
	v_cvt_pk_bf16_f32 v53, v58, v53
	global_store_dwordx4 v[54:55], v[50:53], off
	s_nop 1
	v_mul_f32_e32 v50, 0xbfb8aa3b, v46
	v_exp_f32_e32 v50, v50
	v_mul_f32_e32 v51, 0xbfb8aa3b, v42
	v_exp_f32_e32 v51, v51
	v_add_u32_e32 v52, 0x90, v147
	v_add_f32_e32 v50, 1.0, v50
	v_rcp_f32_e32 v53, v50
	v_add_f32_e32 v50, 1.0, v51
	v_rcp_f32_e32 v54, v50
	v_mad_i64_i32 v[50:51], s[62:63], v52, s90, v[134:135]
	v_mul_f32_e32 v46, v46, v53
	v_mul_f32_e32 v46, v46, v38
	v_mul_f32_e32 v38, v42, v54
	v_mul_f32_e32 v42, 0xbfb8aa3b, v47
	v_exp_f32_e32 v42, v42
	v_mul_f32_e32 v52, 0xbfb8aa3b, v43
	v_mul_f32_e32 v53, v38, v34
	v_exp_f32_e32 v52, v52
	v_add_f32_e32 v34, 1.0, v42
	v_rcp_f32_e32 v34, v34
	v_mul_f32_e32 v42, 0xbfb8aa3b, v48
	v_exp_f32_e32 v42, v42
	v_add_f32_e32 v38, 1.0, v52
	v_mul_f32_e32 v34, v47, v34
	v_rcp_f32_e32 v38, v38
	v_mul_f32_e32 v34, v34, v39
	v_add_f32_e32 v39, 1.0, v42
	v_rcp_f32_e32 v39, v39
	v_mul_f32_e32 v38, v43, v38
	v_mul_f32_e32 v42, 0xbfb8aa3b, v44
	v_mul_f32_e32 v43, v38, v35
	v_mul_f32_e32 v35, v48, v39
	v_exp_f32_e32 v42, v42
	v_mul_f32_e32 v35, v35, v40
	v_mul_f32_e32 v39, 0xbfb8aa3b, v49
	v_mul_f32_e32 v40, 0xbfb8aa3b, v45
	v_exp_f32_e32 v39, v39
	v_exp_f32_e32 v40, v40
	v_add_f32_e32 v38, 1.0, v42
	v_rcp_f32_e32 v38, v38
	v_add_f32_e32 v39, 1.0, v39
	v_add_f32_e32 v40, 1.0, v40
	v_rcp_f32_e32 v39, v39
	v_rcp_f32_e32 v40, v40
	v_mul_f32_e32 v38, v44, v38
	v_mul_f32_e32 v42, v38, v36
	v_mul_f32_e32 v36, v49, v39
	v_mul_f32_e32 v38, v45, v40
	v_mul_f32_e32 v36, v36, v41
	v_mul_f32_e32 v37, v38, v37
	v_lshl_add_u64 v[38:39], v[50:51], 0, v[114:115]
	v_cvt_pk_bf16_f32 v34, v46, v34
	v_cvt_pk_bf16_f32 v35, v35, v36
	v_cvt_pk_bf16_f32 v36, v53, v43
	v_cvt_pk_bf16_f32 v37, v42, v37
	global_store_dwordx4 v[38:39], v[34:37], off
	s_nop 1
	v_mul_f32_e32 v34, 0xbfb8aa3b, v30
	v_exp_f32_e32 v34, v34
	v_mul_f32_e32 v35, 0xbfb8aa3b, v26
	v_exp_f32_e32 v35, v35
	v_add_u32_e32 v36, 0xa0, v147
	v_add_f32_e32 v34, 1.0, v34
	v_rcp_f32_e32 v37, v34
	v_add_f32_e32 v34, 1.0, v35
	v_rcp_f32_e32 v38, v34
	v_mad_i64_i32 v[34:35], s[62:63], v36, s90, v[134:135]
	v_mul_f32_e32 v30, v30, v37
	v_mul_f32_e32 v30, v30, v22
	v_mul_f32_e32 v22, v26, v38
	v_mul_f32_e32 v26, 0xbfb8aa3b, v31
	v_exp_f32_e32 v26, v26
	v_mul_f32_e32 v36, 0xbfb8aa3b, v27
	v_mul_f32_e32 v37, v22, v18
	v_exp_f32_e32 v36, v36
	v_add_f32_e32 v18, 1.0, v26
	v_rcp_f32_e32 v18, v18
	v_mul_f32_e32 v26, 0xbfb8aa3b, v32
	v_exp_f32_e32 v26, v26
	v_add_f32_e32 v22, 1.0, v36
	v_mul_f32_e32 v18, v31, v18
	v_rcp_f32_e32 v22, v22
	v_mul_f32_e32 v18, v18, v23
	v_add_f32_e32 v23, 1.0, v26
	v_rcp_f32_e32 v23, v23
	v_mul_f32_e32 v22, v27, v22
	v_mul_f32_e32 v26, 0xbfb8aa3b, v28
	v_mul_f32_e32 v27, v22, v19
	v_mul_f32_e32 v19, v32, v23
	v_exp_f32_e32 v26, v26
	v_mul_f32_e32 v19, v19, v24
	v_mul_f32_e32 v23, 0xbfb8aa3b, v33
	v_mul_f32_e32 v24, 0xbfb8aa3b, v29
	v_exp_f32_e32 v23, v23
	v_exp_f32_e32 v24, v24
	v_add_f32_e32 v22, 1.0, v26
	v_rcp_f32_e32 v22, v22
	v_add_f32_e32 v23, 1.0, v23
	v_add_f32_e32 v24, 1.0, v24
	v_rcp_f32_e32 v23, v23
	v_rcp_f32_e32 v24, v24
	v_mul_f32_e32 v22, v28, v22
	v_mul_f32_e32 v26, v22, v20
	v_mul_f32_e32 v20, v33, v23
	v_mul_f32_e32 v22, v29, v24
	v_mul_f32_e32 v20, v20, v25
	v_mul_f32_e32 v21, v22, v21
	v_lshl_add_u64 v[22:23], v[34:35], 0, v[114:115]
	v_cvt_pk_bf16_f32 v18, v30, v18
	v_cvt_pk_bf16_f32 v19, v19, v20
	v_cvt_pk_bf16_f32 v20, v37, v27
	v_cvt_pk_bf16_f32 v21, v26, v21
	global_store_dwordx4 v[22:23], v[18:21], off
	s_nop 1
	v_mul_f32_e32 v18, 0xbfb8aa3b, v14
	v_exp_f32_e32 v18, v18
	v_mul_f32_e32 v19, 0xbfb8aa3b, v10
	v_exp_f32_e32 v19, v19
	v_add_u32_e32 v20, 0xb0, v147
	v_add_f32_e32 v18, 1.0, v18
	v_rcp_f32_e32 v21, v18
	v_add_f32_e32 v18, 1.0, v19
	v_rcp_f32_e32 v22, v18
	v_mad_i64_i32 v[18:19], s[62:63], v20, s90, v[134:135]
	v_mul_f32_e32 v14, v14, v21
	v_mul_f32_e32 v14, v14, v6
	v_mul_f32_e32 v6, v10, v22
	v_mul_f32_e32 v10, 0xbfb8aa3b, v15
	v_exp_f32_e32 v10, v10
	v_mul_f32_e32 v20, 0xbfb8aa3b, v11
	v_mul_f32_e32 v21, v6, v2
	v_exp_f32_e32 v20, v20
	v_add_f32_e32 v2, 1.0, v10
	v_rcp_f32_e32 v2, v2
	v_mul_f32_e32 v10, 0xbfb8aa3b, v16
	v_exp_f32_e32 v10, v10
	v_add_f32_e32 v6, 1.0, v20
	v_mul_f32_e32 v2, v15, v2
	v_rcp_f32_e32 v6, v6
	v_mul_f32_e32 v2, v2, v7
	v_add_f32_e32 v7, 1.0, v10
	v_rcp_f32_e32 v7, v7
	v_mul_f32_e32 v6, v11, v6
	v_mul_f32_e32 v10, 0xbfb8aa3b, v12
	v_mul_f32_e32 v11, v6, v3
	v_mul_f32_e32 v3, v16, v7
	v_exp_f32_e32 v10, v10
	v_mul_f32_e32 v3, v3, v8
	v_mul_f32_e32 v7, 0xbfb8aa3b, v17
	v_mul_f32_e32 v8, 0xbfb8aa3b, v13
	v_exp_f32_e32 v7, v7
	v_exp_f32_e32 v8, v8
	v_add_f32_e32 v6, 1.0, v10
	v_rcp_f32_e32 v6, v6
	v_add_f32_e32 v7, 1.0, v7
	v_add_f32_e32 v8, 1.0, v8
	v_rcp_f32_e32 v7, v7
	v_rcp_f32_e32 v8, v8
	v_mul_f32_e32 v6, v12, v6
	v_mul_f32_e32 v10, v6, v4
	v_mul_f32_e32 v4, v17, v7
	v_mul_f32_e32 v6, v13, v8
	v_mul_f32_e32 v4, v4, v9
	v_mul_f32_e32 v5, v6, v5
	v_lshl_add_u64 v[6:7], v[18:19], 0, v[114:115]
	s_mov_b64 s[62:63], s[16:17]
	v_cvt_pk_bf16_f32 v2, v14, v2
	v_cvt_pk_bf16_f32 v3, v3, v4
	v_cvt_pk_bf16_f32 v4, v21, v11
	v_cvt_pk_bf16_f32 v5, v10, v5
	global_store_dwordx4 v[6:7], v[2:5], off
	s_cbranch_vccz .LBB0_135
	s_waitcnt vmcnt(0)
	s_cmpk_gt_u32 s3, 0xff
	s_cbranch_scc1 .LBB0_142
	s_barrier

; #define PG8_STAGE(bufoff, gbase, voff) do { _Pragma("unroll") for (int _i = 0; _i < 2; ++_i) \
;         asm volatile("s_mov_b32 m0, %2\n\ts_nop 0\n\tglobal_load_lds_dwordx4 %0, %1" :: "v"((voff)[_i]), "s"((const char*)(gbase)), "s"(ldsbase + (unsigned)(bufoff) + ldsw + (unsigned)_i * 8192u) : "memory", "m0"); } while (0)
; #define PG8_LDA(dst, b, h) do { _Pragma("unroll") for (int m = 0; m < 4; ++m) _Pragma("unroll") for (int k = 0; k < 2; ++k) dst[m][k] = *(const PG8_LAS bf16x8*)(lds + PG8_SA(b, h) + aoff + m * 2048 + k * 1024); } while (0)
; #define PG8_LDB(dst, b, h) do { _Pragma("unroll") for (int n = 0; n < 2; ++n) _Pragma("unroll") for (int k = 0; k < 2; ++k) dst[n][k] = *(const PG8_LAS bf16x8*)(lds + PG8_SB(b, h) + boff + n * 2048 + k * 1024); } while (0)
; #define PG8_MMA(ai, bj, At, Bt) do { __builtin_amdgcn_s_setprio(1); _Pragma("unroll") for (int m = 0; m < 4; ++m) _Pragma("unroll") for (int n = 0; n < 2; ++n) _Pragma("unroll") for (int k = 0; k < 2; ++k) \
;         acc[ai][bj][m][n] = __builtin_amdgcn_mfma_f32_16x16x32_bf16(Bt[n][k], At[m][k], acc[ai][bj][m][n], 0, 0, 0); __builtin_amdgcn_s_setprio(0); } while (0)
; template <class Epi, class Sched, bool ALIGN_EPI = false, bool SP2 = false>
; __device__ __forceinline__ void gemm_phase(PG8_LAS unsigned char* lds, const Gemm g, const Sched& S, const Epi& E) {
;     ...
;             const bool last = (t == nt - 2);
;             const char* a1 = cA + (size_t)(t + 1) * kstep;
;             const char* a2 = last ? nA : cA + (size_t)(t + 2) * kstep; const char* b2 = last ? nB : cB + (size_t)(t + 2) * kstep;
;             const char* a3 = a2 + kstep; const char* b3 = b2 + kstep;
;             if (last && has_next) S.a_ready(nxt);
;             if constexpr (epi_has_mid<Epi>::value) { if (t == Epi::MID_T) E.mid(acc, cur, wr, wc, fr, fq); }
;             if constexpr (SP2) {
;             PG8_LDB(B0, 0, 0); PG8_LDB(B1, 0, 1); PG8_SCHED; PG8_LDA(At, 0, 0); PG8_STAGE(PG8_SA(1, 1), a1 + hstep, voffA);
;             PG8_WAIT_V(8); PG8_WAIT_L(0); PG8_BAR; PG8_MMA(0, 0, At, B0); PG8_MMA(0, 1, At, B1); PG8_BAR; PG8_SCHED;
;             PG8_LDA(At, 0, 1); PG8_STAGE(PG8_SB(0, 0), b2, voffB); PG8_STAGE(PG8_SB(0, 1), b2 + hstep, voffB); PG8_STAGE(PG8_SA(0, 0), a2, voffA);
;             PG8_WAIT_V(8); PG8_WAIT_L(0); PG8_BAR; PG8_MMA(1, 0, At, B0); PG8_MMA(1, 1, At, B1); PG8_BAR; PG8_SCHED;
.LBB0_234:
	ds_read_b128 v[134:137], v145
	ds_read_b128 v[152:155], v145 offset:1024
	ds_read_b128 v[156:159], v145 offset:2048
	ds_read_b128 v[160:163], v145 offset:3072
	ds_read_b128 v[164:167], v146
	ds_read_b128 v[168:171], v146 offset:1024
	ds_read_b128 v[172:175], v146 offset:2048
	ds_read_b128 v[176:179], v146 offset:3072
	s_cmpk_eq_i32 s57, 0xa8
	s_cselect_b32 s76, s4, s53
	s_cselect_b32 s77, s5, s54
	s_cselect_b32 s66, s46, s55
	s_cselect_b32 s67, s47, s56
	s_add_u32 s62, s76, 0x80
	s_addc_u32 s63, s77, 0
	ds_read_b128 v[180:183], v147
	ds_read_b128 v[184:187], v147 offset:1024
	ds_read_b128 v[188:191], v147 offset:2048
	ds_read_b128 v[192:195], v147 offset:3072
	ds_read_b128 v[196:199], v147 offset:4096
	ds_read_b128 v[200:203], v147 offset:5120
	ds_read_b128 v[204:207], v147 offset:6144
	ds_read_b128 v[208:211], v147 offset:7168
	s_mov_b32 m0, s94
	s_nop 0
	global_load_lds_dwordx4 v1, s[50:51]
	s_nop 0
	s_mov_b32 m0, s95
	s_nop 0
	global_load_lds_dwordx4 v141, s[50:51]
	s_waitcnt vmcnt(8)
	s_waitcnt lgkmcnt(0)
	s_barrier
	s_setprio 1
	s_waitcnt lgkmcnt(7)
	v_mfma_f32_16x16x32_bf16 v[126:129], v[134:137], v[180:183], v[126:129]
	v_mfma_f32_16x16x32_bf16 v[126:129], v[152:155], v[184:187], v[126:129]
	s_waitcnt lgkmcnt(5)
	v_mfma_f32_16x16x32_bf16 v[122:125], v[160:163], v[184:187], v[122:125]
	v_mfma_f32_16x16x32_bf16 v[122:125], v[156:159], v[180:183], v[122:125]
	s_waitcnt lgkmcnt(3)
	v_mfma_f32_16x16x32_bf16 v[118:121], v[164:167], v[180:183], v[118:121]
	v_mfma_f32_16x16x32_bf16 v[118:121], v[168:171], v[184:187], v[118:121]
	s_waitcnt lgkmcnt(1)
	v_mfma_f32_16x16x32_bf16 v[114:117], v[176:179], v[184:187], v[114:117]
	v_mfma_f32_16x16x32_bf16 v[114:117], v[172:175], v[180:183], v[114:117]
	v_mfma_f32_16x16x32_bf16 v[98:101], v[172:175], v[188:191], v[98:101]
	v_mfma_f32_16x16x32_bf16 v[98:101], v[176:179], v[192:195], v[98:101]
	v_mfma_f32_16x16x32_bf16 v[102:105], v[168:171], v[192:195], v[102:105]
	v_mfma_f32_16x16x32_bf16 v[102:105], v[164:167], v[188:191], v[102:105]
	v_mfma_f32_16x16x32_bf16 v[106:109], v[156:159], v[188:191], v[106:109]
	v_mfma_f32_16x16x32_bf16 v[106:109], v[160:163], v[192:195], v[106:109]
	s_waitcnt lgkmcnt(0)
	v_mfma_f32_16x16x32_bf16 v[110:113], v[152:155], v[192:195], v[110:113]
	v_mfma_f32_16x16x32_bf16 v[110:113], v[134:137], v[188:191], v[110:113]
	s_setprio 0
	s_setprio 1
	v_mfma_f32_16x16x32_bf16 v[94:97], v[134:137], v[196:199], v[94:97]
	v_mfma_f32_16x16x32_bf16 v[94:97], v[152:155], v[200:203], v[94:97]
	v_mfma_f32_16x16x32_bf16 v[90:93], v[160:163], v[200:203], v[90:93]
	v_mfma_f32_16x16x32_bf16 v[90:93], v[156:159], v[196:199], v[90:93]
	v_mfma_f32_16x16x32_bf16 v[86:89], v[164:167], v[196:199], v[86:89]
	v_mfma_f32_16x16x32_bf16 v[86:89], v[168:171], v[200:203], v[86:89]
	v_mfma_f32_16x16x32_bf16 v[82:85], v[176:179], v[200:203], v[82:85]
	v_mfma_f32_16x16x32_bf16 v[82:85], v[172:175], v[196:199], v[82:85]
	v_mfma_f32_16x16x32_bf16 v[66:69], v[172:175], v[204:207], v[66:69]
	v_mfma_f32_16x16x32_bf16 v[66:69], v[176:179], v[208:211], v[66:69]
	v_mfma_f32_16x16x32_bf16 v[70:73], v[168:171], v[208:211], v[70:73]
	v_mfma_f32_16x16x32_bf16 v[70:73], v[164:167], v[204:207], v[70:73]
	v_mfma_f32_16x16x32_bf16 v[74:77], v[156:159], v[204:207], v[74:77]
	v_mfma_f32_16x16x32_bf16 v[74:77], v[160:163], v[208:211], v[74:77]
	v_mfma_f32_16x16x32_bf16 v[78:81], v[152:155], v[208:211], v[78:81]
	s_setprio 2
	s_barrier
	v_mfma_f32_16x16x32_bf16 v[78:81], v[134:137], v[204:207], v[78:81]
	s_setprio 0
	ds_read_b128 v[180:183], v147 offset:16384
	ds_read_b128 v[184:187], v147 offset:17408
	ds_read_b128 v[188:191], v147 offset:18432
	ds_read_b128 v[192:195], v147 offset:19456
	ds_read_b128 v[196:199], v147 offset:20480
	ds_read_b128 v[200:203], v147 offset:21504
	ds_read_b128 v[252:255], v147 offset:22528
	ds_read_b128 v[208:211], v147 offset:23552
	s_mov_b32 m0, s64
	s_nop 0
	global_load_lds_dwordx4 v140, s[66:67]
	s_add_u32 s58, s66, 0x2b0000
	s_mov_b32 m0, s65
	s_nop 0
	global_load_lds_dwordx4 v142, s[66:67]
	s_addc_u32 s59, s67, 0
	s_mov_b32 m0, s82
	s_nop 0
	global_load_lds_dwordx4 v140, s[58:59]
	s_nop 0
	s_mov_b32 m0, s83
	s_nop 0
	global_load_lds_dwordx4 v142, s[58:59]
	s_nop 0
	s_mov_b32 m0, s35
	s_nop 0
	global_load_lds_dwordx4 v1, s[76:77]
	s_nop 0
	s_mov_b32 m0, s84
	s_nop 0
	global_load_lds_dwordx4 v141, s[76:77]
	s_waitcnt vmcnt(8)
	s_waitcnt lgkmcnt(0)
	s_barrier
	s_setprio 1
	s_waitcnt lgkmcnt(7)
	v_mfma_f32_16x16x32_bf16 v[62:65], v[134:137], v[180:183], v[62:65]
	v_mfma_f32_16x16x32_bf16 v[62:65], v[152:155], v[184:187], v[62:65]
	s_waitcnt lgkmcnt(5)
	v_mfma_f32_16x16x32_bf16 v[58:61], v[160:163], v[184:187], v[58:61]
	v_mfma_f32_16x16x32_bf16 v[58:61], v[156:159], v[180:183], v[58:61]
	s_waitcnt lgkmcnt(3)
	v_mfma_f32_16x16x32_bf16 v[54:57], v[164:167], v[180:183], v[54:57]
	v_mfma_f32_16x16x32_bf16 v[54:57], v[168:171], v[184:187], v[54:57]
	s_waitcnt lgkmcnt(1)
	v_mfma_f32_16x16x32_bf16 v[50:53], v[176:179], v[184:187], v[50:53]
	v_mfma_f32_16x16x32_bf16 v[50:53], v[172:175], v[180:183], v[50:53]
	v_mfma_f32_16x16x32_bf16 v[34:37], v[172:175], v[188:191], v[34:37]
	v_mfma_f32_16x16x32_bf16 v[34:37], v[176:179], v[192:195], v[34:37]
	v_mfma_f32_16x16x32_bf16 v[38:41], v[168:171], v[192:195], v[38:41]
	v_mfma_f32_16x16x32_bf16 v[38:41], v[164:167], v[188:191], v[38:41]
	v_mfma_f32_16x16x32_bf16 v[42:45], v[156:159], v[188:191], v[42:45]
	v_mfma_f32_16x16x32_bf16 v[42:45], v[160:163], v[192:195], v[42:45]
	s_waitcnt lgkmcnt(0)
	v_mfma_f32_16x16x32_bf16 v[46:49], v[152:155], v[192:195], v[46:49]
	v_mfma_f32_16x16x32_bf16 v[46:49], v[134:137], v[188:191], v[46:49]
	s_setprio 0
	s_setprio 1
	v_mfma_f32_16x16x32_bf16 v[30:33], v[134:137], v[196:199], v[30:33]
	v_mfma_f32_16x16x32_bf16 v[30:33], v[152:155], v[200:203], v[30:33]
	v_mfma_f32_16x16x32_bf16 v[26:29], v[160:163], v[200:203], v[26:29]
	v_mfma_f32_16x16x32_bf16 v[26:29], v[156:159], v[196:199], v[26:29]
	v_mfma_f32_16x16x32_bf16 v[22:25], v[164:167], v[196:199], v[22:25]
	v_mfma_f32_16x16x32_bf16 v[22:25], v[168:171], v[200:203], v[22:25]
	v_mfma_f32_16x16x32_bf16 v[18:21], v[176:179], v[200:203], v[18:21]
	v_mfma_f32_16x16x32_bf16 v[18:21], v[172:175], v[196:199], v[18:21]
	v_mfma_f32_16x16x32_bf16 v[2:5], v[172:175], v[252:255], v[2:5]
	v_mfma_f32_16x16x32_bf16 v[2:5], v[176:179], v[208:211], v[2:5]
	v_mfma_f32_16x16x32_bf16 v[6:9], v[168:171], v[208:211], v[6:9]
	v_mfma_f32_16x16x32_bf16 v[6:9], v[164:167], v[252:255], v[6:9]
	v_mfma_f32_16x16x32_bf16 v[10:13], v[156:159], v[252:255], v[10:13]
	v_mfma_f32_16x16x32_bf16 v[10:13], v[160:163], v[208:211], v[10:13]
	v_mfma_f32_16x16x32_bf16 v[14:17], v[152:155], v[208:211], v[14:17]
	s_setprio 2
	s_barrier
; #define PG8_STAGE(bufoff, gbase, voff) do { _Pragma("unroll") for (int _i = 0; _i < 2; ++_i) \
;         asm volatile("s_mov_b32 m0, %2\n\ts_nop 0\n\tglobal_load_lds_dwordx4 %0, %1" :: "v"((voff)[_i]), "s"((const char*)(gbase)), "s"(ldsbase + (unsigned)(bufoff) + ldsw + (unsigned)_i * 8192u) : "memory", "m0"); } while (0)
; #define PG8_LDA(dst, b, h) do { _Pragma("unroll") for (int m = 0; m < 4; ++m) _Pragma("unroll") for (int k = 0; k < 2; ++k) dst[m][k] = *(const PG8_LAS bf16x8*)(lds + PG8_SA(b, h) + aoff + m * 2048 + k * 1024); } while (0)
; #define PG8_LDB(dst, b, h) do { _Pragma("unroll") for (int n = 0; n < 2; ++n) _Pragma("unroll") for (int k = 0; k < 2; ++k) dst[n][k] = *(const PG8_LAS bf16x8*)(lds + PG8_SB(b, h) + boff + n * 2048 + k * 1024); } while (0)
; #define PG8_MMA(ai, bj, At, Bt) do { __builtin_amdgcn_s_setprio(1); _Pragma("unroll") for (int m = 0; m < 4; ++m) _Pragma("unroll") for (int n = 0; n < 2; ++n) _Pragma("unroll") for (int k = 0; k < 2; ++k) \
;         acc[ai][bj][m][n] = __builtin_amdgcn_mfma_f32_16x16x32_bf16(Bt[n][k], At[m][k], acc[ai][bj][m][n], 0, 0, 0); __builtin_amdgcn_s_setprio(0); } while (0)
; #define PG8_WAIT_V(n) asm volatile("s_waitcnt vmcnt(" #n ")" ::: "memory")
; #define PG8_WAIT_L(n) asm volatile("s_waitcnt lgkmcnt(" #n ")" ::: "memory")
; #define PG8_BAR __builtin_amdgcn_s_barrier()
; #define PG8_SCHED __builtin_amdgcn_sched_barrier(0)
; template <class Epi, class Sched, bool ALIGN_EPI = false, bool SP2 = false>
; __device__ __forceinline__ void gemm_phase(PG8_LAS unsigned char* lds, const Gemm g, const Sched& S, const Epi& E) {
;     ...
;             PG8_WAIT_V(8); PG8_WAIT_L(0); PG8_BAR; PG8_MMA(1, 0, At, B0); PG8_MMA(1, 1, At, B1); PG8_BAR; PG8_SCHED;
;             PG8_LDB(B0, 1, 0); PG8_LDB(B1, 1, 1); PG8_SCHED; PG8_LDA(At, 1, 0); PG8_STAGE(PG8_SA(0, 1), a2 + hstep, voffA);
;             PG8_WAIT_V(8); PG8_WAIT_L(0); PG8_BAR; PG8_MMA(0, 0, At, B0); PG8_MMA(0, 1, At, B1); PG8_BAR; PG8_SCHED;
	v_mfma_f32_16x16x32_bf16 v[14:17], v[134:137], v[252:255], v[14:17]
	s_setprio 0
	ds_read_b128 v[248:251], v148
	ds_read_b128 v[152:155], v148 offset:1024
	ds_read_b128 v[156:159], v148 offset:2048
	ds_read_b128 v[160:163], v148 offset:3072
	ds_read_b128 v[164:167], v149
	ds_read_b128 v[168:171], v149 offset:1024
	ds_read_b128 v[172:175], v149 offset:2048
	ds_read_b128 v[176:179], v149 offset:3072
	ds_read_b128 v[180:183], v147 offset:32768
	ds_read_b128 v[184:187], v147 offset:33792
	ds_read_b128 v[188:191], v147 offset:34816
	ds_read_b128 v[192:195], v147 offset:35840
	ds_read_b128 v[196:199], v147 offset:36864
	ds_read_b128 v[200:203], v147 offset:37888
	ds_read_b128 v[204:207], v147 offset:38912
	ds_read_b128 v[208:211], v147 offset:39936
	s_add_u32 s58, s76, 0x2b0000
	s_addc_u32 s59, s77, 0
	s_mov_b32 m0, s85
	s_nop 0
	global_load_lds_dwordx4 v1, s[58:59]
	s_nop 0
	s_mov_b32 m0, s86
	s_nop 0
	global_load_lds_dwordx4 v141, s[58:59]
	s_waitcnt vmcnt(8)
	s_waitcnt lgkmcnt(0)
	s_barrier
	s_setprio 1
	s_waitcnt lgkmcnt(7)
	v_mfma_f32_16x16x32_bf16 v[126:129], v[248:251], v[180:183], v[126:129]
	v_mfma_f32_16x16x32_bf16 v[126:129], v[152:155], v[184:187], v[126:129]
	s_waitcnt lgkmcnt(5)
	v_mfma_f32_16x16x32_bf16 v[122:125], v[160:163], v[184:187], v[122:125]
	v_mfma_f32_16x16x32_bf16 v[122:125], v[156:159], v[180:183], v[122:125]
	s_waitcnt lgkmcnt(3)
	v_mfma_f32_16x16x32_bf16 v[118:121], v[164:167], v[180:183], v[118:121]
	v_mfma_f32_16x16x32_bf16 v[118:121], v[168:171], v[184:187], v[118:121]
	s_waitcnt lgkmcnt(1)
	v_mfma_f32_16x16x32_bf16 v[114:117], v[176:179], v[184:187], v[114:117]
	v_mfma_f32_16x16x32_bf16 v[114:117], v[172:175], v[180:183], v[114:117]
	v_mfma_f32_16x16x32_bf16 v[98:101], v[172:175], v[188:191], v[98:101]
	v_mfma_f32_16x16x32_bf16 v[98:101], v[176:179], v[192:195], v[98:101]
	v_mfma_f32_16x16x32_bf16 v[102:105], v[168:171], v[192:195], v[102:105]
	v_mfma_f32_16x16x32_bf16 v[102:105], v[164:167], v[188:191], v[102:105]
	v_mfma_f32_16x16x32_bf16 v[106:109], v[156:159], v[188:191], v[106:109]
	v_mfma_f32_16x16x32_bf16 v[106:109], v[160:163], v[192:195], v[106:109]
	s_waitcnt lgkmcnt(0)
	v_mfma_f32_16x16x32_bf16 v[110:113], v[152:155], v[192:195], v[110:113]
	v_mfma_f32_16x16x32_bf16 v[110:113], v[248:251], v[188:191], v[110:113]
	s_setprio 0
	s_setprio 1
	v_mfma_f32_16x16x32_bf16 v[94:97], v[248:251], v[196:199], v[94:97]
	v_mfma_f32_16x16x32_bf16 v[94:97], v[152:155], v[200:203], v[94:97]
	v_mfma_f32_16x16x32_bf16 v[90:93], v[160:163], v[200:203], v[90:93]
	v_mfma_f32_16x16x32_bf16 v[90:93], v[156:159], v[196:199], v[90:93]
	v_mfma_f32_16x16x32_bf16 v[86:89], v[164:167], v[196:199], v[86:89]
	v_mfma_f32_16x16x32_bf16 v[86:89], v[168:171], v[200:203], v[86:89]
	v_mfma_f32_16x16x32_bf16 v[82:85], v[176:179], v[200:203], v[82:85]
	v_mfma_f32_16x16x32_bf16 v[82:85], v[172:175], v[196:199], v[82:85]
	v_mfma_f32_16x16x32_bf16 v[66:69], v[172:175], v[204:207], v[66:69]
	v_mfma_f32_16x16x32_bf16 v[66:69], v[176:179], v[208:211], v[66:69]
	v_mfma_f32_16x16x32_bf16 v[70:73], v[168:171], v[208:211], v[70:73]
	v_mfma_f32_16x16x32_bf16 v[70:73], v[164:167], v[204:207], v[70:73]
	v_mfma_f32_16x16x32_bf16 v[74:77], v[156:159], v[204:207], v[74:77]
	v_mfma_f32_16x16x32_bf16 v[74:77], v[160:163], v[208:211], v[74:77]
	v_mfma_f32_16x16x32_bf16 v[78:81], v[152:155], v[208:211], v[78:81]
	s_setprio 2
	s_barrier
; #define PG8_STAGE(bufoff, gbase, voff) do { _Pragma("unroll") for (int _i = 0; _i < 2; ++_i) \
;         asm volatile("s_mov_b32 m0, %2\n\ts_nop 0\n\tglobal_load_lds_dwordx4 %0, %1" :: "v"((voff)[_i]), "s"((const char*)(gbase)), "s"(ldsbase + (unsigned)(bufoff) + ldsw + (unsigned)_i * 8192u) : "memory", "m0"); } while (0)
; #define PG8_LDA(dst, b, h) do { _Pragma("unroll") for (int m = 0; m < 4; ++m) _Pragma("unroll") for (int k = 0; k < 2; ++k) dst[m][k] = *(const PG8_LAS bf16x8*)(lds + PG8_SA(b, h) + aoff + m * 2048 + k * 1024); } while (0)
; #define PG8_MMA(ai, bj, At, Bt) do { __builtin_amdgcn_s_setprio(1); _Pragma("unroll") for (int m = 0; m < 4; ++m) _Pragma("unroll") for (int n = 0; n < 2; ++n) _Pragma("unroll") for (int k = 0; k < 2; ++k) \
;         acc[ai][bj][m][n] = __builtin_amdgcn_mfma_f32_16x16x32_bf16(Bt[n][k], At[m][k], acc[ai][bj][m][n], 0, 0, 0); __builtin_amdgcn_s_setprio(0); } while (0)
; #define PG8_WAIT_V(n) asm volatile("s_waitcnt vmcnt(" #n ")" ::: "memory")
; #define PG8_WAIT_L(n) asm volatile("s_waitcnt lgkmcnt(" #n ")" ::: "memory")
; #define PG8_BAR __builtin_amdgcn_s_barrier()
; #define PG8_SCHED __builtin_amdgcn_sched_barrier(0)
; template <class Epi, class Sched, bool ALIGN_EPI = false, bool SP2 = false>
; __device__ __forceinline__ void gemm_phase(PG8_LAS unsigned char* lds, const Gemm g, const Sched& S, const Epi& E) {
;     ...
;             PG8_WAIT_V(8); PG8_WAIT_L(0); PG8_BAR; PG8_MMA(0, 0, At, B0); PG8_MMA(0, 1, At, B1); PG8_BAR; PG8_SCHED;
;             PG8_LDA(At, 1, 1); PG8_STAGE(PG8_SB(1, 0), b3, voffB); PG8_STAGE(PG8_SB(1, 1), b3 + hstep, voffB); PG8_STAGE(PG8_SA(1, 0), a3, voffA);
;             PG8_WAIT_V(8); PG8_WAIT_L(0); PG8_BAR; PG8_MMA(1, 0, At, B0); PG8_MMA(1, 1, At, B1); PG8_BAR; PG8_SCHED;
;     ...
;         if constexpr (ALIGN_EPI) { if (wr == 0) PG8_BAR; }
	v_mfma_f32_16x16x32_bf16 v[78:81], v[248:251], v[204:207], v[78:81]
	s_setprio 0
	ds_read_b128 v[180:183], v147 offset:49152
	ds_read_b128 v[184:187], v147 offset:50176
	ds_read_b128 v[188:191], v147 offset:51200
	ds_read_b128 v[192:195], v147 offset:52224
	ds_read_b128 v[196:199], v147 offset:53248
	ds_read_b128 v[200:203], v147 offset:54272
	ds_read_b128 v[252:255], v147 offset:55296
	ds_read_b128 v[208:211], v147 offset:56320
	s_add_u32 s58, s66, 0x80
	s_addc_u32 s59, s67, 0
	s_mov_b32 m0, s88
	s_nop 0
	global_load_lds_dwordx4 v140, s[58:59]
	s_nop 0
	s_mov_b32 m0, s89
	s_nop 0
	global_load_lds_dwordx4 v142, s[58:59]
	s_add_u32 s58, s66, 0x2b0080
	s_addc_u32 s59, s67, 0
	s_mov_b32 m0, s92
	s_nop 0
	global_load_lds_dwordx4 v140, s[58:59]
	s_nop 0
	s_mov_b32 m0, s93
	s_nop 0
	global_load_lds_dwordx4 v142, s[58:59]
	s_nop 0
	s_mov_b32 m0, s90
	s_nop 0
	global_load_lds_dwordx4 v1, s[62:63]
	s_nop 0
	s_mov_b32 m0, s91
	s_nop 0
	global_load_lds_dwordx4 v141, s[62:63]
	s_waitcnt vmcnt(8)
	s_waitcnt lgkmcnt(0)
	s_barrier
	s_setprio 1
	s_waitcnt lgkmcnt(7)
	v_mfma_f32_16x16x32_bf16 v[62:65], v[248:251], v[180:183], v[62:65]
	v_mfma_f32_16x16x32_bf16 v[62:65], v[152:155], v[184:187], v[62:65]
	s_waitcnt lgkmcnt(5)
	v_mfma_f32_16x16x32_bf16 v[58:61], v[160:163], v[184:187], v[58:61]
	v_mfma_f32_16x16x32_bf16 v[58:61], v[156:159], v[180:183], v[58:61]
	s_waitcnt lgkmcnt(3)
	v_mfma_f32_16x16x32_bf16 v[54:57], v[164:167], v[180:183], v[54:57]
	v_mfma_f32_16x16x32_bf16 v[54:57], v[168:171], v[184:187], v[54:57]
	s_waitcnt lgkmcnt(1)
	v_mfma_f32_16x16x32_bf16 v[50:53], v[176:179], v[184:187], v[50:53]
	v_mfma_f32_16x16x32_bf16 v[50:53], v[172:175], v[180:183], v[50:53]
	v_mfma_f32_16x16x32_bf16 v[34:37], v[172:175], v[188:191], v[34:37]
	v_mfma_f32_16x16x32_bf16 v[34:37], v[176:179], v[192:195], v[34:37]
	v_mfma_f32_16x16x32_bf16 v[38:41], v[168:171], v[192:195], v[38:41]
	v_mfma_f32_16x16x32_bf16 v[38:41], v[164:167], v[188:191], v[38:41]
	v_mfma_f32_16x16x32_bf16 v[42:45], v[156:159], v[188:191], v[42:45]
	v_mfma_f32_16x16x32_bf16 v[42:45], v[160:163], v[192:195], v[42:45]
	s_waitcnt lgkmcnt(0)
	v_mfma_f32_16x16x32_bf16 v[46:49], v[152:155], v[192:195], v[46:49]
	v_mfma_f32_16x16x32_bf16 v[46:49], v[248:251], v[188:191], v[46:49]
	s_setprio 0
	s_setprio 1
	v_mfma_f32_16x16x32_bf16 v[30:33], v[248:251], v[196:199], v[30:33]
	v_mfma_f32_16x16x32_bf16 v[30:33], v[152:155], v[200:203], v[30:33]
	v_mfma_f32_16x16x32_bf16 v[26:29], v[160:163], v[200:203], v[26:29]
	v_mfma_f32_16x16x32_bf16 v[26:29], v[156:159], v[196:199], v[26:29]
	v_mfma_f32_16x16x32_bf16 v[22:25], v[164:167], v[196:199], v[22:25]
	v_mfma_f32_16x16x32_bf16 v[22:25], v[168:171], v[200:203], v[22:25]
	v_mfma_f32_16x16x32_bf16 v[18:21], v[176:179], v[200:203], v[18:21]
	v_mfma_f32_16x16x32_bf16 v[18:21], v[172:175], v[196:199], v[18:21]
	v_mfma_f32_16x16x32_bf16 v[2:5], v[172:175], v[252:255], v[2:5]
	v_mfma_f32_16x16x32_bf16 v[2:5], v[176:179], v[208:211], v[2:5]
	v_mfma_f32_16x16x32_bf16 v[6:9], v[168:171], v[208:211], v[6:9]
	v_mfma_f32_16x16x32_bf16 v[6:9], v[164:167], v[252:255], v[6:9]
	v_mfma_f32_16x16x32_bf16 v[10:13], v[156:159], v[252:255], v[10:13]
	v_mfma_f32_16x16x32_bf16 v[10:13], v[160:163], v[208:211], v[10:13]
	v_mfma_f32_16x16x32_bf16 v[14:17], v[152:155], v[208:211], v[14:17]
	s_setprio 2
	s_barrier
	v_mfma_f32_16x16x32_bf16 v[14:17], v[248:251], v[252:255], v[14:17]
	s_setprio 0
	s_add_i32 s57, s57, 2
	s_add_u32 s53, s53, 0x100
	s_addc_u32 s54, s54, 0
	s_add_u32 s55, s55, 0x100
	s_addc_u32 s56, s56, 0
	s_add_u32 s50, s50, 0x100
	s_addc_u32 s51, s51, 0
	s_cmpk_gt_u32 s57, 0xa9
	s_cbranch_scc0 .LBB0_234
	s_and_b64 vcc, exec, s[16:17]
	s_cbranch_vccz .LBB0_237
	s_barrier

; #define PG8_STAGE(bufoff, gbase, voff) do { _Pragma("unroll") for (int _i = 0; _i < 2; ++_i) \
;         asm volatile("s_mov_b32 m0, %2\n\ts_nop 0\n\tglobal_load_lds_dwordx4 %0, %1" :: "v"((voff)[_i]), "s"((const char*)(gbase)), "s"(ldsbase + (unsigned)(bufoff) + ldsw + (unsigned)_i * 8192u) : "memory", "m0"); } while (0)
; #define PG8_LDA(dst, b, h) do { _Pragma("unroll") for (int m = 0; m < 4; ++m) _Pragma("unroll") for (int k = 0; k < 2; ++k) dst[m][k] = *(const PG8_LAS bf16x8*)(lds + PG8_SA(b, h) + aoff + m * 2048 + k * 1024); } while (0)
; #define PG8_LDB(dst, b, h) do { _Pragma("unroll") for (int n = 0; n < 2; ++n) _Pragma("unroll") for (int k = 0; k < 2; ++k) dst[n][k] = *(const PG8_LAS bf16x8*)(lds + PG8_SB(b, h) + boff + n * 2048 + k * 1024); } while (0)
; #define PG8_MMA(ai, bj, At, Bt) do { __builtin_amdgcn_s_setprio(1); _Pragma("unroll") for (int m = 0; m < 4; ++m) _Pragma("unroll") for (int n = 0; n < 2; ++n) _Pragma("unroll") for (int k = 0; k < 2; ++k) \
;         acc[ai][bj][m][n] = __builtin_amdgcn_mfma_f32_16x16x32_bf16(Bt[n][k], At[m][k], acc[ai][bj][m][n], 0, 0, 0); __builtin_amdgcn_s_setprio(0); } while (0)
; template <class Epi, class Sched, bool ALIGN_EPI = false, bool SP2 = false>
; __device__ __forceinline__ void gemm_phase(PG8_LAS unsigned char* lds, const Gemm g, const Sched& S, const Epi& E) {
;     ...
;             const bool last = (t == nt - 2);
;             const char* a1 = cA + (size_t)(t + 1) * kstep;
;             const char* a2 = last ? nA : cA + (size_t)(t + 2) * kstep; const char* b2 = last ? nB : cB + (size_t)(t + 2) * kstep;
;             const char* a3 = a2 + kstep; const char* b3 = b2 + kstep;
;             if (last && has_next) S.a_ready(nxt);
;             if constexpr (epi_has_mid<Epi>::value) { if (t == Epi::MID_T) E.mid(acc, cur, wr, wc, fr, fq); }
;             if constexpr (SP2) {
;             PG8_LDB(B0, 0, 0); PG8_LDB(B1, 0, 1); PG8_SCHED; PG8_LDA(At, 0, 0); PG8_STAGE(PG8_SA(1, 1), a1 + hstep, voffA);
;             PG8_WAIT_V(8); PG8_WAIT_L(0); PG8_BAR; PG8_MMA(0, 0, At, B0); PG8_MMA(0, 1, At, B1); PG8_BAR; PG8_SCHED;
;             PG8_LDA(At, 0, 1); PG8_STAGE(PG8_SB(0, 0), b2, voffB); PG8_STAGE(PG8_SB(0, 1), b2 + hstep, voffB); PG8_STAGE(PG8_SA(0, 0), a2, voffA);
;             PG8_WAIT_V(8); PG8_WAIT_L(0); PG8_BAR; PG8_MMA(1, 0, At, B0); PG8_MMA(1, 1, At, B1); PG8_BAR; PG8_SCHED;
.LBB0_325:
	v_add_u32_e32 v138, 0x10000, v151
	ds_read_b128 v[154:157], v138
	ds_read_b128 v[158:161], v138 offset:1024
	ds_read_b128 v[162:165], v138 offset:2048
	ds_read_b128 v[166:169], v138 offset:3072
	v_add_u32_e32 v138, 0x14000, v151
	s_add_u32 s8, s82, 0x100
	ds_read_b128 v[170:173], v138
	ds_read_b128 v[174:177], v138 offset:1024
	ds_read_b128 v[178:181], v138 offset:2048
	ds_read_b128 v[182:185], v138 offset:3072
	s_addc_u32 s9, s83, 0
	s_and_b64 s[60:61], s[62:63], exec
	s_cselect_b32 s84, s54, s8
	s_cselect_b32 s85, s19, s9
	s_cselect_b32 s63, s17, s57
	s_cselect_b32 s62, s55, s56
	s_add_u32 s66, s84, 0x80
	s_addc_u32 s67, s85, 0
	s_add_u32 s76, s62, 0x80
	s_addc_u32 s77, s63, 0
	ds_read_b128 v[186:189], v152
	ds_read_b128 v[190:193], v152 offset:1024
	ds_read_b128 v[194:197], v152 offset:2048
	ds_read_b128 v[198:201], v152 offset:3072
	ds_read_b128 v[202:205], v152 offset:4096
	ds_read_b128 v[206:209], v152 offset:5120
	ds_read_b128 v[210:213], v152 offset:6144
	ds_read_b128 v[214:217], v152 offset:7168
	s_add_u32 s60, s82, 0x100080
	s_addc_u32 s61, s83, 0
	s_mov_b32 m0, s97
	s_nop 0
	global_load_lds_dwordx4 v141, s[60:61]
	s_nop 0
	s_mov_b32 m0, s70
	s_nop 0
	global_load_lds_dwordx4 v143, s[60:61]
	s_waitcnt vmcnt(8)
	s_waitcnt lgkmcnt(0)
	s_barrier
	s_setprio 1
	s_waitcnt lgkmcnt(7)
	v_mfma_f32_16x16x32_bf16 v[126:129], v[154:157], v[186:189], v[126:129]
	v_mfma_f32_16x16x32_bf16 v[126:129], v[158:161], v[190:193], v[126:129]
	s_waitcnt lgkmcnt(5)
	v_mfma_f32_16x16x32_bf16 v[122:125], v[166:169], v[190:193], v[122:125]
	v_mfma_f32_16x16x32_bf16 v[122:125], v[162:165], v[186:189], v[122:125]
	s_waitcnt lgkmcnt(3)
	v_mfma_f32_16x16x32_bf16 v[118:121], v[170:173], v[186:189], v[118:121]
	v_mfma_f32_16x16x32_bf16 v[118:121], v[174:177], v[190:193], v[118:121]
	s_waitcnt lgkmcnt(1)
	v_mfma_f32_16x16x32_bf16 v[114:117], v[182:185], v[190:193], v[114:117]
	v_mfma_f32_16x16x32_bf16 v[114:117], v[178:181], v[186:189], v[114:117]
	v_mfma_f32_16x16x32_bf16 v[98:101], v[178:181], v[194:197], v[98:101]
	v_mfma_f32_16x16x32_bf16 v[98:101], v[182:185], v[198:201], v[98:101]
	v_mfma_f32_16x16x32_bf16 v[102:105], v[174:177], v[198:201], v[102:105]
	v_mfma_f32_16x16x32_bf16 v[102:105], v[170:173], v[194:197], v[102:105]
	v_mfma_f32_16x16x32_bf16 v[106:109], v[162:165], v[194:197], v[106:109]
	v_mfma_f32_16x16x32_bf16 v[106:109], v[166:169], v[198:201], v[106:109]
	s_waitcnt lgkmcnt(0)
	v_mfma_f32_16x16x32_bf16 v[110:113], v[158:161], v[198:201], v[110:113]
	v_mfma_f32_16x16x32_bf16 v[110:113], v[154:157], v[194:197], v[110:113]
	s_setprio 0
	s_setprio 1
	v_mfma_f32_16x16x32_bf16 v[94:97], v[154:157], v[202:205], v[94:97]
	v_mfma_f32_16x16x32_bf16 v[94:97], v[158:161], v[206:209], v[94:97]
	v_mfma_f32_16x16x32_bf16 v[90:93], v[166:169], v[206:209], v[90:93]
	v_mfma_f32_16x16x32_bf16 v[90:93], v[162:165], v[202:205], v[90:93]
	v_mfma_f32_16x16x32_bf16 v[86:89], v[170:173], v[202:205], v[86:89]
	v_mfma_f32_16x16x32_bf16 v[86:89], v[174:177], v[206:209], v[86:89]
	v_mfma_f32_16x16x32_bf16 v[82:85], v[182:185], v[206:209], v[82:85]
	v_mfma_f32_16x16x32_bf16 v[82:85], v[178:181], v[202:205], v[82:85]
	v_mfma_f32_16x16x32_bf16 v[66:69], v[178:181], v[210:213], v[66:69]
	v_mfma_f32_16x16x32_bf16 v[66:69], v[182:185], v[214:217], v[66:69]
	v_mfma_f32_16x16x32_bf16 v[70:73], v[174:177], v[214:217], v[70:73]
	v_mfma_f32_16x16x32_bf16 v[70:73], v[170:173], v[210:213], v[70:73]
	v_mfma_f32_16x16x32_bf16 v[74:77], v[162:165], v[210:213], v[74:77]
	v_mfma_f32_16x16x32_bf16 v[74:77], v[166:169], v[214:217], v[74:77]
	v_mfma_f32_16x16x32_bf16 v[78:81], v[158:161], v[214:217], v[78:81]
	s_setprio 2
	s_barrier
	v_mfma_f32_16x16x32_bf16 v[78:81], v[154:157], v[210:213], v[78:81]
	s_setprio 0
	ds_read_b128 v[186:189], v152 offset:16384
	ds_read_b128 v[190:193], v152 offset:17408
	ds_read_b128 v[194:197], v152 offset:18432
	ds_read_b128 v[198:201], v152 offset:19456
	ds_read_b128 v[202:205], v152 offset:20480
	ds_read_b128 v[206:209], v152 offset:21504
	ds_read_b128 v[252:255], v152 offset:22528
	ds_read_b128 v[214:217], v152 offset:23552
	s_mov_b32 m0, s68
	s_nop 0
	global_load_lds_dwordx4 v142, s[62:63]
	s_add_u32 s60, s62, 0x100000
	s_mov_b32 m0, s69
	s_nop 0
	global_load_lds_dwordx4 v144, s[62:63]
	s_addc_u32 s61, s63, 0
	s_mov_b32 m0, s81
	s_nop 0
	global_load_lds_dwordx4 v142, s[60:61]
	s_nop 0
	s_mov_b32 m0, s86
	s_nop 0
	global_load_lds_dwordx4 v144, s[60:61]
	s_nop 0
	s_mov_b32 m0, s65
	s_nop 0
	global_load_lds_dwordx4 v141, s[84:85]
	s_nop 0
	s_mov_b32 m0, s87
	s_nop 0
	global_load_lds_dwordx4 v143, s[84:85]
	s_waitcnt vmcnt(8)
	s_waitcnt lgkmcnt(0)
	s_barrier
; #define PG8_STAGE(bufoff, gbase, voff) do { _Pragma("unroll") for (int _i = 0; _i < 2; ++_i) \
;         asm volatile("s_mov_b32 m0, %2\n\ts_nop 0\n\tglobal_load_lds_dwordx4 %0, %1" :: "v"((voff)[_i]), "s"((const char*)(gbase)), "s"(ldsbase + (unsigned)(bufoff) + ldsw + (unsigned)_i * 8192u) : "memory", "m0"); } while (0)
; #define PG8_LDA(dst, b, h) do { _Pragma("unroll") for (int m = 0; m < 4; ++m) _Pragma("unroll") for (int k = 0; k < 2; ++k) dst[m][k] = *(const PG8_LAS bf16x8*)(lds + PG8_SA(b, h) + aoff + m * 2048 + k * 1024); } while (0)
; #define PG8_LDB(dst, b, h) do { _Pragma("unroll") for (int n = 0; n < 2; ++n) _Pragma("unroll") for (int k = 0; k < 2; ++k) dst[n][k] = *(const PG8_LAS bf16x8*)(lds + PG8_SB(b, h) + boff + n * 2048 + k * 1024); } while (0)
; #define PG8_MMA(ai, bj, At, Bt) do { __builtin_amdgcn_s_setprio(1); _Pragma("unroll") for (int m = 0; m < 4; ++m) _Pragma("unroll") for (int n = 0; n < 2; ++n) _Pragma("unroll") for (int k = 0; k < 2; ++k) \
;         acc[ai][bj][m][n] = __builtin_amdgcn_mfma_f32_16x16x32_bf16(Bt[n][k], At[m][k], acc[ai][bj][m][n], 0, 0, 0); __builtin_amdgcn_s_setprio(0); } while (0)
; #define PG8_WAIT_V(n) asm volatile("s_waitcnt vmcnt(" #n ")" ::: "memory")
; #define PG8_WAIT_L(n) asm volatile("s_waitcnt lgkmcnt(" #n ")" ::: "memory")
; #define PG8_BAR __builtin_amdgcn_s_barrier()
; #define PG8_SCHED __builtin_amdgcn_sched_barrier(0)
; template <class Epi, class Sched, bool ALIGN_EPI = false, bool SP2 = false>
; __device__ __forceinline__ void gemm_phase(PG8_LAS unsigned char* lds, const Gemm g, const Sched& S, const Epi& E) {
;     ...
;             PG8_WAIT_V(8); PG8_WAIT_L(0); PG8_BAR; PG8_MMA(1, 0, At, B0); PG8_MMA(1, 1, At, B1); PG8_BAR; PG8_SCHED;
;             PG8_LDB(B0, 1, 0); PG8_LDB(B1, 1, 1); PG8_SCHED; PG8_LDA(At, 1, 0); PG8_STAGE(PG8_SA(0, 1), a2 + hstep, voffA);
;             PG8_WAIT_V(8); PG8_WAIT_L(0); PG8_BAR; PG8_MMA(0, 0, At, B0); PG8_MMA(0, 1, At, B1); PG8_BAR; PG8_SCHED;
	s_setprio 1
	s_waitcnt lgkmcnt(7)
	v_mfma_f32_16x16x32_bf16 v[62:65], v[154:157], v[186:189], v[62:65]
	v_mfma_f32_16x16x32_bf16 v[62:65], v[158:161], v[190:193], v[62:65]
	s_waitcnt lgkmcnt(5)
	v_mfma_f32_16x16x32_bf16 v[58:61], v[166:169], v[190:193], v[58:61]
	v_mfma_f32_16x16x32_bf16 v[58:61], v[162:165], v[186:189], v[58:61]
	s_waitcnt lgkmcnt(3)
	v_mfma_f32_16x16x32_bf16 v[54:57], v[170:173], v[186:189], v[54:57]
	v_mfma_f32_16x16x32_bf16 v[54:57], v[174:177], v[190:193], v[54:57]
	s_waitcnt lgkmcnt(1)
	v_mfma_f32_16x16x32_bf16 v[50:53], v[182:185], v[190:193], v[50:53]
	v_mfma_f32_16x16x32_bf16 v[50:53], v[178:181], v[186:189], v[50:53]
	v_mfma_f32_16x16x32_bf16 v[34:37], v[178:181], v[194:197], v[34:37]
	v_mfma_f32_16x16x32_bf16 v[34:37], v[182:185], v[198:201], v[34:37]
	v_mfma_f32_16x16x32_bf16 v[38:41], v[174:177], v[198:201], v[38:41]
	v_mfma_f32_16x16x32_bf16 v[38:41], v[170:173], v[194:197], v[38:41]
	v_mfma_f32_16x16x32_bf16 v[42:45], v[162:165], v[194:197], v[42:45]
	v_mfma_f32_16x16x32_bf16 v[42:45], v[166:169], v[198:201], v[42:45]
	s_waitcnt lgkmcnt(0)
	v_mfma_f32_16x16x32_bf16 v[46:49], v[158:161], v[198:201], v[46:49]
	v_mfma_f32_16x16x32_bf16 v[46:49], v[154:157], v[194:197], v[46:49]
	s_setprio 0
	s_setprio 1
	v_mfma_f32_16x16x32_bf16 v[30:33], v[154:157], v[202:205], v[30:33]
	v_mfma_f32_16x16x32_bf16 v[30:33], v[158:161], v[206:209], v[30:33]
	v_mfma_f32_16x16x32_bf16 v[26:29], v[166:169], v[206:209], v[26:29]
	v_mfma_f32_16x16x32_bf16 v[26:29], v[162:165], v[202:205], v[26:29]
	v_mfma_f32_16x16x32_bf16 v[22:25], v[170:173], v[202:205], v[22:25]
	v_mfma_f32_16x16x32_bf16 v[22:25], v[174:177], v[206:209], v[22:25]
	v_mfma_f32_16x16x32_bf16 v[18:21], v[182:185], v[206:209], v[18:21]
	v_mfma_f32_16x16x32_bf16 v[18:21], v[178:181], v[202:205], v[18:21]
	v_mfma_f32_16x16x32_bf16 v[2:5], v[178:181], v[252:255], v[2:5]
	v_mfma_f32_16x16x32_bf16 v[2:5], v[182:185], v[214:217], v[2:5]
	v_mfma_f32_16x16x32_bf16 v[6:9], v[174:177], v[214:217], v[6:9]
	v_mfma_f32_16x16x32_bf16 v[6:9], v[170:173], v[252:255], v[6:9]
	v_mfma_f32_16x16x32_bf16 v[10:13], v[162:165], v[252:255], v[10:13]
	v_mfma_f32_16x16x32_bf16 v[10:13], v[166:169], v[214:217], v[10:13]
	v_mfma_f32_16x16x32_bf16 v[14:17], v[158:161], v[214:217], v[14:17]
	s_setprio 2
	s_barrier
	v_mfma_f32_16x16x32_bf16 v[14:17], v[154:157], v[252:255], v[14:17]
	s_setprio 0
	v_add_u32_e32 v138, 0x18000, v151
	ds_read_b128 v[248:251], v138
	ds_read_b128 v[158:161], v138 offset:1024
	ds_read_b128 v[162:165], v138 offset:2048
	ds_read_b128 v[166:169], v138 offset:3072
	v_add_u32_e32 v138, 0x1c000, v151
	ds_read_b128 v[170:173], v138
	ds_read_b128 v[174:177], v138 offset:1024
	ds_read_b128 v[178:181], v138 offset:2048
	ds_read_b128 v[182:185], v138 offset:3072
	ds_read_b128 v[186:189], v152 offset:32768
	ds_read_b128 v[190:193], v152 offset:33792
	ds_read_b128 v[194:197], v152 offset:34816
	ds_read_b128 v[198:201], v152 offset:35840
	ds_read_b128 v[202:205], v152 offset:36864
	ds_read_b128 v[206:209], v152 offset:37888
	ds_read_b128 v[210:213], v152 offset:38912
	ds_read_b128 v[214:217], v152 offset:39936
	s_add_u32 s60, s84, 0x100000
	s_addc_u32 s61, s85, 0
	s_mov_b32 m0, s88
	s_nop 0
	global_load_lds_dwordx4 v141, s[60:61]
	s_nop 0
	s_mov_b32 m0, s89
	s_nop 0
	global_load_lds_dwordx4 v143, s[60:61]
	s_waitcnt vmcnt(8)
	s_waitcnt lgkmcnt(0)
	s_barrier
	s_setprio 1
	s_waitcnt lgkmcnt(7)
	v_mfma_f32_16x16x32_bf16 v[126:129], v[248:251], v[186:189], v[126:129]
	v_mfma_f32_16x16x32_bf16 v[126:129], v[158:161], v[190:193], v[126:129]
	s_waitcnt lgkmcnt(5)
	v_mfma_f32_16x16x32_bf16 v[122:125], v[166:169], v[190:193], v[122:125]
	v_mfma_f32_16x16x32_bf16 v[122:125], v[162:165], v[186:189], v[122:125]
	s_waitcnt lgkmcnt(3)
	v_mfma_f32_16x16x32_bf16 v[118:121], v[170:173], v[186:189], v[118:121]
	v_mfma_f32_16x16x32_bf16 v[118:121], v[174:177], v[190:193], v[118:121]
	s_waitcnt lgkmcnt(1)
	v_mfma_f32_16x16x32_bf16 v[114:117], v[182:185], v[190:193], v[114:117]
	v_mfma_f32_16x16x32_bf16 v[114:117], v[178:181], v[186:189], v[114:117]
	v_mfma_f32_16x16x32_bf16 v[98:101], v[178:181], v[194:197], v[98:101]
	v_mfma_f32_16x16x32_bf16 v[98:101], v[182:185], v[198:201], v[98:101]
	v_mfma_f32_16x16x32_bf16 v[102:105], v[174:177], v[198:201], v[102:105]
	v_mfma_f32_16x16x32_bf16 v[102:105], v[170:173], v[194:197], v[102:105]
	v_mfma_f32_16x16x32_bf16 v[106:109], v[162:165], v[194:197], v[106:109]
	v_mfma_f32_16x16x32_bf16 v[106:109], v[166:169], v[198:201], v[106:109]
	s_waitcnt lgkmcnt(0)
	v_mfma_f32_16x16x32_bf16 v[110:113], v[158:161], v[198:201], v[110:113]
	v_mfma_f32_16x16x32_bf16 v[110:113], v[248:251], v[194:197], v[110:113]
	s_setprio 0
	s_setprio 1
	v_mfma_f32_16x16x32_bf16 v[94:97], v[248:251], v[202:205], v[94:97]
	v_mfma_f32_16x16x32_bf16 v[94:97], v[158:161], v[206:209], v[94:97]
	v_mfma_f32_16x16x32_bf16 v[90:93], v[166:169], v[206:209], v[90:93]
	v_mfma_f32_16x16x32_bf16 v[90:93], v[162:165], v[202:205], v[90:93]
	v_mfma_f32_16x16x32_bf16 v[86:89], v[170:173], v[202:205], v[86:89]
	v_mfma_f32_16x16x32_bf16 v[86:89], v[174:177], v[206:209], v[86:89]
	v_mfma_f32_16x16x32_bf16 v[82:85], v[182:185], v[206:209], v[82:85]
	v_mfma_f32_16x16x32_bf16 v[82:85], v[178:181], v[202:205], v[82:85]
	v_mfma_f32_16x16x32_bf16 v[66:69], v[178:181], v[210:213], v[66:69]
	v_mfma_f32_16x16x32_bf16 v[66:69], v[182:185], v[214:217], v[66:69]
	v_mfma_f32_16x16x32_bf16 v[70:73], v[174:177], v[214:217], v[70:73]
	v_mfma_f32_16x16x32_bf16 v[70:73], v[170:173], v[210:213], v[70:73]
	v_mfma_f32_16x16x32_bf16 v[74:77], v[162:165], v[210:213], v[74:77]
	v_mfma_f32_16x16x32_bf16 v[74:77], v[166:169], v[214:217], v[74:77]
	v_mfma_f32_16x16x32_bf16 v[78:81], v[158:161], v[214:217], v[78:81]
	s_setprio 2
	s_barrier
; #define PG8_STAGE(bufoff, gbase, voff) do { _Pragma("unroll") for (int _i = 0; _i < 2; ++_i) \
;         asm volatile("s_mov_b32 m0, %2\n\ts_nop 0\n\tglobal_load_lds_dwordx4 %0, %1" :: "v"((voff)[_i]), "s"((const char*)(gbase)), "s"(ldsbase + (unsigned)(bufoff) + ldsw + (unsigned)_i * 8192u) : "memory", "m0"); } while (0)
; #define PG8_LDA(dst, b, h) do { _Pragma("unroll") for (int m = 0; m < 4; ++m) _Pragma("unroll") for (int k = 0; k < 2; ++k) dst[m][k] = *(const PG8_LAS bf16x8*)(lds + PG8_SA(b, h) + aoff + m * 2048 + k * 1024); } while (0)
; #define PG8_MMA(ai, bj, At, Bt) do { __builtin_amdgcn_s_setprio(1); _Pragma("unroll") for (int m = 0; m < 4; ++m) _Pragma("unroll") for (int n = 0; n < 2; ++n) _Pragma("unroll") for (int k = 0; k < 2; ++k) \
;         acc[ai][bj][m][n] = __builtin_amdgcn_mfma_f32_16x16x32_bf16(Bt[n][k], At[m][k], acc[ai][bj][m][n], 0, 0, 0); __builtin_amdgcn_s_setprio(0); } while (0)
; #define PG8_WAIT_V(n) asm volatile("s_waitcnt vmcnt(" #n ")" ::: "memory")
; #define PG8_WAIT_L(n) asm volatile("s_waitcnt lgkmcnt(" #n ")" ::: "memory")
; #define PG8_BAR __builtin_amdgcn_s_barrier()
; #define PG8_SCHED __builtin_amdgcn_sched_barrier(0)
; template <class Epi, class Sched, bool ALIGN_EPI = false, bool SP2 = false>
; __device__ __forceinline__ void gemm_phase(PG8_LAS unsigned char* lds, const Gemm g, const Sched& S, const Epi& E) {
;     ...
;             PG8_WAIT_V(8); PG8_WAIT_L(0); PG8_BAR; PG8_MMA(0, 0, At, B0); PG8_MMA(0, 1, At, B1); PG8_BAR; PG8_SCHED;
;             PG8_LDA(At, 1, 1); PG8_STAGE(PG8_SB(1, 0), b3, voffB); PG8_STAGE(PG8_SB(1, 1), b3 + hstep, voffB); PG8_STAGE(PG8_SA(1, 0), a3, voffA);
;             PG8_WAIT_V(8); PG8_WAIT_L(0); PG8_BAR; PG8_MMA(1, 0, At, B0); PG8_MMA(1, 1, At, B1); PG8_BAR; PG8_SCHED;
	v_mfma_f32_16x16x32_bf16 v[78:81], v[248:251], v[210:213], v[78:81]
	s_setprio 0
	ds_read_b128 v[186:189], v152 offset:49152
	ds_read_b128 v[190:193], v152 offset:50176
	ds_read_b128 v[194:197], v152 offset:51200
	ds_read_b128 v[198:201], v152 offset:52224
	ds_read_b128 v[202:205], v152 offset:53248
	ds_read_b128 v[206:209], v152 offset:54272
	ds_read_b128 v[252:255], v152 offset:55296
	ds_read_b128 v[214:217], v152 offset:56320
	s_mov_b32 m0, s90
	s_nop 0
	global_load_lds_dwordx4 v142, s[76:77]
	s_add_u32 s60, s62, 0x100080
	s_mov_b32 m0, s91
	s_nop 0
	global_load_lds_dwordx4 v144, s[76:77]
	s_addc_u32 s61, s63, 0
	s_mov_b32 m0, s95
	s_nop 0
	global_load_lds_dwordx4 v142, s[60:61]
	s_nop 0
	s_mov_b32 m0, s96
	s_nop 0
	global_load_lds_dwordx4 v144, s[60:61]
	s_nop 0
	s_mov_b32 m0, s92
	s_nop 0
	global_load_lds_dwordx4 v141, s[66:67]
	s_nop 0
	s_mov_b32 m0, s94
	s_nop 0
	global_load_lds_dwordx4 v143, s[66:67]
	s_waitcnt vmcnt(8)
	s_waitcnt lgkmcnt(0)
	s_barrier
	s_setprio 1
	s_waitcnt lgkmcnt(7)
	v_mfma_f32_16x16x32_bf16 v[62:65], v[248:251], v[186:189], v[62:65]
	v_mfma_f32_16x16x32_bf16 v[62:65], v[158:161], v[190:193], v[62:65]
	s_waitcnt lgkmcnt(5)
	v_mfma_f32_16x16x32_bf16 v[58:61], v[166:169], v[190:193], v[58:61]
	v_mfma_f32_16x16x32_bf16 v[58:61], v[162:165], v[186:189], v[58:61]
	s_waitcnt lgkmcnt(3)
	v_mfma_f32_16x16x32_bf16 v[54:57], v[170:173], v[186:189], v[54:57]
	v_mfma_f32_16x16x32_bf16 v[54:57], v[174:177], v[190:193], v[54:57]
	s_waitcnt lgkmcnt(1)
	v_mfma_f32_16x16x32_bf16 v[50:53], v[182:185], v[190:193], v[50:53]
	v_mfma_f32_16x16x32_bf16 v[50:53], v[178:181], v[186:189], v[50:53]
	v_mfma_f32_16x16x32_bf16 v[34:37], v[178:181], v[194:197], v[34:37]
	v_mfma_f32_16x16x32_bf16 v[34:37], v[182:185], v[198:201], v[34:37]
	v_mfma_f32_16x16x32_bf16 v[38:41], v[174:177], v[198:201], v[38:41]
	v_mfma_f32_16x16x32_bf16 v[38:41], v[170:173], v[194:197], v[38:41]
	v_mfma_f32_16x16x32_bf16 v[42:45], v[162:165], v[194:197], v[42:45]
	v_mfma_f32_16x16x32_bf16 v[42:45], v[166:169], v[198:201], v[42:45]
	s_waitcnt lgkmcnt(0)
	v_mfma_f32_16x16x32_bf16 v[46:49], v[158:161], v[198:201], v[46:49]
	v_mfma_f32_16x16x32_bf16 v[46:49], v[248:251], v[194:197], v[46:49]
	s_setprio 0
	s_setprio 1
	v_mfma_f32_16x16x32_bf16 v[30:33], v[248:251], v[202:205], v[30:33]
	v_mfma_f32_16x16x32_bf16 v[30:33], v[158:161], v[206:209], v[30:33]
	v_mfma_f32_16x16x32_bf16 v[26:29], v[166:169], v[206:209], v[26:29]
	v_mfma_f32_16x16x32_bf16 v[26:29], v[162:165], v[202:205], v[26:29]
	v_mfma_f32_16x16x32_bf16 v[22:25], v[170:173], v[202:205], v[22:25]
	v_mfma_f32_16x16x32_bf16 v[22:25], v[174:177], v[206:209], v[22:25]
	v_mfma_f32_16x16x32_bf16 v[18:21], v[182:185], v[206:209], v[18:21]
	v_mfma_f32_16x16x32_bf16 v[18:21], v[178:181], v[202:205], v[18:21]
	v_mfma_f32_16x16x32_bf16 v[2:5], v[178:181], v[252:255], v[2:5]
	v_mfma_f32_16x16x32_bf16 v[2:5], v[182:185], v[214:217], v[2:5]
	v_mfma_f32_16x16x32_bf16 v[6:9], v[174:177], v[214:217], v[6:9]
	v_mfma_f32_16x16x32_bf16 v[6:9], v[170:173], v[252:255], v[6:9]
	v_mfma_f32_16x16x32_bf16 v[10:13], v[162:165], v[252:255], v[10:13]
	v_mfma_f32_16x16x32_bf16 v[10:13], v[166:169], v[214:217], v[10:13]
	v_mfma_f32_16x16x32_bf16 v[14:17], v[158:161], v[214:217], v[14:17]
	s_setprio 2
	s_barrier
	v_mfma_f32_16x16x32_bf16 v[14:17], v[248:251], v[252:255], v[14:17]
	s_setprio 0
	s_add_i32 s58, s58, 2
	s_add_u32 s56, s56, 0x100
	s_addc_u32 s57, s57, 0
	s_cmp_gt_u32 s58, 61
	s_cbranch_scc1 .LBB0_316
	s_mov_b64 s[82:83], s[8:9]
	s_branch .LBB0_320

; #define PG8_STAGE(bufoff, gbase, voff) do { _Pragma("unroll") for (int _i = 0; _i < 2; ++_i) \
;         asm volatile("s_mov_b32 m0, %2\n\ts_nop 0\n\tglobal_load_lds_dwordx4 %0, %1" :: "v"((voff)[_i]), "s"((const char*)(gbase)), "s"(ldsbase + (unsigned)(bufoff) + ldsw + (unsigned)_i * 8192u) : "memory", "m0"); } while (0)
; #define PG8_LDA(dst, b, h) do { _Pragma("unroll") for (int m = 0; m < 4; ++m) _Pragma("unroll") for (int k = 0; k < 2; ++k) dst[m][k] = *(const PG8_LAS bf16x8*)(lds + PG8_SA(b, h) + aoff + m * 2048 + k * 1024); } while (0)
; #define PG8_LDB(dst, b, h) do { _Pragma("unroll") for (int n = 0; n < 2; ++n) _Pragma("unroll") for (int k = 0; k < 2; ++k) dst[n][k] = *(const PG8_LAS bf16x8*)(lds + PG8_SB(b, h) + boff + n * 2048 + k * 1024); } while (0)
; #define PG8_MMA(ai, bj, At, Bt) do { __builtin_amdgcn_s_setprio(1); _Pragma("unroll") for (int m = 0; m < 4; ++m) _Pragma("unroll") for (int n = 0; n < 2; ++n) _Pragma("unroll") for (int k = 0; k < 2; ++k) \
;         acc[ai][bj][m][n] = __builtin_amdgcn_mfma_f32_16x16x32_bf16(Bt[n][k], At[m][k], acc[ai][bj][m][n], 0, 0, 0); __builtin_amdgcn_s_setprio(0); } while (0)
; template <class Epi, class Sched, bool ALIGN_EPI = false, bool SP2 = false>
; __device__ __forceinline__ void gemm_phase(PG8_LAS unsigned char* lds, const Gemm g, const Sched& S, const Epi& E) {
;     ...
;             const bool last = (t == nt - 2);
;             const char* a1 = cA + (size_t)(t + 1) * kstep;
;             const char* a2 = last ? nA : cA + (size_t)(t + 2) * kstep; const char* b2 = last ? nB : cB + (size_t)(t + 2) * kstep;
;             const char* a3 = a2 + kstep; const char* b3 = b2 + kstep;
;             if (last && has_next) S.a_ready(nxt);
;             if constexpr (epi_has_mid<Epi>::value) { if (t == Epi::MID_T) E.mid(acc, cur, wr, wc, fr, fq); }
;             if constexpr (SP2) {
;             PG8_LDB(B0, 0, 0); PG8_LDB(B1, 0, 1); PG8_SCHED; PG8_LDA(At, 0, 0); PG8_STAGE(PG8_SA(1, 1), a1 + hstep, voffA);
;             PG8_WAIT_V(8); PG8_WAIT_L(0); PG8_BAR; PG8_MMA(0, 0, At, B0); PG8_MMA(0, 1, At, B1); PG8_BAR; PG8_SCHED;
;             PG8_LDA(At, 0, 1); PG8_STAGE(PG8_SB(0, 0), b2, voffB); PG8_STAGE(PG8_SB(0, 1), b2 + hstep, voffB); PG8_STAGE(PG8_SA(0, 0), a2, voffA);
;             PG8_WAIT_V(8); PG8_WAIT_L(0); PG8_BAR; PG8_MMA(1, 0, At, B0); PG8_MMA(1, 1, At, B1); PG8_BAR; PG8_SCHED;
.LBB0_698:
	ds_read_b128 v[134:137], v145
	ds_read_b128 v[152:155], v145 offset:1024
	ds_read_b128 v[156:159], v145 offset:2048
	ds_read_b128 v[160:163], v145 offset:3072
	ds_read_b128 v[164:167], v146
	ds_read_b128 v[168:171], v146 offset:1024
	ds_read_b128 v[172:175], v146 offset:2048
	ds_read_b128 v[176:179], v146 offset:3072
	s_cmp_eq_u32 s69, 60
	s_cselect_b32 s48, s41, s53
	s_cselect_b32 s49, s19, s58
	s_cselect_b32 s46, s52, s59
	s_cselect_b32 s47, s17, s68
	s_add_u32 s44, s48, 0x80
	s_addc_u32 s45, s49, 0
	ds_read_b128 v[180:183], v147
	ds_read_b128 v[184:187], v147 offset:1024
	ds_read_b128 v[188:191], v147 offset:2048
	ds_read_b128 v[192:195], v147 offset:3072
	ds_read_b128 v[196:199], v147 offset:4096
	ds_read_b128 v[200:203], v147 offset:5120
	ds_read_b128 v[204:207], v147 offset:6144
	ds_read_b128 v[208:211], v147 offset:7168
	s_mov_b32 m0, s67
	s_nop 0
	global_load_lds_dwordx4 v1, s[42:43]
	s_nop 0
	s_mov_b32 m0, s74
	s_nop 0
	global_load_lds_dwordx4 v141, s[42:43]
	s_waitcnt vmcnt(8)
	s_waitcnt lgkmcnt(0)
	s_barrier
	s_setprio 1
	s_waitcnt lgkmcnt(7)
	v_mfma_f32_16x16x32_bf16 v[126:129], v[134:137], v[180:183], v[126:129]
	v_mfma_f32_16x16x32_bf16 v[126:129], v[152:155], v[184:187], v[126:129]
	s_waitcnt lgkmcnt(5)
	v_mfma_f32_16x16x32_bf16 v[122:125], v[160:163], v[184:187], v[122:125]
	v_mfma_f32_16x16x32_bf16 v[122:125], v[156:159], v[180:183], v[122:125]
	s_waitcnt lgkmcnt(3)
	v_mfma_f32_16x16x32_bf16 v[118:121], v[164:167], v[180:183], v[118:121]
	v_mfma_f32_16x16x32_bf16 v[118:121], v[168:171], v[184:187], v[118:121]
	s_waitcnt lgkmcnt(1)
	v_mfma_f32_16x16x32_bf16 v[114:117], v[176:179], v[184:187], v[114:117]
	v_mfma_f32_16x16x32_bf16 v[114:117], v[172:175], v[180:183], v[114:117]
	v_mfma_f32_16x16x32_bf16 v[98:101], v[172:175], v[188:191], v[98:101]
	v_mfma_f32_16x16x32_bf16 v[98:101], v[176:179], v[192:195], v[98:101]
	v_mfma_f32_16x16x32_bf16 v[102:105], v[168:171], v[192:195], v[102:105]
	v_mfma_f32_16x16x32_bf16 v[102:105], v[164:167], v[188:191], v[102:105]
	v_mfma_f32_16x16x32_bf16 v[106:109], v[156:159], v[188:191], v[106:109]
	v_mfma_f32_16x16x32_bf16 v[106:109], v[160:163], v[192:195], v[106:109]
	s_waitcnt lgkmcnt(0)
	v_mfma_f32_16x16x32_bf16 v[110:113], v[152:155], v[192:195], v[110:113]
	v_mfma_f32_16x16x32_bf16 v[110:113], v[134:137], v[188:191], v[110:113]
	s_setprio 0
	s_setprio 1
	v_mfma_f32_16x16x32_bf16 v[94:97], v[134:137], v[196:199], v[94:97]
	v_mfma_f32_16x16x32_bf16 v[94:97], v[152:155], v[200:203], v[94:97]
	v_mfma_f32_16x16x32_bf16 v[90:93], v[160:163], v[200:203], v[90:93]
	v_mfma_f32_16x16x32_bf16 v[90:93], v[156:159], v[196:199], v[90:93]
	v_mfma_f32_16x16x32_bf16 v[86:89], v[164:167], v[196:199], v[86:89]
	v_mfma_f32_16x16x32_bf16 v[86:89], v[168:171], v[200:203], v[86:89]
	v_mfma_f32_16x16x32_bf16 v[82:85], v[176:179], v[200:203], v[82:85]
	v_mfma_f32_16x16x32_bf16 v[82:85], v[172:175], v[196:199], v[82:85]
	v_mfma_f32_16x16x32_bf16 v[66:69], v[172:175], v[204:207], v[66:69]
	v_mfma_f32_16x16x32_bf16 v[66:69], v[176:179], v[208:211], v[66:69]
	v_mfma_f32_16x16x32_bf16 v[70:73], v[168:171], v[208:211], v[70:73]
	v_mfma_f32_16x16x32_bf16 v[70:73], v[164:167], v[204:207], v[70:73]
	v_mfma_f32_16x16x32_bf16 v[74:77], v[156:159], v[204:207], v[74:77]
	v_mfma_f32_16x16x32_bf16 v[74:77], v[160:163], v[208:211], v[74:77]
	v_mfma_f32_16x16x32_bf16 v[78:81], v[152:155], v[208:211], v[78:81]
	s_setprio 2
	s_barrier
	v_mfma_f32_16x16x32_bf16 v[78:81], v[134:137], v[204:207], v[78:81]
	s_setprio 0
	ds_read_b128 v[180:183], v147 offset:16384
	ds_read_b128 v[184:187], v147 offset:17408
	ds_read_b128 v[188:191], v147 offset:18432
	ds_read_b128 v[192:195], v147 offset:19456
	ds_read_b128 v[196:199], v147 offset:20480
	ds_read_b128 v[200:203], v147 offset:21504
	ds_read_b128 v[252:255], v147 offset:22528
	ds_read_b128 v[208:211], v147 offset:23552
	s_mov_b32 m0, s35
	s_nop 0
	global_load_lds_dwordx4 v140, s[46:47]
	s_add_u32 s70, s46, 0x100000
	s_mov_b32 m0, s50
	s_nop 0
	global_load_lds_dwordx4 v142, s[46:47]
	s_addc_u32 s71, s47, 0
	s_mov_b32 m0, s51
	s_nop 0
	global_load_lds_dwordx4 v140, s[70:71]
	s_nop 0
	s_mov_b32 m0, s54
	s_nop 0
	global_load_lds_dwordx4 v142, s[70:71]
	s_nop 0
	s_mov_b32 m0, s3
	s_nop 0
	global_load_lds_dwordx4 v1, s[48:49]
	s_nop 0
	s_mov_b32 m0, s55
	s_nop 0
	global_load_lds_dwordx4 v141, s[48:49]
	s_waitcnt vmcnt(8)
	s_waitcnt lgkmcnt(0)
	s_barrier
	s_setprio 1
	s_waitcnt lgkmcnt(7)
	v_mfma_f32_16x16x32_bf16 v[62:65], v[134:137], v[180:183], v[62:65]
	v_mfma_f32_16x16x32_bf16 v[62:65], v[152:155], v[184:187], v[62:65]
	s_waitcnt lgkmcnt(5)
	v_mfma_f32_16x16x32_bf16 v[58:61], v[160:163], v[184:187], v[58:61]
	v_mfma_f32_16x16x32_bf16 v[58:61], v[156:159], v[180:183], v[58:61]
	s_waitcnt lgkmcnt(3)
	v_mfma_f32_16x16x32_bf16 v[54:57], v[164:167], v[180:183], v[54:57]
	v_mfma_f32_16x16x32_bf16 v[54:57], v[168:171], v[184:187], v[54:57]
	s_waitcnt lgkmcnt(1)
	v_mfma_f32_16x16x32_bf16 v[50:53], v[176:179], v[184:187], v[50:53]
	v_mfma_f32_16x16x32_bf16 v[50:53], v[172:175], v[180:183], v[50:53]
	v_mfma_f32_16x16x32_bf16 v[34:37], v[172:175], v[188:191], v[34:37]
	v_mfma_f32_16x16x32_bf16 v[34:37], v[176:179], v[192:195], v[34:37]
	v_mfma_f32_16x16x32_bf16 v[38:41], v[168:171], v[192:195], v[38:41]
	v_mfma_f32_16x16x32_bf16 v[38:41], v[164:167], v[188:191], v[38:41]
	v_mfma_f32_16x16x32_bf16 v[42:45], v[156:159], v[188:191], v[42:45]
	v_mfma_f32_16x16x32_bf16 v[42:45], v[160:163], v[192:195], v[42:45]
	s_waitcnt lgkmcnt(0)
	v_mfma_f32_16x16x32_bf16 v[46:49], v[152:155], v[192:195], v[46:49]
	v_mfma_f32_16x16x32_bf16 v[46:49], v[134:137], v[188:191], v[46:49]
	s_setprio 0
	s_setprio 1
	v_mfma_f32_16x16x32_bf16 v[30:33], v[134:137], v[196:199], v[30:33]
	v_mfma_f32_16x16x32_bf16 v[30:33], v[152:155], v[200:203], v[30:33]
	v_mfma_f32_16x16x32_bf16 v[26:29], v[160:163], v[200:203], v[26:29]
	v_mfma_f32_16x16x32_bf16 v[26:29], v[156:159], v[196:199], v[26:29]
	v_mfma_f32_16x16x32_bf16 v[22:25], v[164:167], v[196:199], v[22:25]
	v_mfma_f32_16x16x32_bf16 v[22:25], v[168:171], v[200:203], v[22:25]
	v_mfma_f32_16x16x32_bf16 v[18:21], v[176:179], v[200:203], v[18:21]
	v_mfma_f32_16x16x32_bf16 v[18:21], v[172:175], v[196:199], v[18:21]
	v_mfma_f32_16x16x32_bf16 v[2:5], v[172:175], v[252:255], v[2:5]
	v_mfma_f32_16x16x32_bf16 v[2:5], v[176:179], v[208:211], v[2:5]
	v_mfma_f32_16x16x32_bf16 v[6:9], v[168:171], v[208:211], v[6:9]
	v_mfma_f32_16x16x32_bf16 v[6:9], v[164:167], v[252:255], v[6:9]
	v_mfma_f32_16x16x32_bf16 v[10:13], v[156:159], v[252:255], v[10:13]
	v_mfma_f32_16x16x32_bf16 v[10:13], v[160:163], v[208:211], v[10:13]
	v_mfma_f32_16x16x32_bf16 v[14:17], v[152:155], v[208:211], v[14:17]
	s_setprio 2
	s_barrier
; #define PG8_STAGE(bufoff, gbase, voff) do { _Pragma("unroll") for (int _i = 0; _i < 2; ++_i) \
;         asm volatile("s_mov_b32 m0, %2\n\ts_nop 0\n\tglobal_load_lds_dwordx4 %0, %1" :: "v"((voff)[_i]), "s"((const char*)(gbase)), "s"(ldsbase + (unsigned)(bufoff) + ldsw + (unsigned)_i * 8192u) : "memory", "m0"); } while (0)
; #define PG8_LDA(dst, b, h) do { _Pragma("unroll") for (int m = 0; m < 4; ++m) _Pragma("unroll") for (int k = 0; k < 2; ++k) dst[m][k] = *(const PG8_LAS bf16x8*)(lds + PG8_SA(b, h) + aoff + m * 2048 + k * 1024); } while (0)
; #define PG8_LDB(dst, b, h) do { _Pragma("unroll") for (int n = 0; n < 2; ++n) _Pragma("unroll") for (int k = 0; k < 2; ++k) dst[n][k] = *(const PG8_LAS bf16x8*)(lds + PG8_SB(b, h) + boff + n * 2048 + k * 1024); } while (0)
; #define PG8_MMA(ai, bj, At, Bt) do { __builtin_amdgcn_s_setprio(1); _Pragma("unroll") for (int m = 0; m < 4; ++m) _Pragma("unroll") for (int n = 0; n < 2; ++n) _Pragma("unroll") for (int k = 0; k < 2; ++k) \
;         acc[ai][bj][m][n] = __builtin_amdgcn_mfma_f32_16x16x32_bf16(Bt[n][k], At[m][k], acc[ai][bj][m][n], 0, 0, 0); __builtin_amdgcn_s_setprio(0); } while (0)
; #define PG8_WAIT_V(n) asm volatile("s_waitcnt vmcnt(" #n ")" ::: "memory")
; #define PG8_WAIT_L(n) asm volatile("s_waitcnt lgkmcnt(" #n ")" ::: "memory")
; #define PG8_BAR __builtin_amdgcn_s_barrier()
; #define PG8_SCHED __builtin_amdgcn_sched_barrier(0)
; template <class Epi, class Sched, bool ALIGN_EPI = false, bool SP2 = false>
; __device__ __forceinline__ void gemm_phase(PG8_LAS unsigned char* lds, const Gemm g, const Sched& S, const Epi& E) {
;     ...
;             PG8_WAIT_V(8); PG8_WAIT_L(0); PG8_BAR; PG8_MMA(1, 0, At, B0); PG8_MMA(1, 1, At, B1); PG8_BAR; PG8_SCHED;
;             PG8_LDB(B0, 1, 0); PG8_LDB(B1, 1, 1); PG8_SCHED; PG8_LDA(At, 1, 0); PG8_STAGE(PG8_SA(0, 1), a2 + hstep, voffA);
;             PG8_WAIT_V(8); PG8_WAIT_L(0); PG8_BAR; PG8_MMA(0, 0, At, B0); PG8_MMA(0, 1, At, B1); PG8_BAR; PG8_SCHED;
	v_mfma_f32_16x16x32_bf16 v[14:17], v[134:137], v[252:255], v[14:17]
	s_setprio 0
	ds_read_b128 v[248:251], v148
	ds_read_b128 v[152:155], v148 offset:1024
	ds_read_b128 v[156:159], v148 offset:2048
	ds_read_b128 v[160:163], v148 offset:3072
	ds_read_b128 v[164:167], v149
	ds_read_b128 v[168:171], v149 offset:1024
	ds_read_b128 v[172:175], v149 offset:2048
	ds_read_b128 v[176:179], v149 offset:3072
	ds_read_b128 v[180:183], v147 offset:32768
	ds_read_b128 v[184:187], v147 offset:33792
	ds_read_b128 v[188:191], v147 offset:34816
	ds_read_b128 v[192:195], v147 offset:35840
	ds_read_b128 v[196:199], v147 offset:36864
	ds_read_b128 v[200:203], v147 offset:37888
	ds_read_b128 v[204:207], v147 offset:38912
	ds_read_b128 v[208:211], v147 offset:39936
	s_add_u32 s48, s48, 0x100000
	s_addc_u32 s49, s49, 0
	s_mov_b32 m0, s56
	s_nop 0
	global_load_lds_dwordx4 v1, s[48:49]
	s_nop 0
	s_mov_b32 m0, s57
	s_nop 0
	global_load_lds_dwordx4 v141, s[48:49]
	s_waitcnt vmcnt(8)
	s_waitcnt lgkmcnt(0)
	s_barrier
	s_setprio 1
	s_waitcnt lgkmcnt(7)
	v_mfma_f32_16x16x32_bf16 v[126:129], v[248:251], v[180:183], v[126:129]
	v_mfma_f32_16x16x32_bf16 v[126:129], v[152:155], v[184:187], v[126:129]
	s_waitcnt lgkmcnt(5)
	v_mfma_f32_16x16x32_bf16 v[122:125], v[160:163], v[184:187], v[122:125]
	v_mfma_f32_16x16x32_bf16 v[122:125], v[156:159], v[180:183], v[122:125]
	s_waitcnt lgkmcnt(3)
	v_mfma_f32_16x16x32_bf16 v[118:121], v[164:167], v[180:183], v[118:121]
	v_mfma_f32_16x16x32_bf16 v[118:121], v[168:171], v[184:187], v[118:121]
	s_waitcnt lgkmcnt(1)
	v_mfma_f32_16x16x32_bf16 v[114:117], v[176:179], v[184:187], v[114:117]
	v_mfma_f32_16x16x32_bf16 v[114:117], v[172:175], v[180:183], v[114:117]
	v_mfma_f32_16x16x32_bf16 v[98:101], v[172:175], v[188:191], v[98:101]
	v_mfma_f32_16x16x32_bf16 v[98:101], v[176:179], v[192:195], v[98:101]
	v_mfma_f32_16x16x32_bf16 v[102:105], v[168:171], v[192:195], v[102:105]
	v_mfma_f32_16x16x32_bf16 v[102:105], v[164:167], v[188:191], v[102:105]
	v_mfma_f32_16x16x32_bf16 v[106:109], v[156:159], v[188:191], v[106:109]
	v_mfma_f32_16x16x32_bf16 v[106:109], v[160:163], v[192:195], v[106:109]
	s_waitcnt lgkmcnt(0)
	v_mfma_f32_16x16x32_bf16 v[110:113], v[152:155], v[192:195], v[110:113]
	v_mfma_f32_16x16x32_bf16 v[110:113], v[248:251], v[188:191], v[110:113]
	s_setprio 0
	s_setprio 1
	v_mfma_f32_16x16x32_bf16 v[94:97], v[248:251], v[196:199], v[94:97]
	v_mfma_f32_16x16x32_bf16 v[94:97], v[152:155], v[200:203], v[94:97]
	v_mfma_f32_16x16x32_bf16 v[90:93], v[160:163], v[200:203], v[90:93]
	v_mfma_f32_16x16x32_bf16 v[90:93], v[156:159], v[196:199], v[90:93]
	v_mfma_f32_16x16x32_bf16 v[86:89], v[164:167], v[196:199], v[86:89]
	v_mfma_f32_16x16x32_bf16 v[86:89], v[168:171], v[200:203], v[86:89]
	v_mfma_f32_16x16x32_bf16 v[82:85], v[176:179], v[200:203], v[82:85]
	v_mfma_f32_16x16x32_bf16 v[82:85], v[172:175], v[196:199], v[82:85]
	v_mfma_f32_16x16x32_bf16 v[66:69], v[172:175], v[204:207], v[66:69]
	v_mfma_f32_16x16x32_bf16 v[66:69], v[176:179], v[208:211], v[66:69]
	v_mfma_f32_16x16x32_bf16 v[70:73], v[168:171], v[208:211], v[70:73]
	v_mfma_f32_16x16x32_bf16 v[70:73], v[164:167], v[204:207], v[70:73]
	v_mfma_f32_16x16x32_bf16 v[74:77], v[156:159], v[204:207], v[74:77]
	v_mfma_f32_16x16x32_bf16 v[74:77], v[160:163], v[208:211], v[74:77]
	v_mfma_f32_16x16x32_bf16 v[78:81], v[152:155], v[208:211], v[78:81]
	s_setprio 2
	s_barrier
; #define PG8_STAGE(bufoff, gbase, voff) do { _Pragma("unroll") for (int _i = 0; _i < 2; ++_i) \
;         asm volatile("s_mov_b32 m0, %2\n\ts_nop 0\n\tglobal_load_lds_dwordx4 %0, %1" :: "v"((voff)[_i]), "s"((const char*)(gbase)), "s"(ldsbase + (unsigned)(bufoff) + ldsw + (unsigned)_i * 8192u) : "memory", "m0"); } while (0)
; #define PG8_LDA(dst, b, h) do { _Pragma("unroll") for (int m = 0; m < 4; ++m) _Pragma("unroll") for (int k = 0; k < 2; ++k) dst[m][k] = *(const PG8_LAS bf16x8*)(lds + PG8_SA(b, h) + aoff + m * 2048 + k * 1024); } while (0)
; #define PG8_MMA(ai, bj, At, Bt) do { __builtin_amdgcn_s_setprio(1); _Pragma("unroll") for (int m = 0; m < 4; ++m) _Pragma("unroll") for (int n = 0; n < 2; ++n) _Pragma("unroll") for (int k = 0; k < 2; ++k) \
;         acc[ai][bj][m][n] = __builtin_amdgcn_mfma_f32_16x16x32_bf16(Bt[n][k], At[m][k], acc[ai][bj][m][n], 0, 0, 0); __builtin_amdgcn_s_setprio(0); } while (0)
; #define PG8_WAIT_V(n) asm volatile("s_waitcnt vmcnt(" #n ")" ::: "memory")
; #define PG8_WAIT_L(n) asm volatile("s_waitcnt lgkmcnt(" #n ")" ::: "memory")
; #define PG8_BAR __builtin_amdgcn_s_barrier()
; #define PG8_SCHED __builtin_amdgcn_sched_barrier(0)
; template <class Epi, class Sched, bool ALIGN_EPI = false, bool SP2 = false>
; __device__ __forceinline__ void gemm_phase(PG8_LAS unsigned char* lds, const Gemm g, const Sched& S, const Epi& E) {
;     ...
;             PG8_WAIT_V(8); PG8_WAIT_L(0); PG8_BAR; PG8_MMA(0, 0, At, B0); PG8_MMA(0, 1, At, B1); PG8_BAR; PG8_SCHED;
;             PG8_LDA(At, 1, 1); PG8_STAGE(PG8_SB(1, 0), b3, voffB); PG8_STAGE(PG8_SB(1, 1), b3 + hstep, voffB); PG8_STAGE(PG8_SA(1, 0), a3, voffA);
;             PG8_WAIT_V(8); PG8_WAIT_L(0); PG8_BAR; PG8_MMA(1, 0, At, B0); PG8_MMA(1, 1, At, B1); PG8_BAR; PG8_SCHED;
;     ...
;         if constexpr (ALIGN_EPI) { if (wr == 0) PG8_BAR; }
	v_mfma_f32_16x16x32_bf16 v[78:81], v[248:251], v[204:207], v[78:81]
	s_setprio 0
	ds_read_b128 v[180:183], v147 offset:49152
	ds_read_b128 v[184:187], v147 offset:50176
	ds_read_b128 v[188:191], v147 offset:51200
	ds_read_b128 v[192:195], v147 offset:52224
	ds_read_b128 v[196:199], v147 offset:53248
	ds_read_b128 v[200:203], v147 offset:54272
	ds_read_b128 v[252:255], v147 offset:55296
	ds_read_b128 v[208:211], v147 offset:56320
	s_add_u32 s48, s46, 0x80
	s_addc_u32 s49, s47, 0
	s_mov_b32 m0, s61
	s_nop 0
	global_load_lds_dwordx4 v140, s[48:49]
	s_add_u32 s46, s46, 0x100080
	s_mov_b32 m0, s62
	s_nop 0
	global_load_lds_dwordx4 v142, s[48:49]
	s_addc_u32 s47, s47, 0
	s_mov_b32 m0, s65
	s_nop 0
	global_load_lds_dwordx4 v140, s[46:47]
	s_nop 0
	s_mov_b32 m0, s66
	s_nop 0
	global_load_lds_dwordx4 v142, s[46:47]
	s_nop 0
	s_mov_b32 m0, s63
	s_nop 0
	global_load_lds_dwordx4 v1, s[44:45]
	s_nop 0
	s_mov_b32 m0, s64
	s_nop 0
	global_load_lds_dwordx4 v141, s[44:45]
	s_waitcnt vmcnt(8)
	s_waitcnt lgkmcnt(0)
	s_barrier
	s_setprio 1
	s_waitcnt lgkmcnt(7)
	v_mfma_f32_16x16x32_bf16 v[62:65], v[248:251], v[180:183], v[62:65]
	v_mfma_f32_16x16x32_bf16 v[62:65], v[152:155], v[184:187], v[62:65]
	s_waitcnt lgkmcnt(5)
	v_mfma_f32_16x16x32_bf16 v[58:61], v[160:163], v[184:187], v[58:61]
	v_mfma_f32_16x16x32_bf16 v[58:61], v[156:159], v[180:183], v[58:61]
	s_waitcnt lgkmcnt(3)
	v_mfma_f32_16x16x32_bf16 v[54:57], v[164:167], v[180:183], v[54:57]
	v_mfma_f32_16x16x32_bf16 v[54:57], v[168:171], v[184:187], v[54:57]
	s_waitcnt lgkmcnt(1)
	v_mfma_f32_16x16x32_bf16 v[50:53], v[176:179], v[184:187], v[50:53]
	v_mfma_f32_16x16x32_bf16 v[50:53], v[172:175], v[180:183], v[50:53]
	v_mfma_f32_16x16x32_bf16 v[34:37], v[172:175], v[188:191], v[34:37]
	v_mfma_f32_16x16x32_bf16 v[34:37], v[176:179], v[192:195], v[34:37]
	v_mfma_f32_16x16x32_bf16 v[38:41], v[168:171], v[192:195], v[38:41]
	v_mfma_f32_16x16x32_bf16 v[38:41], v[164:167], v[188:191], v[38:41]
	v_mfma_f32_16x16x32_bf16 v[42:45], v[156:159], v[188:191], v[42:45]
	v_mfma_f32_16x16x32_bf16 v[42:45], v[160:163], v[192:195], v[42:45]
	s_waitcnt lgkmcnt(0)
	v_mfma_f32_16x16x32_bf16 v[46:49], v[152:155], v[192:195], v[46:49]
	v_mfma_f32_16x16x32_bf16 v[46:49], v[248:251], v[188:191], v[46:49]
	s_setprio 0
	s_setprio 1
	v_mfma_f32_16x16x32_bf16 v[30:33], v[248:251], v[196:199], v[30:33]
	v_mfma_f32_16x16x32_bf16 v[30:33], v[152:155], v[200:203], v[30:33]
	v_mfma_f32_16x16x32_bf16 v[26:29], v[160:163], v[200:203], v[26:29]
	v_mfma_f32_16x16x32_bf16 v[26:29], v[156:159], v[196:199], v[26:29]
	v_mfma_f32_16x16x32_bf16 v[22:25], v[164:167], v[196:199], v[22:25]
	v_mfma_f32_16x16x32_bf16 v[22:25], v[168:171], v[200:203], v[22:25]
	v_mfma_f32_16x16x32_bf16 v[18:21], v[176:179], v[200:203], v[18:21]
	v_mfma_f32_16x16x32_bf16 v[18:21], v[172:175], v[196:199], v[18:21]
	v_mfma_f32_16x16x32_bf16 v[2:5], v[172:175], v[252:255], v[2:5]
	v_mfma_f32_16x16x32_bf16 v[2:5], v[176:179], v[208:211], v[2:5]
	v_mfma_f32_16x16x32_bf16 v[6:9], v[168:171], v[208:211], v[6:9]
	v_mfma_f32_16x16x32_bf16 v[6:9], v[164:167], v[252:255], v[6:9]
	v_mfma_f32_16x16x32_bf16 v[10:13], v[156:159], v[252:255], v[10:13]
	v_mfma_f32_16x16x32_bf16 v[10:13], v[160:163], v[208:211], v[10:13]
	v_mfma_f32_16x16x32_bf16 v[14:17], v[152:155], v[208:211], v[14:17]
	s_setprio 2
	s_barrier
	v_mfma_f32_16x16x32_bf16 v[14:17], v[248:251], v[252:255], v[14:17]
	s_setprio 0
	s_add_i32 s69, s69, 2
	s_add_u32 s53, s53, 0x100
	s_addc_u32 s58, s58, 0
	s_add_u32 s59, s59, 0x100
	s_addc_u32 s68, s68, 0
	s_add_u32 s42, s42, 0x100
	s_addc_u32 s43, s43, 0
	s_cmp_gt_u32 s69, 61
	s_cbranch_scc0 .LBB0_698
	s_and_b64 vcc, exec, s[14:15]
	s_cbranch_vccz .LBB0_701
	s_barrier

; #define PG8_STAGE(bufoff, gbase, voff) do { _Pragma("unroll") for (int _i = 0; _i < 2; ++_i) \
;         asm volatile("s_mov_b32 m0, %2\n\ts_nop 0\n\tglobal_load_lds_dwordx4 %0, %1" :: "v"((voff)[_i]), "s"((const char*)(gbase)), "s"(ldsbase + (unsigned)(bufoff) + ldsw + (unsigned)_i * 8192u) : "memory", "m0"); } while (0)
; #define PG8_LDA(dst, b, h) do { _Pragma("unroll") for (int m = 0; m < 4; ++m) _Pragma("unroll") for (int k = 0; k < 2; ++k) dst[m][k] = *(const PG8_LAS bf16x8*)(lds + PG8_SA(b, h) + aoff + m * 2048 + k * 1024); } while (0)
; #define PG8_LDB(dst, b, h) do { _Pragma("unroll") for (int n = 0; n < 2; ++n) _Pragma("unroll") for (int k = 0; k < 2; ++k) dst[n][k] = *(const PG8_LAS bf16x8*)(lds + PG8_SB(b, h) + boff + n * 2048 + k * 1024); } while (0)
; #define PG8_MMA(ai, bj, At, Bt) do { __builtin_amdgcn_s_setprio(1); _Pragma("unroll") for (int m = 0; m < 4; ++m) _Pragma("unroll") for (int n = 0; n < 2; ++n) _Pragma("unroll") for (int k = 0; k < 2; ++k) \
;         acc[ai][bj][m][n] = __builtin_amdgcn_mfma_f32_16x16x32_bf16(Bt[n][k], At[m][k], acc[ai][bj][m][n], 0, 0, 0); __builtin_amdgcn_s_setprio(0); } while (0)
; template <class Epi, class Sched, bool ALIGN_EPI = false, bool SP2 = false>
; __device__ __forceinline__ void gemm_phase(PG8_LAS unsigned char* lds, const Gemm g, const Sched& S, const Epi& E) {
;     ...
;             const bool last = (t == nt - 2);
;             const char* a1 = cA + (size_t)(t + 1) * kstep;
;             const char* a2 = last ? nA : cA + (size_t)(t + 2) * kstep; const char* b2 = last ? nB : cB + (size_t)(t + 2) * kstep;
;             const char* a3 = a2 + kstep; const char* b3 = b2 + kstep;
;             if (last && has_next) S.a_ready(nxt);
;             if constexpr (epi_has_mid<Epi>::value) { if (t == Epi::MID_T) E.mid(acc, cur, wr, wc, fr, fq); }
;             if constexpr (SP2) {
;             PG8_LDB(B0, 0, 0); PG8_LDB(B1, 0, 1); PG8_SCHED; PG8_LDA(At, 0, 0); PG8_STAGE(PG8_SA(1, 1), a1 + hstep, voffA);
;             PG8_WAIT_V(8); PG8_WAIT_L(0); PG8_BAR; PG8_MMA(0, 0, At, B0); PG8_MMA(0, 1, At, B1); PG8_BAR; PG8_SCHED;
;             PG8_LDA(At, 0, 1); PG8_STAGE(PG8_SB(0, 0), b2, voffB); PG8_STAGE(PG8_SB(0, 1), b2 + hstep, voffB); PG8_STAGE(PG8_SA(0, 0), a2, voffA);
;             PG8_WAIT_V(8); PG8_WAIT_L(0); PG8_BAR; PG8_MMA(1, 0, At, B0); PG8_MMA(1, 1, At, B1); PG8_BAR; PG8_SCHED;
.LBB0_789:
	v_add_u32_e32 v164, 0x10000, v149
	v_add_u32_e32 v180, 0x14000, v149
	s_add_u32 s8, s40, 0x100
	s_waitcnt lgkmcnt(0)
	ds_read_b128 v[152:155], v164
	ds_read_b128 v[156:159], v164 offset:1024
	ds_read_b128 v[160:163], v164 offset:2048
	ds_read_b128 v[164:167], v164 offset:3072
	ds_read_b128 v[168:171], v180
	ds_read_b128 v[172:175], v180 offset:1024
	ds_read_b128 v[176:179], v180 offset:2048
	ds_read_b128 v[180:183], v180 offset:3072
	s_addc_u32 s9, s41, 0
	s_and_b64 s[38:39], s[38:39], exec
	s_cselect_b32 s46, s59, s8
	s_cselect_b32 s47, s17, s9
	s_cselect_b32 s39, s15, s75
	s_cselect_b32 s38, s71, s74
	s_add_u32 s42, s46, 0x80
	s_addc_u32 s43, s47, 0
	s_add_u32 s44, s38, 0x80
	s_addc_u32 s45, s39, 0
	ds_read_b128 v[184:187], v150
	ds_read_b128 v[188:191], v150 offset:1024
	ds_read_b128 v[192:195], v150 offset:2048
	ds_read_b128 v[196:199], v150 offset:3072
	ds_read_b128 v[200:203], v150 offset:4096
	ds_read_b128 v[204:207], v150 offset:5120
	ds_read_b128 v[208:211], v150 offset:6144
	ds_read_b128 v[212:215], v150 offset:7168
	s_add_u32 s40, s40, 0x100080
	s_addc_u32 s41, s41, 0
	s_mov_b32 m0, s64
	s_nop 0
	global_load_lds_dwordx4 v139, s[40:41]
	s_nop 0
	s_mov_b32 m0, s65
	s_nop 0
	global_load_lds_dwordx4 v141, s[40:41]
	s_waitcnt vmcnt(8)
	s_waitcnt lgkmcnt(0)
	s_barrier
	s_setprio 1
	s_waitcnt lgkmcnt(7)
	v_mfma_f32_16x16x32_bf16 v[126:129], v[152:155], v[184:187], v[126:129]
	v_mfma_f32_16x16x32_bf16 v[126:129], v[156:159], v[188:191], v[126:129]
	s_waitcnt lgkmcnt(5)
	v_mfma_f32_16x16x32_bf16 v[122:125], v[164:167], v[188:191], v[122:125]
	v_mfma_f32_16x16x32_bf16 v[122:125], v[160:163], v[184:187], v[122:125]
	s_waitcnt lgkmcnt(3)
	v_mfma_f32_16x16x32_bf16 v[118:121], v[168:171], v[184:187], v[118:121]
	v_mfma_f32_16x16x32_bf16 v[118:121], v[172:175], v[188:191], v[118:121]
	s_waitcnt lgkmcnt(1)
	v_mfma_f32_16x16x32_bf16 v[114:117], v[180:183], v[188:191], v[114:117]
	v_mfma_f32_16x16x32_bf16 v[114:117], v[176:179], v[184:187], v[114:117]
	v_mfma_f32_16x16x32_bf16 v[98:101], v[176:179], v[192:195], v[98:101]
	v_mfma_f32_16x16x32_bf16 v[98:101], v[180:183], v[196:199], v[98:101]
	v_mfma_f32_16x16x32_bf16 v[102:105], v[172:175], v[196:199], v[102:105]
	v_mfma_f32_16x16x32_bf16 v[102:105], v[168:171], v[192:195], v[102:105]
	v_mfma_f32_16x16x32_bf16 v[106:109], v[160:163], v[192:195], v[106:109]
	v_mfma_f32_16x16x32_bf16 v[106:109], v[164:167], v[196:199], v[106:109]
	s_waitcnt lgkmcnt(0)
	v_mfma_f32_16x16x32_bf16 v[110:113], v[156:159], v[196:199], v[110:113]
	v_mfma_f32_16x16x32_bf16 v[110:113], v[152:155], v[192:195], v[110:113]
	s_setprio 0
	s_setprio 1
	v_mfma_f32_16x16x32_bf16 v[94:97], v[152:155], v[200:203], v[94:97]
	v_mfma_f32_16x16x32_bf16 v[94:97], v[156:159], v[204:207], v[94:97]
	v_mfma_f32_16x16x32_bf16 v[90:93], v[164:167], v[204:207], v[90:93]
	v_mfma_f32_16x16x32_bf16 v[90:93], v[160:163], v[200:203], v[90:93]
	v_mfma_f32_16x16x32_bf16 v[86:89], v[168:171], v[200:203], v[86:89]
	v_mfma_f32_16x16x32_bf16 v[86:89], v[172:175], v[204:207], v[86:89]
	v_mfma_f32_16x16x32_bf16 v[82:85], v[180:183], v[204:207], v[82:85]
	v_mfma_f32_16x16x32_bf16 v[82:85], v[176:179], v[200:203], v[82:85]
	v_mfma_f32_16x16x32_bf16 v[66:69], v[176:179], v[208:211], v[66:69]
	v_mfma_f32_16x16x32_bf16 v[66:69], v[180:183], v[212:215], v[66:69]
	v_mfma_f32_16x16x32_bf16 v[70:73], v[172:175], v[212:215], v[70:73]
	v_mfma_f32_16x16x32_bf16 v[70:73], v[168:171], v[208:211], v[70:73]
	v_mfma_f32_16x16x32_bf16 v[74:77], v[160:163], v[208:211], v[74:77]
	v_mfma_f32_16x16x32_bf16 v[74:77], v[164:167], v[212:215], v[74:77]
	v_mfma_f32_16x16x32_bf16 v[78:81], v[156:159], v[212:215], v[78:81]
	s_setprio 2
	s_barrier
	v_mfma_f32_16x16x32_bf16 v[78:81], v[152:155], v[208:211], v[78:81]
	s_setprio 0
	ds_read_b128 v[184:187], v150 offset:16384
	ds_read_b128 v[188:191], v150 offset:17408
	ds_read_b128 v[192:195], v150 offset:18432
	ds_read_b128 v[196:199], v150 offset:19456
	ds_read_b128 v[200:203], v150 offset:20480
	ds_read_b128 v[204:207], v150 offset:21504
	ds_read_b128 v[252:255], v150 offset:22528
	ds_read_b128 v[212:215], v150 offset:23552
	s_mov_b32 m0, s49
	s_nop 0
	global_load_lds_dwordx4 v140, s[38:39]
	s_add_u32 s40, s38, 0x100000
	s_mov_b32 m0, s50
	s_nop 0
	global_load_lds_dwordx4 v142, s[38:39]
	s_addc_u32 s41, s39, 0
	s_mov_b32 m0, s51
	s_nop 0
	global_load_lds_dwordx4 v140, s[40:41]
	s_nop 0
	s_mov_b32 m0, s52
	s_nop 0
	global_load_lds_dwordx4 v142, s[40:41]
	s_nop 0
	s_mov_b32 m0, s37
	s_nop 0
	global_load_lds_dwordx4 v139, s[46:47]
	s_nop 0
	s_mov_b32 m0, s53
	s_nop 0
	global_load_lds_dwordx4 v141, s[46:47]
	s_waitcnt vmcnt(8)
	s_waitcnt lgkmcnt(0)
	s_barrier
; #define PG8_STAGE(bufoff, gbase, voff) do { _Pragma("unroll") for (int _i = 0; _i < 2; ++_i) \
;         asm volatile("s_mov_b32 m0, %2\n\ts_nop 0\n\tglobal_load_lds_dwordx4 %0, %1" :: "v"((voff)[_i]), "s"((const char*)(gbase)), "s"(ldsbase + (unsigned)(bufoff) + ldsw + (unsigned)_i * 8192u) : "memory", "m0"); } while (0)
; #define PG8_LDA(dst, b, h) do { _Pragma("unroll") for (int m = 0; m < 4; ++m) _Pragma("unroll") for (int k = 0; k < 2; ++k) dst[m][k] = *(const PG8_LAS bf16x8*)(lds + PG8_SA(b, h) + aoff + m * 2048 + k * 1024); } while (0)
; #define PG8_LDB(dst, b, h) do { _Pragma("unroll") for (int n = 0; n < 2; ++n) _Pragma("unroll") for (int k = 0; k < 2; ++k) dst[n][k] = *(const PG8_LAS bf16x8*)(lds + PG8_SB(b, h) + boff + n * 2048 + k * 1024); } while (0)
; #define PG8_MMA(ai, bj, At, Bt) do { __builtin_amdgcn_s_setprio(1); _Pragma("unroll") for (int m = 0; m < 4; ++m) _Pragma("unroll") for (int n = 0; n < 2; ++n) _Pragma("unroll") for (int k = 0; k < 2; ++k) \
;         acc[ai][bj][m][n] = __builtin_amdgcn_mfma_f32_16x16x32_bf16(Bt[n][k], At[m][k], acc[ai][bj][m][n], 0, 0, 0); __builtin_amdgcn_s_setprio(0); } while (0)
; #define PG8_WAIT_V(n) asm volatile("s_waitcnt vmcnt(" #n ")" ::: "memory")
; #define PG8_WAIT_L(n) asm volatile("s_waitcnt lgkmcnt(" #n ")" ::: "memory")
; #define PG8_BAR __builtin_amdgcn_s_barrier()
; #define PG8_SCHED __builtin_amdgcn_sched_barrier(0)
; template <class Epi, class Sched, bool ALIGN_EPI = false, bool SP2 = false>
; __device__ __forceinline__ void gemm_phase(PG8_LAS unsigned char* lds, const Gemm g, const Sched& S, const Epi& E) {
;     ...
;             PG8_WAIT_V(8); PG8_WAIT_L(0); PG8_BAR; PG8_MMA(1, 0, At, B0); PG8_MMA(1, 1, At, B1); PG8_BAR; PG8_SCHED;
;             PG8_LDB(B0, 1, 0); PG8_LDB(B1, 1, 1); PG8_SCHED; PG8_LDA(At, 1, 0); PG8_STAGE(PG8_SA(0, 1), a2 + hstep, voffA);
;             PG8_WAIT_V(8); PG8_WAIT_L(0); PG8_BAR; PG8_MMA(0, 0, At, B0); PG8_MMA(0, 1, At, B1); PG8_BAR; PG8_SCHED;
	s_setprio 1
	s_waitcnt lgkmcnt(7)
	v_mfma_f32_16x16x32_bf16 v[62:65], v[152:155], v[184:187], v[62:65]
	v_mfma_f32_16x16x32_bf16 v[62:65], v[156:159], v[188:191], v[62:65]
	s_waitcnt lgkmcnt(5)
	v_mfma_f32_16x16x32_bf16 v[58:61], v[164:167], v[188:191], v[58:61]
	v_mfma_f32_16x16x32_bf16 v[58:61], v[160:163], v[184:187], v[58:61]
	s_waitcnt lgkmcnt(3)
	v_mfma_f32_16x16x32_bf16 v[54:57], v[168:171], v[184:187], v[54:57]
	v_mfma_f32_16x16x32_bf16 v[54:57], v[172:175], v[188:191], v[54:57]
	s_waitcnt lgkmcnt(1)
	v_mfma_f32_16x16x32_bf16 v[50:53], v[180:183], v[188:191], v[50:53]
	v_mfma_f32_16x16x32_bf16 v[50:53], v[176:179], v[184:187], v[50:53]
	v_mfma_f32_16x16x32_bf16 v[34:37], v[176:179], v[192:195], v[34:37]
	v_mfma_f32_16x16x32_bf16 v[34:37], v[180:183], v[196:199], v[34:37]
	v_mfma_f32_16x16x32_bf16 v[38:41], v[172:175], v[196:199], v[38:41]
	v_mfma_f32_16x16x32_bf16 v[38:41], v[168:171], v[192:195], v[38:41]
	v_mfma_f32_16x16x32_bf16 v[42:45], v[160:163], v[192:195], v[42:45]
	v_mfma_f32_16x16x32_bf16 v[42:45], v[164:167], v[196:199], v[42:45]
	s_waitcnt lgkmcnt(0)
	v_mfma_f32_16x16x32_bf16 v[46:49], v[156:159], v[196:199], v[46:49]
	v_mfma_f32_16x16x32_bf16 v[46:49], v[152:155], v[192:195], v[46:49]
	s_setprio 0
	s_setprio 1
	v_mfma_f32_16x16x32_bf16 v[30:33], v[152:155], v[200:203], v[30:33]
	v_mfma_f32_16x16x32_bf16 v[30:33], v[156:159], v[204:207], v[30:33]
	v_mfma_f32_16x16x32_bf16 v[26:29], v[164:167], v[204:207], v[26:29]
	v_mfma_f32_16x16x32_bf16 v[26:29], v[160:163], v[200:203], v[26:29]
	v_mfma_f32_16x16x32_bf16 v[22:25], v[168:171], v[200:203], v[22:25]
	v_mfma_f32_16x16x32_bf16 v[22:25], v[172:175], v[204:207], v[22:25]
	v_mfma_f32_16x16x32_bf16 v[18:21], v[180:183], v[204:207], v[18:21]
	v_mfma_f32_16x16x32_bf16 v[18:21], v[176:179], v[200:203], v[18:21]
	v_mfma_f32_16x16x32_bf16 v[2:5], v[176:179], v[252:255], v[2:5]
	v_mfma_f32_16x16x32_bf16 v[2:5], v[180:183], v[212:215], v[2:5]
	v_mfma_f32_16x16x32_bf16 v[6:9], v[172:175], v[212:215], v[6:9]
	v_mfma_f32_16x16x32_bf16 v[6:9], v[168:171], v[252:255], v[6:9]
	v_mfma_f32_16x16x32_bf16 v[10:13], v[160:163], v[252:255], v[10:13]
	v_mfma_f32_16x16x32_bf16 v[10:13], v[164:167], v[212:215], v[10:13]
	v_mfma_f32_16x16x32_bf16 v[14:17], v[156:159], v[212:215], v[14:17]
	s_setprio 2
	s_barrier
	v_mfma_f32_16x16x32_bf16 v[14:17], v[152:155], v[252:255], v[14:17]
	s_setprio 0
	v_add_u32_e32 v164, 0x18000, v149
	v_add_u32_e32 v180, 0x1c000, v149
	ds_read_b128 v[248:251], v164
	ds_read_b128 v[156:159], v164 offset:1024
	ds_read_b128 v[160:163], v164 offset:2048
	ds_read_b128 v[164:167], v164 offset:3072
	ds_read_b128 v[168:171], v180
	ds_read_b128 v[172:175], v180 offset:1024
	ds_read_b128 v[176:179], v180 offset:2048
	ds_read_b128 v[180:183], v180 offset:3072
	ds_read_b128 v[184:187], v150 offset:32768
	ds_read_b128 v[188:191], v150 offset:33792
	ds_read_b128 v[192:195], v150 offset:34816
	ds_read_b128 v[196:199], v150 offset:35840
	ds_read_b128 v[200:203], v150 offset:36864
	ds_read_b128 v[204:207], v150 offset:37888
	ds_read_b128 v[208:211], v150 offset:38912
	ds_read_b128 v[212:215], v150 offset:39936
	s_add_u32 s40, s46, 0x100000
	s_addc_u32 s41, s47, 0
	s_mov_b32 m0, s54
	s_nop 0
	global_load_lds_dwordx4 v139, s[40:41]
	s_nop 0
	s_mov_b32 m0, s55
	s_nop 0
	global_load_lds_dwordx4 v141, s[40:41]
	s_waitcnt vmcnt(8)
	s_waitcnt lgkmcnt(0)
	s_barrier
	s_setprio 1
	s_waitcnt lgkmcnt(7)
	v_mfma_f32_16x16x32_bf16 v[126:129], v[248:251], v[184:187], v[126:129]
	v_mfma_f32_16x16x32_bf16 v[126:129], v[156:159], v[188:191], v[126:129]
	s_waitcnt lgkmcnt(5)
	v_mfma_f32_16x16x32_bf16 v[122:125], v[164:167], v[188:191], v[122:125]
	v_mfma_f32_16x16x32_bf16 v[122:125], v[160:163], v[184:187], v[122:125]
	s_waitcnt lgkmcnt(3)
	v_mfma_f32_16x16x32_bf16 v[118:121], v[168:171], v[184:187], v[118:121]
	v_mfma_f32_16x16x32_bf16 v[118:121], v[172:175], v[188:191], v[118:121]
	s_waitcnt lgkmcnt(1)
	v_mfma_f32_16x16x32_bf16 v[114:117], v[180:183], v[188:191], v[114:117]
	v_mfma_f32_16x16x32_bf16 v[114:117], v[176:179], v[184:187], v[114:117]
	v_mfma_f32_16x16x32_bf16 v[98:101], v[176:179], v[192:195], v[98:101]
	v_mfma_f32_16x16x32_bf16 v[98:101], v[180:183], v[196:199], v[98:101]
	v_mfma_f32_16x16x32_bf16 v[102:105], v[172:175], v[196:199], v[102:105]
	v_mfma_f32_16x16x32_bf16 v[102:105], v[168:171], v[192:195], v[102:105]
	v_mfma_f32_16x16x32_bf16 v[106:109], v[160:163], v[192:195], v[106:109]
	v_mfma_f32_16x16x32_bf16 v[106:109], v[164:167], v[196:199], v[106:109]
	s_waitcnt lgkmcnt(0)
	v_mfma_f32_16x16x32_bf16 v[110:113], v[156:159], v[196:199], v[110:113]
	v_mfma_f32_16x16x32_bf16 v[110:113], v[248:251], v[192:195], v[110:113]
	s_setprio 0
	s_setprio 1
	v_mfma_f32_16x16x32_bf16 v[94:97], v[248:251], v[200:203], v[94:97]
	v_mfma_f32_16x16x32_bf16 v[94:97], v[156:159], v[204:207], v[94:97]
	v_mfma_f32_16x16x32_bf16 v[90:93], v[164:167], v[204:207], v[90:93]
	v_mfma_f32_16x16x32_bf16 v[90:93], v[160:163], v[200:203], v[90:93]
	v_mfma_f32_16x16x32_bf16 v[86:89], v[168:171], v[200:203], v[86:89]
	v_mfma_f32_16x16x32_bf16 v[86:89], v[172:175], v[204:207], v[86:89]
	v_mfma_f32_16x16x32_bf16 v[82:85], v[180:183], v[204:207], v[82:85]
	v_mfma_f32_16x16x32_bf16 v[82:85], v[176:179], v[200:203], v[82:85]
	v_mfma_f32_16x16x32_bf16 v[66:69], v[176:179], v[208:211], v[66:69]
	v_mfma_f32_16x16x32_bf16 v[66:69], v[180:183], v[212:215], v[66:69]
	v_mfma_f32_16x16x32_bf16 v[70:73], v[172:175], v[212:215], v[70:73]
	v_mfma_f32_16x16x32_bf16 v[70:73], v[168:171], v[208:211], v[70:73]
	v_mfma_f32_16x16x32_bf16 v[74:77], v[160:163], v[208:211], v[74:77]
	v_mfma_f32_16x16x32_bf16 v[74:77], v[164:167], v[212:215], v[74:77]
	v_mfma_f32_16x16x32_bf16 v[78:81], v[156:159], v[212:215], v[78:81]
	s_setprio 2
	s_barrier
; #define PG8_STAGE(bufoff, gbase, voff) do { _Pragma("unroll") for (int _i = 0; _i < 2; ++_i) \
;         asm volatile("s_mov_b32 m0, %2\n\ts_nop 0\n\tglobal_load_lds_dwordx4 %0, %1" :: "v"((voff)[_i]), "s"((const char*)(gbase)), "s"(ldsbase + (unsigned)(bufoff) + ldsw + (unsigned)_i * 8192u) : "memory", "m0"); } while (0)
; #define PG8_LDA(dst, b, h) do { _Pragma("unroll") for (int m = 0; m < 4; ++m) _Pragma("unroll") for (int k = 0; k < 2; ++k) dst[m][k] = *(const PG8_LAS bf16x8*)(lds + PG8_SA(b, h) + aoff + m * 2048 + k * 1024); } while (0)
; #define PG8_MMA(ai, bj, At, Bt) do { __builtin_amdgcn_s_setprio(1); _Pragma("unroll") for (int m = 0; m < 4; ++m) _Pragma("unroll") for (int n = 0; n < 2; ++n) _Pragma("unroll") for (int k = 0; k < 2; ++k) \
;         acc[ai][bj][m][n] = __builtin_amdgcn_mfma_f32_16x16x32_bf16(Bt[n][k], At[m][k], acc[ai][bj][m][n], 0, 0, 0); __builtin_amdgcn_s_setprio(0); } while (0)
; #define PG8_WAIT_V(n) asm volatile("s_waitcnt vmcnt(" #n ")" ::: "memory")
; #define PG8_WAIT_L(n) asm volatile("s_waitcnt lgkmcnt(" #n ")" ::: "memory")
; #define PG8_BAR __builtin_amdgcn_s_barrier()
; #define PG8_SCHED __builtin_amdgcn_sched_barrier(0)
; template <class Epi, class Sched, bool ALIGN_EPI = false, bool SP2 = false>
; __device__ __forceinline__ void gemm_phase(PG8_LAS unsigned char* lds, const Gemm g, const Sched& S, const Epi& E) {
;     ...
;             PG8_WAIT_V(8); PG8_WAIT_L(0); PG8_BAR; PG8_MMA(0, 0, At, B0); PG8_MMA(0, 1, At, B1); PG8_BAR; PG8_SCHED;
;             PG8_LDA(At, 1, 1); PG8_STAGE(PG8_SB(1, 0), b3, voffB); PG8_STAGE(PG8_SB(1, 1), b3 + hstep, voffB); PG8_STAGE(PG8_SA(1, 0), a3, voffA);
;             PG8_WAIT_V(8); PG8_WAIT_L(0); PG8_BAR; PG8_MMA(1, 0, At, B0); PG8_MMA(1, 1, At, B1); PG8_BAR; PG8_SCHED;
	v_mfma_f32_16x16x32_bf16 v[78:81], v[248:251], v[208:211], v[78:81]
	s_setprio 0
	ds_read_b128 v[184:187], v150 offset:49152
	ds_read_b128 v[188:191], v150 offset:50176
	ds_read_b128 v[192:195], v150 offset:51200
	ds_read_b128 v[196:199], v150 offset:52224
	ds_read_b128 v[200:203], v150 offset:53248
	ds_read_b128 v[204:207], v150 offset:54272
	ds_read_b128 v[252:255], v150 offset:55296
	ds_read_b128 v[212:215], v150 offset:56320
	s_mov_b32 m0, s56
	s_nop 0
	global_load_lds_dwordx4 v140, s[44:45]
	s_add_u32 s38, s38, 0x100080
	s_mov_b32 m0, s57
	s_nop 0
	global_load_lds_dwordx4 v142, s[44:45]
	s_addc_u32 s39, s39, 0
	s_mov_b32 m0, s62
	s_nop 0
	global_load_lds_dwordx4 v140, s[38:39]
	s_nop 0
	s_mov_b32 m0, s63
	s_nop 0
	global_load_lds_dwordx4 v142, s[38:39]
	s_nop 0
	s_mov_b32 m0, s60
	s_nop 0
	global_load_lds_dwordx4 v139, s[42:43]
	s_nop 0
	s_mov_b32 m0, s61
	s_nop 0
	global_load_lds_dwordx4 v141, s[42:43]
	s_waitcnt vmcnt(8)
	s_waitcnt lgkmcnt(0)
	s_barrier
	s_setprio 1
	s_waitcnt lgkmcnt(7)
	v_mfma_f32_16x16x32_bf16 v[62:65], v[248:251], v[184:187], v[62:65]
	v_mfma_f32_16x16x32_bf16 v[62:65], v[156:159], v[188:191], v[62:65]
	s_waitcnt lgkmcnt(5)
	v_mfma_f32_16x16x32_bf16 v[58:61], v[164:167], v[188:191], v[58:61]
	v_mfma_f32_16x16x32_bf16 v[58:61], v[160:163], v[184:187], v[58:61]
	s_waitcnt lgkmcnt(3)
	v_mfma_f32_16x16x32_bf16 v[54:57], v[168:171], v[184:187], v[54:57]
	v_mfma_f32_16x16x32_bf16 v[54:57], v[172:175], v[188:191], v[54:57]
	s_waitcnt lgkmcnt(1)
	v_mfma_f32_16x16x32_bf16 v[50:53], v[180:183], v[188:191], v[50:53]
	v_mfma_f32_16x16x32_bf16 v[50:53], v[176:179], v[184:187], v[50:53]
	v_mfma_f32_16x16x32_bf16 v[34:37], v[176:179], v[192:195], v[34:37]
	v_mfma_f32_16x16x32_bf16 v[34:37], v[180:183], v[196:199], v[34:37]
	v_mfma_f32_16x16x32_bf16 v[38:41], v[172:175], v[196:199], v[38:41]
	v_mfma_f32_16x16x32_bf16 v[38:41], v[168:171], v[192:195], v[38:41]
	v_mfma_f32_16x16x32_bf16 v[42:45], v[160:163], v[192:195], v[42:45]
	v_mfma_f32_16x16x32_bf16 v[42:45], v[164:167], v[196:199], v[42:45]
	s_waitcnt lgkmcnt(0)
	v_mfma_f32_16x16x32_bf16 v[46:49], v[156:159], v[196:199], v[46:49]
	v_mfma_f32_16x16x32_bf16 v[46:49], v[248:251], v[192:195], v[46:49]
	s_setprio 0
	s_setprio 1
	v_mfma_f32_16x16x32_bf16 v[30:33], v[248:251], v[200:203], v[30:33]
	v_mfma_f32_16x16x32_bf16 v[30:33], v[156:159], v[204:207], v[30:33]
	v_mfma_f32_16x16x32_bf16 v[26:29], v[164:167], v[204:207], v[26:29]
	v_mfma_f32_16x16x32_bf16 v[26:29], v[160:163], v[200:203], v[26:29]
	v_mfma_f32_16x16x32_bf16 v[22:25], v[168:171], v[200:203], v[22:25]
	v_mfma_f32_16x16x32_bf16 v[22:25], v[172:175], v[204:207], v[22:25]
	v_mfma_f32_16x16x32_bf16 v[18:21], v[180:183], v[204:207], v[18:21]
	v_mfma_f32_16x16x32_bf16 v[18:21], v[176:179], v[200:203], v[18:21]
	v_mfma_f32_16x16x32_bf16 v[2:5], v[176:179], v[252:255], v[2:5]
	v_mfma_f32_16x16x32_bf16 v[2:5], v[180:183], v[212:215], v[2:5]
	v_mfma_f32_16x16x32_bf16 v[6:9], v[172:175], v[212:215], v[6:9]
	v_mfma_f32_16x16x32_bf16 v[6:9], v[168:171], v[252:255], v[6:9]
	v_mfma_f32_16x16x32_bf16 v[10:13], v[160:163], v[252:255], v[10:13]
	v_mfma_f32_16x16x32_bf16 v[10:13], v[164:167], v[212:215], v[10:13]
	v_mfma_f32_16x16x32_bf16 v[14:17], v[156:159], v[212:215], v[14:17]
	s_setprio 2
	s_barrier
	v_mfma_f32_16x16x32_bf16 v[14:17], v[248:251], v[252:255], v[14:17]
	s_setprio 0
	s_add_i32 s76, s76, 2
	s_add_u32 s74, s74, 0x100
	s_addc_u32 s75, s75, 0
	s_cmp_gt_u32 s76, 61
	s_cbranch_scc1 .LBB0_780
	s_mov_b64 s[40:41], s[8:9]
	s_branch .LBB0_784

; #define PG8_STAGE(bufoff, gbase, voff) do { _Pragma("unroll") for (int _i = 0; _i < 2; ++_i) \
;         asm volatile("s_mov_b32 m0, %2\n\ts_nop 0\n\tglobal_load_lds_dwordx4 %0, %1" :: "v"((voff)[_i]), "s"((const char*)(gbase)), "s"(ldsbase + (unsigned)(bufoff) + ldsw + (unsigned)_i * 8192u) : "memory", "m0"); } while (0)
; #define PG8_LDA(dst, b, h) do { _Pragma("unroll") for (int m = 0; m < 4; ++m) _Pragma("unroll") for (int k = 0; k < 2; ++k) dst[m][k] = *(const PG8_LAS bf16x8*)(lds + PG8_SA(b, h) + aoff + m * 2048 + k * 1024); } while (0)
; #define PG8_LDB(dst, b, h) do { _Pragma("unroll") for (int n = 0; n < 2; ++n) _Pragma("unroll") for (int k = 0; k < 2; ++k) dst[n][k] = *(const PG8_LAS bf16x8*)(lds + PG8_SB(b, h) + boff + n * 2048 + k * 1024); } while (0)
; #define PG8_MMA(ai, bj, At, Bt) do { __builtin_amdgcn_s_setprio(1); _Pragma("unroll") for (int m = 0; m < 4; ++m) _Pragma("unroll") for (int n = 0; n < 2; ++n) _Pragma("unroll") for (int k = 0; k < 2; ++k) \
;         acc[ai][bj][m][n] = __builtin_amdgcn_mfma_f32_16x16x32_bf16(Bt[n][k], At[m][k], acc[ai][bj][m][n], 0, 0, 0); __builtin_amdgcn_s_setprio(0); } while (0)
; template <class Epi, class Sched, bool ALIGN_EPI = false, bool SP2 = false>
; __device__ __forceinline__ void gemm_phase(PG8_LAS unsigned char* lds, const Gemm g, const Sched& S, const Epi& E) {
;     ...
;             const bool last = (t == nt - 2);
;             const char* a1 = cA + (size_t)(t + 1) * kstep;
;             const char* a2 = last ? nA : cA + (size_t)(t + 2) * kstep; const char* b2 = last ? nB : cB + (size_t)(t + 2) * kstep;
;             const char* a3 = a2 + kstep; const char* b3 = b2 + kstep;
;             if (last && has_next) S.a_ready(nxt);
;             if constexpr (epi_has_mid<Epi>::value) { if (t == Epi::MID_T) E.mid(acc, cur, wr, wc, fr, fq); }
;             if constexpr (SP2) {
;             PG8_LDB(B0, 0, 0); PG8_LDB(B1, 0, 1); PG8_SCHED; PG8_LDA(At, 0, 0); PG8_STAGE(PG8_SA(1, 1), a1 + hstep, voffA);
;             PG8_WAIT_V(8); PG8_WAIT_L(0); PG8_BAR; PG8_MMA(0, 0, At, B0); PG8_MMA(0, 1, At, B1); PG8_BAR; PG8_SCHED;
;             PG8_LDA(At, 0, 1); PG8_STAGE(PG8_SB(0, 0), b2, voffB); PG8_STAGE(PG8_SB(0, 1), b2 + hstep, voffB); PG8_STAGE(PG8_SA(0, 0), a2, voffA);
;             PG8_WAIT_V(8); PG8_WAIT_L(0); PG8_BAR; PG8_MMA(1, 0, At, B0); PG8_MMA(1, 1, At, B1); PG8_BAR; PG8_SCHED;
.LBB0_873:
	ds_read_b128 v[134:137], v145
	ds_read_b128 v[150:153], v145 offset:1024
	ds_read_b128 v[154:157], v145 offset:2048
	ds_read_b128 v[158:161], v145 offset:3072
	ds_read_b128 v[162:165], v146
	ds_read_b128 v[166:169], v146 offset:1024
	ds_read_b128 v[170:173], v146 offset:2048
	ds_read_b128 v[174:177], v146 offset:3072
	s_add_u32 s38, s36, 0x100
	s_addc_u32 s39, s37, 0
	s_cmpk_eq_i32 s69, 0xa8
	s_cselect_b32 s44, s4, s38
	s_cselect_b32 s45, s5, s39
	s_cselect_b32 s42, s22, s67
	s_cselect_b32 s43, s23, s68
	s_add_u32 s40, s44, 0x80
	s_addc_u32 s41, s45, 0
	ds_read_b128 v[178:181], v147
	ds_read_b128 v[182:185], v147 offset:1024
	ds_read_b128 v[186:189], v147 offset:2048
	ds_read_b128 v[190:193], v147 offset:3072
	ds_read_b128 v[194:197], v147 offset:4096
	ds_read_b128 v[198:201], v147 offset:5120
	ds_read_b128 v[202:205], v147 offset:6144
	ds_read_b128 v[206:209], v147 offset:7168
	s_add_u32 s36, s36, 0x2b0080
	s_addc_u32 s37, s37, 0
	s_mov_b32 m0, s60
	s_nop 0
	global_load_lds_dwordx4 v1, s[36:37]
	s_nop 0
	s_mov_b32 m0, s61
	s_nop 0
	global_load_lds_dwordx4 v141, s[36:37]
	s_waitcnt vmcnt(8)
	s_waitcnt lgkmcnt(0)
	s_barrier
	s_setprio 1
	s_waitcnt lgkmcnt(7)
	v_mfma_f32_16x16x32_bf16 v[126:129], v[134:137], v[178:181], v[126:129]
	v_mfma_f32_16x16x32_bf16 v[126:129], v[150:153], v[182:185], v[126:129]
	s_waitcnt lgkmcnt(5)
	v_mfma_f32_16x16x32_bf16 v[122:125], v[158:161], v[182:185], v[122:125]
	v_mfma_f32_16x16x32_bf16 v[122:125], v[154:157], v[178:181], v[122:125]
	s_waitcnt lgkmcnt(3)
	v_mfma_f32_16x16x32_bf16 v[118:121], v[162:165], v[178:181], v[118:121]
	v_mfma_f32_16x16x32_bf16 v[118:121], v[166:169], v[182:185], v[118:121]
	s_waitcnt lgkmcnt(1)
	v_mfma_f32_16x16x32_bf16 v[114:117], v[174:177], v[182:185], v[114:117]
	v_mfma_f32_16x16x32_bf16 v[114:117], v[170:173], v[178:181], v[114:117]
	v_mfma_f32_16x16x32_bf16 v[98:101], v[170:173], v[186:189], v[98:101]
	v_mfma_f32_16x16x32_bf16 v[98:101], v[174:177], v[190:193], v[98:101]
	v_mfma_f32_16x16x32_bf16 v[102:105], v[166:169], v[190:193], v[102:105]
	v_mfma_f32_16x16x32_bf16 v[102:105], v[162:165], v[186:189], v[102:105]
	v_mfma_f32_16x16x32_bf16 v[106:109], v[154:157], v[186:189], v[106:109]
	v_mfma_f32_16x16x32_bf16 v[106:109], v[158:161], v[190:193], v[106:109]
	s_waitcnt lgkmcnt(0)
	v_mfma_f32_16x16x32_bf16 v[110:113], v[150:153], v[190:193], v[110:113]
	v_mfma_f32_16x16x32_bf16 v[110:113], v[134:137], v[186:189], v[110:113]
	s_setprio 0
	s_setprio 1
	v_mfma_f32_16x16x32_bf16 v[94:97], v[134:137], v[194:197], v[94:97]
	v_mfma_f32_16x16x32_bf16 v[94:97], v[150:153], v[198:201], v[94:97]
	v_mfma_f32_16x16x32_bf16 v[90:93], v[158:161], v[198:201], v[90:93]
	v_mfma_f32_16x16x32_bf16 v[90:93], v[154:157], v[194:197], v[90:93]
	v_mfma_f32_16x16x32_bf16 v[86:89], v[162:165], v[194:197], v[86:89]
	v_mfma_f32_16x16x32_bf16 v[86:89], v[166:169], v[198:201], v[86:89]
	v_mfma_f32_16x16x32_bf16 v[82:85], v[174:177], v[198:201], v[82:85]
	v_mfma_f32_16x16x32_bf16 v[82:85], v[170:173], v[194:197], v[82:85]
	v_mfma_f32_16x16x32_bf16 v[66:69], v[170:173], v[202:205], v[66:69]
	v_mfma_f32_16x16x32_bf16 v[66:69], v[174:177], v[206:209], v[66:69]
	v_mfma_f32_16x16x32_bf16 v[70:73], v[166:169], v[206:209], v[70:73]
	v_mfma_f32_16x16x32_bf16 v[70:73], v[162:165], v[202:205], v[70:73]
	v_mfma_f32_16x16x32_bf16 v[74:77], v[154:157], v[202:205], v[74:77]
	v_mfma_f32_16x16x32_bf16 v[74:77], v[158:161], v[206:209], v[74:77]
	v_mfma_f32_16x16x32_bf16 v[78:81], v[150:153], v[206:209], v[78:81]
	s_setprio 2
	s_barrier
	v_mfma_f32_16x16x32_bf16 v[78:81], v[134:137], v[202:205], v[78:81]
	s_setprio 0
	ds_read_b128 v[178:181], v147 offset:16384
	ds_read_b128 v[182:185], v147 offset:17408
	ds_read_b128 v[186:189], v147 offset:18432
	ds_read_b128 v[190:193], v147 offset:19456
	ds_read_b128 v[194:197], v147 offset:20480
	ds_read_b128 v[198:201], v147 offset:21504
	ds_read_b128 v[252:255], v147 offset:22528
	ds_read_b128 v[206:209], v147 offset:23552
	s_mov_b32 m0, s47
	s_nop 0
	global_load_lds_dwordx4 v140, s[42:43]
	s_add_u32 s36, s42, 0x2b0000
	s_mov_b32 m0, s48
	s_nop 0
	global_load_lds_dwordx4 v142, s[42:43]
	s_addc_u32 s37, s43, 0
	s_mov_b32 m0, s49
	s_nop 0
	global_load_lds_dwordx4 v140, s[36:37]
	s_nop 0
	s_mov_b32 m0, s50
	s_nop 0
	global_load_lds_dwordx4 v142, s[36:37]
	s_nop 0
	s_mov_b32 m0, s46
	s_nop 0
	global_load_lds_dwordx4 v1, s[44:45]
	s_nop 0
	s_mov_b32 m0, s51
	s_nop 0
	global_load_lds_dwordx4 v141, s[44:45]
	s_waitcnt vmcnt(8)
	s_waitcnt lgkmcnt(0)
	s_barrier
; #define PG8_STAGE(bufoff, gbase, voff) do { _Pragma("unroll") for (int _i = 0; _i < 2; ++_i) \
;         asm volatile("s_mov_b32 m0, %2\n\ts_nop 0\n\tglobal_load_lds_dwordx4 %0, %1" :: "v"((voff)[_i]), "s"((const char*)(gbase)), "s"(ldsbase + (unsigned)(bufoff) + ldsw + (unsigned)_i * 8192u) : "memory", "m0"); } while (0)
; #define PG8_LDA(dst, b, h) do { _Pragma("unroll") for (int m = 0; m < 4; ++m) _Pragma("unroll") for (int k = 0; k < 2; ++k) dst[m][k] = *(const PG8_LAS bf16x8*)(lds + PG8_SA(b, h) + aoff + m * 2048 + k * 1024); } while (0)
; #define PG8_LDB(dst, b, h) do { _Pragma("unroll") for (int n = 0; n < 2; ++n) _Pragma("unroll") for (int k = 0; k < 2; ++k) dst[n][k] = *(const PG8_LAS bf16x8*)(lds + PG8_SB(b, h) + boff + n * 2048 + k * 1024); } while (0)
; #define PG8_MMA(ai, bj, At, Bt) do { __builtin_amdgcn_s_setprio(1); _Pragma("unroll") for (int m = 0; m < 4; ++m) _Pragma("unroll") for (int n = 0; n < 2; ++n) _Pragma("unroll") for (int k = 0; k < 2; ++k) \
;         acc[ai][bj][m][n] = __builtin_amdgcn_mfma_f32_16x16x32_bf16(Bt[n][k], At[m][k], acc[ai][bj][m][n], 0, 0, 0); __builtin_amdgcn_s_setprio(0); } while (0)
; #define PG8_WAIT_V(n) asm volatile("s_waitcnt vmcnt(" #n ")" ::: "memory")
; #define PG8_WAIT_L(n) asm volatile("s_waitcnt lgkmcnt(" #n ")" ::: "memory")
; #define PG8_BAR __builtin_amdgcn_s_barrier()
; #define PG8_SCHED __builtin_amdgcn_sched_barrier(0)
; template <class Epi, class Sched, bool ALIGN_EPI = false, bool SP2 = false>
; __device__ __forceinline__ void gemm_phase(PG8_LAS unsigned char* lds, const Gemm g, const Sched& S, const Epi& E) {
;     ...
;             PG8_WAIT_V(8); PG8_WAIT_L(0); PG8_BAR; PG8_MMA(1, 0, At, B0); PG8_MMA(1, 1, At, B1); PG8_BAR; PG8_SCHED;
;             PG8_LDB(B0, 1, 0); PG8_LDB(B1, 1, 1); PG8_SCHED; PG8_LDA(At, 1, 0); PG8_STAGE(PG8_SA(0, 1), a2 + hstep, voffA);
;             PG8_WAIT_V(8); PG8_WAIT_L(0); PG8_BAR; PG8_MMA(0, 0, At, B0); PG8_MMA(0, 1, At, B1); PG8_BAR; PG8_SCHED;
	s_setprio 1
	s_waitcnt lgkmcnt(7)
	v_mfma_f32_16x16x32_bf16 v[62:65], v[134:137], v[178:181], v[62:65]
	v_mfma_f32_16x16x32_bf16 v[62:65], v[150:153], v[182:185], v[62:65]
	s_waitcnt lgkmcnt(5)
	v_mfma_f32_16x16x32_bf16 v[58:61], v[158:161], v[182:185], v[58:61]
	v_mfma_f32_16x16x32_bf16 v[58:61], v[154:157], v[178:181], v[58:61]
	s_waitcnt lgkmcnt(3)
	v_mfma_f32_16x16x32_bf16 v[54:57], v[162:165], v[178:181], v[54:57]
	v_mfma_f32_16x16x32_bf16 v[54:57], v[166:169], v[182:185], v[54:57]
	s_waitcnt lgkmcnt(1)
	v_mfma_f32_16x16x32_bf16 v[50:53], v[174:177], v[182:185], v[50:53]
	v_mfma_f32_16x16x32_bf16 v[50:53], v[170:173], v[178:181], v[50:53]
	v_mfma_f32_16x16x32_bf16 v[34:37], v[170:173], v[186:189], v[34:37]
	v_mfma_f32_16x16x32_bf16 v[34:37], v[174:177], v[190:193], v[34:37]
	v_mfma_f32_16x16x32_bf16 v[38:41], v[166:169], v[190:193], v[38:41]
	v_mfma_f32_16x16x32_bf16 v[38:41], v[162:165], v[186:189], v[38:41]
	v_mfma_f32_16x16x32_bf16 v[42:45], v[154:157], v[186:189], v[42:45]
	v_mfma_f32_16x16x32_bf16 v[42:45], v[158:161], v[190:193], v[42:45]
	s_waitcnt lgkmcnt(0)
	v_mfma_f32_16x16x32_bf16 v[46:49], v[150:153], v[190:193], v[46:49]
	v_mfma_f32_16x16x32_bf16 v[46:49], v[134:137], v[186:189], v[46:49]
	s_setprio 0
	s_setprio 1
	v_mfma_f32_16x16x32_bf16 v[30:33], v[134:137], v[194:197], v[30:33]
	v_mfma_f32_16x16x32_bf16 v[30:33], v[150:153], v[198:201], v[30:33]
	v_mfma_f32_16x16x32_bf16 v[26:29], v[158:161], v[198:201], v[26:29]
	v_mfma_f32_16x16x32_bf16 v[26:29], v[154:157], v[194:197], v[26:29]
	v_mfma_f32_16x16x32_bf16 v[22:25], v[162:165], v[194:197], v[22:25]
	v_mfma_f32_16x16x32_bf16 v[22:25], v[166:169], v[198:201], v[22:25]
	v_mfma_f32_16x16x32_bf16 v[18:21], v[174:177], v[198:201], v[18:21]
	v_mfma_f32_16x16x32_bf16 v[18:21], v[170:173], v[194:197], v[18:21]
	v_mfma_f32_16x16x32_bf16 v[2:5], v[170:173], v[252:255], v[2:5]
	v_mfma_f32_16x16x32_bf16 v[2:5], v[174:177], v[206:209], v[2:5]
	v_mfma_f32_16x16x32_bf16 v[6:9], v[166:169], v[206:209], v[6:9]
	v_mfma_f32_16x16x32_bf16 v[6:9], v[162:165], v[252:255], v[6:9]
	v_mfma_f32_16x16x32_bf16 v[10:13], v[154:157], v[252:255], v[10:13]
	v_mfma_f32_16x16x32_bf16 v[10:13], v[158:161], v[206:209], v[10:13]
	v_mfma_f32_16x16x32_bf16 v[14:17], v[150:153], v[206:209], v[14:17]
	s_setprio 2
	s_barrier
	v_mfma_f32_16x16x32_bf16 v[14:17], v[134:137], v[252:255], v[14:17]
	s_setprio 0
	ds_read_b128 v[248:251], v148
	ds_read_b128 v[150:153], v148 offset:1024
	ds_read_b128 v[154:157], v148 offset:2048
	ds_read_b128 v[158:161], v148 offset:3072
	ds_read_b128 v[162:165], v149
	ds_read_b128 v[166:169], v149 offset:1024
	ds_read_b128 v[170:173], v149 offset:2048
	ds_read_b128 v[174:177], v149 offset:3072
	ds_read_b128 v[178:181], v147 offset:32768
	ds_read_b128 v[182:185], v147 offset:33792
	ds_read_b128 v[186:189], v147 offset:34816
	ds_read_b128 v[190:193], v147 offset:35840
	ds_read_b128 v[194:197], v147 offset:36864
	ds_read_b128 v[198:201], v147 offset:37888
	ds_read_b128 v[202:205], v147 offset:38912
	ds_read_b128 v[206:209], v147 offset:39936
	s_add_u32 s36, s44, 0x2b0000
	s_addc_u32 s37, s45, 0
	s_mov_b32 m0, s52
	s_nop 0
	global_load_lds_dwordx4 v1, s[36:37]
	s_nop 0
	s_mov_b32 m0, s53
	s_nop 0
	global_load_lds_dwordx4 v141, s[36:37]
	s_waitcnt vmcnt(8)
	s_waitcnt lgkmcnt(0)
	s_barrier
	s_setprio 1
	s_waitcnt lgkmcnt(7)
	v_mfma_f32_16x16x32_bf16 v[126:129], v[248:251], v[178:181], v[126:129]
	v_mfma_f32_16x16x32_bf16 v[126:129], v[150:153], v[182:185], v[126:129]
	s_waitcnt lgkmcnt(5)
	v_mfma_f32_16x16x32_bf16 v[122:125], v[158:161], v[182:185], v[122:125]
	v_mfma_f32_16x16x32_bf16 v[122:125], v[154:157], v[178:181], v[122:125]
	s_waitcnt lgkmcnt(3)
	v_mfma_f32_16x16x32_bf16 v[118:121], v[162:165], v[178:181], v[118:121]
	v_mfma_f32_16x16x32_bf16 v[118:121], v[166:169], v[182:185], v[118:121]
	s_waitcnt lgkmcnt(1)
	v_mfma_f32_16x16x32_bf16 v[114:117], v[174:177], v[182:185], v[114:117]
	v_mfma_f32_16x16x32_bf16 v[114:117], v[170:173], v[178:181], v[114:117]
	v_mfma_f32_16x16x32_bf16 v[98:101], v[170:173], v[186:189], v[98:101]
	v_mfma_f32_16x16x32_bf16 v[98:101], v[174:177], v[190:193], v[98:101]
	v_mfma_f32_16x16x32_bf16 v[102:105], v[166:169], v[190:193], v[102:105]
	v_mfma_f32_16x16x32_bf16 v[102:105], v[162:165], v[186:189], v[102:105]
	v_mfma_f32_16x16x32_bf16 v[106:109], v[154:157], v[186:189], v[106:109]
	v_mfma_f32_16x16x32_bf16 v[106:109], v[158:161], v[190:193], v[106:109]
	s_waitcnt lgkmcnt(0)
	v_mfma_f32_16x16x32_bf16 v[110:113], v[150:153], v[190:193], v[110:113]
	v_mfma_f32_16x16x32_bf16 v[110:113], v[248:251], v[186:189], v[110:113]
	s_setprio 0
	s_setprio 1
	v_mfma_f32_16x16x32_bf16 v[94:97], v[248:251], v[194:197], v[94:97]
	v_mfma_f32_16x16x32_bf16 v[94:97], v[150:153], v[198:201], v[94:97]
	v_mfma_f32_16x16x32_bf16 v[90:93], v[158:161], v[198:201], v[90:93]
	v_mfma_f32_16x16x32_bf16 v[90:93], v[154:157], v[194:197], v[90:93]
	v_mfma_f32_16x16x32_bf16 v[86:89], v[162:165], v[194:197], v[86:89]
	v_mfma_f32_16x16x32_bf16 v[86:89], v[166:169], v[198:201], v[86:89]
	v_mfma_f32_16x16x32_bf16 v[82:85], v[174:177], v[198:201], v[82:85]
	v_mfma_f32_16x16x32_bf16 v[82:85], v[170:173], v[194:197], v[82:85]
	v_mfma_f32_16x16x32_bf16 v[66:69], v[170:173], v[202:205], v[66:69]
	v_mfma_f32_16x16x32_bf16 v[66:69], v[174:177], v[206:209], v[66:69]
	v_mfma_f32_16x16x32_bf16 v[70:73], v[166:169], v[206:209], v[70:73]
	v_mfma_f32_16x16x32_bf16 v[70:73], v[162:165], v[202:205], v[70:73]
	v_mfma_f32_16x16x32_bf16 v[74:77], v[154:157], v[202:205], v[74:77]
	v_mfma_f32_16x16x32_bf16 v[74:77], v[158:161], v[206:209], v[74:77]
	v_mfma_f32_16x16x32_bf16 v[78:81], v[150:153], v[206:209], v[78:81]
	s_setprio 2
	s_barrier
; #define PG8_STAGE(bufoff, gbase, voff) do { _Pragma("unroll") for (int _i = 0; _i < 2; ++_i) \
;         asm volatile("s_mov_b32 m0, %2\n\ts_nop 0\n\tglobal_load_lds_dwordx4 %0, %1" :: "v"((voff)[_i]), "s"((const char*)(gbase)), "s"(ldsbase + (unsigned)(bufoff) + ldsw + (unsigned)_i * 8192u) : "memory", "m0"); } while (0)
; #define PG8_LDA(dst, b, h) do { _Pragma("unroll") for (int m = 0; m < 4; ++m) _Pragma("unroll") for (int k = 0; k < 2; ++k) dst[m][k] = *(const PG8_LAS bf16x8*)(lds + PG8_SA(b, h) + aoff + m * 2048 + k * 1024); } while (0)
; #define PG8_MMA(ai, bj, At, Bt) do { __builtin_amdgcn_s_setprio(1); _Pragma("unroll") for (int m = 0; m < 4; ++m) _Pragma("unroll") for (int n = 0; n < 2; ++n) _Pragma("unroll") for (int k = 0; k < 2; ++k) \
;         acc[ai][bj][m][n] = __builtin_amdgcn_mfma_f32_16x16x32_bf16(Bt[n][k], At[m][k], acc[ai][bj][m][n], 0, 0, 0); __builtin_amdgcn_s_setprio(0); } while (0)
; #define PG8_WAIT_V(n) asm volatile("s_waitcnt vmcnt(" #n ")" ::: "memory")
; #define PG8_WAIT_L(n) asm volatile("s_waitcnt lgkmcnt(" #n ")" ::: "memory")
; #define PG8_BAR __builtin_amdgcn_s_barrier()
; #define PG8_SCHED __builtin_amdgcn_sched_barrier(0)
; template <class Epi, class Sched, bool ALIGN_EPI = false, bool SP2 = false>
; __device__ __forceinline__ void gemm_phase(PG8_LAS unsigned char* lds, const Gemm g, const Sched& S, const Epi& E) {
;     ...
;             PG8_WAIT_V(8); PG8_WAIT_L(0); PG8_BAR; PG8_MMA(0, 0, At, B0); PG8_MMA(0, 1, At, B1); PG8_BAR; PG8_SCHED;
;             PG8_LDA(At, 1, 1); PG8_STAGE(PG8_SB(1, 0), b3, voffB); PG8_STAGE(PG8_SB(1, 1), b3 + hstep, voffB); PG8_STAGE(PG8_SA(1, 0), a3, voffA);
;             PG8_WAIT_V(8); PG8_WAIT_L(0); PG8_BAR; PG8_MMA(1, 0, At, B0); PG8_MMA(1, 1, At, B1); PG8_BAR; PG8_SCHED;
;     ...
;         if constexpr (ALIGN_EPI) { if (wr == 0) PG8_BAR; }
	v_mfma_f32_16x16x32_bf16 v[78:81], v[248:251], v[202:205], v[78:81]
	s_setprio 0
	ds_read_b128 v[178:181], v147 offset:49152
	ds_read_b128 v[182:185], v147 offset:50176
	ds_read_b128 v[186:189], v147 offset:51200
	ds_read_b128 v[190:193], v147 offset:52224
	ds_read_b128 v[194:197], v147 offset:53248
	ds_read_b128 v[198:201], v147 offset:54272
	ds_read_b128 v[252:255], v147 offset:55296
	ds_read_b128 v[206:209], v147 offset:56320
	s_add_u32 s36, s42, 0x80
	s_addc_u32 s37, s43, 0
	s_mov_b32 m0, s54
	s_nop 0
	global_load_lds_dwordx4 v140, s[36:37]
	s_nop 0
	s_mov_b32 m0, s55
	s_nop 0
	global_load_lds_dwordx4 v142, s[36:37]
	s_add_u32 s36, s42, 0x2b0080
	s_addc_u32 s37, s43, 0
	s_mov_b32 m0, s58
	s_nop 0
	global_load_lds_dwordx4 v140, s[36:37]
	s_nop 0
	s_mov_b32 m0, s59
	s_nop 0
	global_load_lds_dwordx4 v142, s[36:37]
	s_nop 0
	s_mov_b32 m0, s56
	s_nop 0
	global_load_lds_dwordx4 v1, s[40:41]
	s_nop 0
	s_mov_b32 m0, s57
	s_nop 0
	global_load_lds_dwordx4 v141, s[40:41]
	s_waitcnt vmcnt(8)
	s_waitcnt lgkmcnt(0)
	s_barrier
	s_setprio 1
	s_waitcnt lgkmcnt(7)
	v_mfma_f32_16x16x32_bf16 v[62:65], v[248:251], v[178:181], v[62:65]
	v_mfma_f32_16x16x32_bf16 v[62:65], v[150:153], v[182:185], v[62:65]
	s_waitcnt lgkmcnt(5)
	v_mfma_f32_16x16x32_bf16 v[58:61], v[158:161], v[182:185], v[58:61]
	v_mfma_f32_16x16x32_bf16 v[58:61], v[154:157], v[178:181], v[58:61]
	s_waitcnt lgkmcnt(3)
	v_mfma_f32_16x16x32_bf16 v[54:57], v[162:165], v[178:181], v[54:57]
	v_mfma_f32_16x16x32_bf16 v[54:57], v[166:169], v[182:185], v[54:57]
	s_waitcnt lgkmcnt(1)
	v_mfma_f32_16x16x32_bf16 v[50:53], v[174:177], v[182:185], v[50:53]
	v_mfma_f32_16x16x32_bf16 v[50:53], v[170:173], v[178:181], v[50:53]
	v_mfma_f32_16x16x32_bf16 v[34:37], v[170:173], v[186:189], v[34:37]
	v_mfma_f32_16x16x32_bf16 v[34:37], v[174:177], v[190:193], v[34:37]
	v_mfma_f32_16x16x32_bf16 v[38:41], v[166:169], v[190:193], v[38:41]
	v_mfma_f32_16x16x32_bf16 v[38:41], v[162:165], v[186:189], v[38:41]
	v_mfma_f32_16x16x32_bf16 v[42:45], v[154:157], v[186:189], v[42:45]
	v_mfma_f32_16x16x32_bf16 v[42:45], v[158:161], v[190:193], v[42:45]
	s_waitcnt lgkmcnt(0)
	v_mfma_f32_16x16x32_bf16 v[46:49], v[150:153], v[190:193], v[46:49]
	v_mfma_f32_16x16x32_bf16 v[46:49], v[248:251], v[186:189], v[46:49]
	s_setprio 0
	s_setprio 1
	v_mfma_f32_16x16x32_bf16 v[30:33], v[248:251], v[194:197], v[30:33]
	v_mfma_f32_16x16x32_bf16 v[30:33], v[150:153], v[198:201], v[30:33]
	v_mfma_f32_16x16x32_bf16 v[26:29], v[158:161], v[198:201], v[26:29]
	v_mfma_f32_16x16x32_bf16 v[26:29], v[154:157], v[194:197], v[26:29]
	v_mfma_f32_16x16x32_bf16 v[22:25], v[162:165], v[194:197], v[22:25]
	v_mfma_f32_16x16x32_bf16 v[22:25], v[166:169], v[198:201], v[22:25]
	v_mfma_f32_16x16x32_bf16 v[18:21], v[174:177], v[198:201], v[18:21]
	v_mfma_f32_16x16x32_bf16 v[18:21], v[170:173], v[194:197], v[18:21]
	v_mfma_f32_16x16x32_bf16 v[2:5], v[170:173], v[252:255], v[2:5]
	v_mfma_f32_16x16x32_bf16 v[2:5], v[174:177], v[206:209], v[2:5]
	v_mfma_f32_16x16x32_bf16 v[6:9], v[166:169], v[206:209], v[6:9]
	v_mfma_f32_16x16x32_bf16 v[6:9], v[162:165], v[252:255], v[6:9]
	v_mfma_f32_16x16x32_bf16 v[10:13], v[154:157], v[252:255], v[10:13]
	v_mfma_f32_16x16x32_bf16 v[10:13], v[158:161], v[206:209], v[10:13]
	v_mfma_f32_16x16x32_bf16 v[14:17], v[150:153], v[206:209], v[14:17]
	s_setprio 2
	s_barrier
	v_mfma_f32_16x16x32_bf16 v[14:17], v[248:251], v[252:255], v[14:17]
	s_setprio 0
	s_add_i32 s69, s69, 2
	s_add_u32 s67, s67, 0x100
	s_addc_u32 s68, s68, 0
	s_cmpk_gt_u32 s69, 0xa9
	s_mov_b64 s[36:37], s[38:39]
	s_cbranch_scc0 .LBB0_873
	s_and_b64 vcc, exec, s[10:11]
	s_cbranch_vccz .LBB0_876
	s_barrier
